# GEMM K-loops: LDS-DMA addresses as scalar base + 32-bit lane offset where the 64-bit VGPR address was dead (126 sites), on top of attention rewrite
# baseline (speedup 1.0000x reference)
.LBB0_266:
	s_and_b32 s16, s10, 3
	s_mov_b64 s[10:11], 0x80
	s_add_i32 m0, s69, 0x18000
	v_lshl_add_u64 v[6:7], v[6:7], 0, s[10:11]
	s_lshl_b32 s13, s12, 13
	s_lshl_b32 s17, s16, 12
	s_waitcnt vmcnt(2)
	s_barrier
	global_load_lds_dwordx4 v[6:7], off
	v_lshl_add_u64 v[4:5], v[4:5], 0, s[10:11]
	s_add_i32 m0, s69, 0x1a000
	s_add_i32 s33, s69, 0x8000
	s_add_i32 s74, s69, 0xa000
	global_load_lds_dwordx4 v[4:5], off
	v_lshl_add_u64 v[0:1], v[0:1], 0, s[10:11]
	s_mov_b32 m0, s33
	s_add_u32 s14, s62, 0x40080
	global_load_lds_dwordx4 v[0:1], off
	v_lshl_add_u64 v[0:1], v[2:3], 0, s[10:11]
	s_mov_b32 m0, s74
	s_addc_u32 s15, s63, 0
	global_load_lds_dwordx4 v[0:1], off
	s_add_i32 m0, s69, 0x1c000
	s_nop 0
	global_load_lds_dwordx4 v132, s[14:15]
	s_add_i32 m0, s69, 0x1e000
	s_cmpk_lt_u32 s5, 0x100
	global_load_lds_dwordx4 v128, s[14:15]
	v_bfe_u32 v1, v10, 4, 2
	v_and_b32_e32 v0, 15, v10
	v_lshlrev_b32_e32 v3, 4, v1
	v_lshl_or_b32 v150, s12, 6, v0
	v_lshl_or_b32 v0, v0, 6, v3
	v_lshlrev_b32_e32 v3, 2, v10
	v_and_b32_e32 v3, 32, v3
	v_bitop3_b32 v4, v0, s13, v3 bitop3:0xde
	s_cselect_b64 s[12:13], -1, 0
	s_cmp_eq_u32 s16, 0
	s_sext_i32_i8 s54, s4
	v_lshlrev_b32_e32 v2, 3, v1
	v_bitop3_b32 v151, v0, s17, v3 bitop3:0xde
	s_cselect_b64 s[4:5], -1, 0
	v_cmp_gt_u32_e32 vcc, 2, v1
	v_lshlrev_b32_e32 v0, 5, v1
	v_mov_b32_e32 v1, v133
	s_and_b64 s[14:15], s[4:5], vcc
	v_lshl_add_u64 v[0:1], s[46:47], 0, v[0:1]
	s_mov_b64 s[4:5], 0xa00000
	v_lshl_add_u64 v[136:137], v[0:1], 0, s[4:5]
	v_lshlrev_b32_e32 v0, 14, v13
	v_and_b32_e32 v0, 0xffff8000, v0
	v_lshl_add_u32 v0, v12, 11, v0
	v_and_b32_e32 v1, 1, v13
	v_lshl_or_b32 v0, v1, 6, v0
	v_lshl_add_u32 v138, v14, 1, v0
	v_lshlrev_b32_e32 v0, 14, v8
	v_and_b32_e32 v0, 0xffff8000, v0
	s_waitcnt vmcnt(6)
	v_lshl_add_u32 v0, v9, 11, v0
	v_and_b32_e32 v1, 1, v8
	v_lshl_or_b32 v0, v1, 6, v0
	s_add_i32 s76, 0, 0x10000
	s_add_i32 s77, 0, 0x14000
	s_ashr_i32 s75, s3, 31
	v_lshl_or_b32 v152, s16, 5, v2
	v_mov_b32_e32 v139, v133
	v_lshl_add_u32 v140, v11, 1, v0
	v_mov_b32_e32 v141, v133
	v_mov_b64_e32 v[142:143], 0x480
	v_mov_b64_e32 v[144:145], 0x47f
	v_add_u32_e32 v153, s76, v151
	v_add_u32_e32 v154, s77, v151
	v_add_u32_e32 v155, 0, v4
	s_mov_b64 s[16:17], 0x2000
	s_mov_b64 s[18:19], 0x2400
	s_mov_b64 s[20:21], 0x2800
	s_mov_b64 s[22:23], 0x2c00
	s_mov_b64 s[24:25], 0x80000
	s_mov_b32 s80, 0x80000
	s_mov_b64 s[26:27], 0x90000
	s_mov_b32 s81, 0x90000
	s_mov_b64 s[28:29], 0xa0000
	s_mov_b32 s82, 0xa0000
	s_mov_b64 s[30:31], 0xb0000
	s_mov_b32 s83, 0xb0000
	s_barrier
	s_branch .LBB0_269

.LBB0_272:
	ds_read_b128 v[146:149], v153
	ds_read_b128 v[156:159], v153 offset:1024
	ds_read_b128 v[160:163], v153 offset:2048
	ds_read_b128 v[164:167], v153 offset:3072
	ds_read_b128 v[168:171], v154
	ds_read_b128 v[172:175], v154 offset:1024
	ds_read_b128 v[176:179], v154 offset:2048
	ds_read_b128 v[180:183], v154 offset:3072
	s_add_u32 s62, s60, 0xfffc0080
	s_addc_u32 s63, s61, -1
	s_cmp_eq_u32 s86, 12
	s_cselect_b32 s65, s37, s63
	s_cselect_b32 s64, s43, s62
	s_cselect_b32 s63, s35, s85
	s_cselect_b32 s62, s55, s84
	s_add_i32 m0, s69, 0xc000
	ds_read_b128 v[184:187], v155
	ds_read_b128 v[192:195], v155 offset:1024
	ds_read_b128 v[196:199], v155 offset:2048
	ds_read_b128 v[200:203], v155 offset:3072
	ds_read_b128 v[204:207], v155 offset:4096
	ds_read_b128 v[208:211], v155 offset:5120
	ds_read_b128 v[212:215], v155 offset:6144
	ds_read_b128 v[216:219], v155 offset:7168
	global_load_lds_dwordx4 v138, s[60:61]
	v_lshl_add_u64 v[188:189], s[60:61], 0, v[140:141]
	s_add_i32 m0, s69, 0xe000
	s_nop 0
	global_load_lds_dwordx4 v[188:189], off
	s_waitcnt vmcnt(8)
	s_waitcnt lgkmcnt(0)
	s_barrier
	s_setprio 1
	s_waitcnt lgkmcnt(0)
	v_mfma_f32_16x16x32_bf16 v[124:127], v[146:149], v[184:187], v[124:127]
	v_mfma_f32_16x16x32_bf16 v[120:123], v[160:163], v[184:187], v[120:123]
	v_mfma_f32_16x16x32_bf16 v[116:119], v[146:149], v[196:199], v[116:119]
	v_mfma_f32_16x16x32_bf16 v[108:111], v[160:163], v[196:199], v[108:111]
	v_mfma_f32_16x16x32_bf16 v[100:103], v[146:149], v[204:207], v[100:103]
	v_mfma_f32_16x16x32_bf16 v[92:95], v[160:163], v[204:207], v[92:95]
	v_mfma_f32_16x16x32_bf16 v[84:87], v[146:149], v[212:215], v[84:87]
	v_mfma_f32_16x16x32_bf16 v[76:79], v[160:163], v[212:215], v[76:79]
	v_mfma_f32_16x16x32_bf16 v[124:127], v[156:159], v[192:195], v[124:127]
	v_mfma_f32_16x16x32_bf16 v[120:123], v[164:167], v[192:195], v[120:123]
	v_mfma_f32_16x16x32_bf16 v[116:119], v[156:159], v[200:203], v[116:119]
	v_mfma_f32_16x16x32_bf16 v[108:111], v[164:167], v[200:203], v[108:111]
	v_mfma_f32_16x16x32_bf16 v[100:103], v[156:159], v[208:211], v[100:103]
	v_mfma_f32_16x16x32_bf16 v[92:95], v[164:167], v[208:211], v[92:95]
	v_mfma_f32_16x16x32_bf16 v[84:87], v[156:159], v[216:219], v[84:87]
	v_mfma_f32_16x16x32_bf16 v[76:79], v[164:167], v[216:219], v[76:79]
	s_setprio 0
	s_setprio 1
	v_mfma_f32_16x16x32_bf16 v[112:115], v[168:171], v[184:187], v[112:115]
	v_mfma_f32_16x16x32_bf16 v[104:107], v[176:179], v[184:187], v[104:107]
	v_mfma_f32_16x16x32_bf16 v[96:99], v[168:171], v[196:199], v[96:99]
	v_mfma_f32_16x16x32_bf16 v[88:91], v[176:179], v[196:199], v[88:91]
	v_mfma_f32_16x16x32_bf16 v[80:83], v[168:171], v[204:207], v[80:83]
	v_mfma_f32_16x16x32_bf16 v[72:75], v[176:179], v[204:207], v[72:75]
	v_mfma_f32_16x16x32_bf16 v[68:71], v[168:171], v[212:215], v[68:71]
	v_mfma_f32_16x16x32_bf16 v[64:67], v[176:179], v[212:215], v[64:67]
	v_mfma_f32_16x16x32_bf16 v[112:115], v[172:175], v[192:195], v[112:115]
	v_mfma_f32_16x16x32_bf16 v[104:107], v[180:183], v[192:195], v[104:107]
	v_mfma_f32_16x16x32_bf16 v[96:99], v[172:175], v[200:203], v[96:99]
	v_mfma_f32_16x16x32_bf16 v[88:91], v[180:183], v[200:203], v[88:91]
	v_mfma_f32_16x16x32_bf16 v[80:83], v[172:175], v[208:211], v[80:83]
	v_mfma_f32_16x16x32_bf16 v[72:75], v[180:183], v[208:211], v[72:75]
	v_mfma_f32_16x16x32_bf16 v[68:71], v[172:175], v[216:219], v[68:71]
	v_mfma_f32_16x16x32_bf16 v[64:67], v[180:183], v[216:219], v[64:67]
	s_setprio 0
	s_barrier
	s_add_i32 s87, s76, s68
	v_lshl_add_u64 v[188:189], s[62:63], 0, v[132:133]
	s_mov_b32 m0, s87
	ds_read_b128 v[184:187], v155 offset:16384
	ds_read_b128 v[192:195], v155 offset:17408
	ds_read_b128 v[196:199], v155 offset:18432
	ds_read_b128 v[200:203], v155 offset:19456
	ds_read_b128 v[204:207], v155 offset:20480
	ds_read_b128 v[208:211], v155 offset:21504
	ds_read_b128 v[212:215], v155 offset:22528
	ds_read_b128 v[216:219], v155 offset:23552
	global_load_lds_dwordx4 v[188:189], off
	s_add_i32 m0, s87, 0x2000
	s_add_u32 s88, s62, 0x40000
	v_lshl_add_u64 v[220:221], s[62:63], 0, v[128:129]
	s_addc_u32 s89, s63, 0
	s_add_i32 s87, s77, s68
	global_load_lds_dwordx4 v[220:221], off
	s_mov_b32 m0, s87
	v_lshl_add_u64 v[224:225], s[64:65], 0, v[130:131]
	global_load_lds_dwordx4 v132, s[88:89]
	s_add_i32 m0, s87, 0x2000
	s_nop 0
	global_load_lds_dwordx4 v128, s[88:89]
	v_lshl_add_u64 v[222:223], s[64:65], 0, v[134:135]
	s_mov_b32 m0, s69
	s_nop 0
	global_load_lds_dwordx4 v[222:223], off
	s_mov_b32 m0, s70
	s_nop 0
	global_load_lds_dwordx4 v[224:225], off
	s_waitcnt vmcnt(8)
	s_waitcnt lgkmcnt(0)
	s_barrier
	s_setprio 1
	s_waitcnt lgkmcnt(0)
	v_mfma_f32_16x16x32_bf16 v[60:63], v[146:149], v[184:187], v[60:63]
	v_mfma_f32_16x16x32_bf16 v[56:59], v[160:163], v[184:187], v[56:59]
	v_mfma_f32_16x16x32_bf16 v[52:55], v[146:149], v[196:199], v[52:55]
	v_mfma_f32_16x16x32_bf16 v[44:47], v[160:163], v[196:199], v[44:47]
	v_mfma_f32_16x16x32_bf16 v[36:39], v[146:149], v[204:207], v[36:39]
	v_mfma_f32_16x16x32_bf16 v[28:31], v[160:163], v[204:207], v[28:31]
	v_mfma_f32_16x16x32_bf16 v[20:23], v[146:149], v[212:215], v[20:23]
	v_mfma_f32_16x16x32_bf16 v[12:15], v[160:163], v[212:215], v[12:15]
	v_mfma_f32_16x16x32_bf16 v[60:63], v[156:159], v[192:195], v[60:63]
	v_mfma_f32_16x16x32_bf16 v[56:59], v[164:167], v[192:195], v[56:59]
	v_mfma_f32_16x16x32_bf16 v[52:55], v[156:159], v[200:203], v[52:55]
	v_mfma_f32_16x16x32_bf16 v[44:47], v[164:167], v[200:203], v[44:47]
	v_mfma_f32_16x16x32_bf16 v[36:39], v[156:159], v[208:211], v[36:39]
	v_mfma_f32_16x16x32_bf16 v[28:31], v[164:167], v[208:211], v[28:31]
	v_mfma_f32_16x16x32_bf16 v[20:23], v[156:159], v[216:219], v[20:23]
	v_mfma_f32_16x16x32_bf16 v[12:15], v[164:167], v[216:219], v[12:15]
	s_setprio 0
	s_setprio 1
	v_mfma_f32_16x16x32_bf16 v[48:51], v[168:171], v[184:187], v[48:51]
	v_mfma_f32_16x16x32_bf16 v[40:43], v[176:179], v[184:187], v[40:43]
	v_mfma_f32_16x16x32_bf16 v[32:35], v[168:171], v[196:199], v[32:35]
	v_mfma_f32_16x16x32_bf16 v[24:27], v[176:179], v[196:199], v[24:27]
	v_mfma_f32_16x16x32_bf16 v[16:19], v[168:171], v[204:207], v[16:19]
	v_mfma_f32_16x16x32_bf16 v[8:11], v[176:179], v[204:207], v[8:11]
	v_mfma_f32_16x16x32_bf16 v[4:7], v[168:171], v[212:215], v[4:7]
	v_mfma_f32_16x16x32_bf16 v[0:3], v[176:179], v[212:215], v[0:3]
	v_mfma_f32_16x16x32_bf16 v[48:51], v[172:175], v[192:195], v[48:51]
	v_mfma_f32_16x16x32_bf16 v[40:43], v[180:183], v[192:195], v[40:43]
	v_mfma_f32_16x16x32_bf16 v[32:35], v[172:175], v[200:203], v[32:35]
	v_mfma_f32_16x16x32_bf16 v[24:27], v[180:183], v[200:203], v[24:27]
	v_mfma_f32_16x16x32_bf16 v[16:19], v[172:175], v[208:211], v[16:19]
	v_mfma_f32_16x16x32_bf16 v[8:11], v[180:183], v[208:211], v[8:11]
	v_mfma_f32_16x16x32_bf16 v[4:7], v[172:175], v[216:219], v[4:7]
	v_mfma_f32_16x16x32_bf16 v[0:3], v[180:183], v[216:219], v[0:3]
	s_setprio 0
	s_barrier
	s_add_i32 s87, 0, 0x18000
	s_add_i32 s88, 0, 0x1c000
	v_add_u32_e32 v164, s87, v151
	v_add_u32_e32 v180, s88, v151
	ds_read_b128 v[146:149], v164
	ds_read_b128 v[156:159], v164 offset:1024
	ds_read_b128 v[160:163], v164 offset:2048
	ds_read_b128 v[164:167], v164 offset:3072
	ds_read_b128 v[168:171], v180
	ds_read_b128 v[172:175], v180 offset:1024
	ds_read_b128 v[176:179], v180 offset:2048
	ds_read_b128 v[180:183], v180 offset:3072
	s_add_u32 s64, s64, 0x40000
	s_addc_u32 s65, s65, 0
	s_mov_b32 m0, s71
	ds_read_b128 v[184:187], v155 offset:32768
	ds_read_b128 v[192:195], v155 offset:33792
	ds_read_b128 v[196:199], v155 offset:34816
	ds_read_b128 v[200:203], v155 offset:35840
	ds_read_b128 v[204:207], v155 offset:36864
	ds_read_b128 v[208:211], v155 offset:37888
	ds_read_b128 v[212:215], v155 offset:38912
	ds_read_b128 v[216:219], v155 offset:39936
	global_load_lds_dwordx4 v134, s[64:65]
	s_mov_b32 m0, s72
	s_nop 0
	global_load_lds_dwordx4 v130, s[64:65]
	s_waitcnt vmcnt(8)
	s_waitcnt lgkmcnt(0)
	s_barrier
	s_setprio 1
	s_waitcnt lgkmcnt(0)
	v_mfma_f32_16x16x32_bf16 v[124:127], v[146:149], v[184:187], v[124:127]
	v_mfma_f32_16x16x32_bf16 v[120:123], v[160:163], v[184:187], v[120:123]
	v_mfma_f32_16x16x32_bf16 v[116:119], v[146:149], v[196:199], v[116:119]
	v_mfma_f32_16x16x32_bf16 v[108:111], v[160:163], v[196:199], v[108:111]
	v_mfma_f32_16x16x32_bf16 v[100:103], v[146:149], v[204:207], v[100:103]
	v_mfma_f32_16x16x32_bf16 v[92:95], v[160:163], v[204:207], v[92:95]
	v_mfma_f32_16x16x32_bf16 v[84:87], v[146:149], v[212:215], v[84:87]
	v_mfma_f32_16x16x32_bf16 v[76:79], v[160:163], v[212:215], v[76:79]
	v_mfma_f32_16x16x32_bf16 v[124:127], v[156:159], v[192:195], v[124:127]
	v_mfma_f32_16x16x32_bf16 v[120:123], v[164:167], v[192:195], v[120:123]
	v_mfma_f32_16x16x32_bf16 v[116:119], v[156:159], v[200:203], v[116:119]
	v_mfma_f32_16x16x32_bf16 v[108:111], v[164:167], v[200:203], v[108:111]
	v_mfma_f32_16x16x32_bf16 v[100:103], v[156:159], v[208:211], v[100:103]
	v_mfma_f32_16x16x32_bf16 v[92:95], v[164:167], v[208:211], v[92:95]
	v_mfma_f32_16x16x32_bf16 v[84:87], v[156:159], v[216:219], v[84:87]
	v_mfma_f32_16x16x32_bf16 v[76:79], v[164:167], v[216:219], v[76:79]
	s_setprio 0
	s_setprio 1
	v_mfma_f32_16x16x32_bf16 v[112:115], v[168:171], v[184:187], v[112:115]
	v_mfma_f32_16x16x32_bf16 v[104:107], v[176:179], v[184:187], v[104:107]
	v_mfma_f32_16x16x32_bf16 v[96:99], v[168:171], v[196:199], v[96:99]
	v_mfma_f32_16x16x32_bf16 v[88:91], v[176:179], v[196:199], v[88:91]
	v_mfma_f32_16x16x32_bf16 v[80:83], v[168:171], v[204:207], v[80:83]
	v_mfma_f32_16x16x32_bf16 v[72:75], v[176:179], v[204:207], v[72:75]
	v_mfma_f32_16x16x32_bf16 v[68:71], v[168:171], v[212:215], v[68:71]
	v_mfma_f32_16x16x32_bf16 v[64:67], v[176:179], v[212:215], v[64:67]
	v_mfma_f32_16x16x32_bf16 v[112:115], v[172:175], v[192:195], v[112:115]
	v_mfma_f32_16x16x32_bf16 v[104:107], v[180:183], v[192:195], v[104:107]
	v_mfma_f32_16x16x32_bf16 v[96:99], v[172:175], v[200:203], v[96:99]
	v_mfma_f32_16x16x32_bf16 v[88:91], v[180:183], v[200:203], v[88:91]
	v_mfma_f32_16x16x32_bf16 v[80:83], v[172:175], v[208:211], v[80:83]
	v_mfma_f32_16x16x32_bf16 v[72:75], v[180:183], v[208:211], v[72:75]
	v_mfma_f32_16x16x32_bf16 v[68:71], v[172:175], v[216:219], v[68:71]
	v_mfma_f32_16x16x32_bf16 v[64:67], v[180:183], v[216:219], v[64:67]
	s_setprio 0
	s_barrier
	s_add_i32 s64, s87, s68
	v_lshl_add_u64 v[188:189], v[188:189], 0, s[10:11]
	s_mov_b32 m0, s64
	ds_read_b128 v[184:187], v155 offset:49152
	ds_read_b128 v[192:195], v155 offset:50176
	ds_read_b128 v[196:199], v155 offset:51200
	ds_read_b128 v[200:203], v155 offset:52224
	ds_read_b128 v[204:207], v155 offset:53248
	ds_read_b128 v[208:211], v155 offset:54272
	ds_read_b128 v[212:215], v155 offset:55296
	ds_read_b128 v[216:219], v155 offset:56320
	global_load_lds_dwordx4 v[188:189], off
	s_add_i32 m0, s64, 0x2000
	s_add_u32 s62, s62, 0x40080
	v_lshl_add_u64 v[188:189], v[220:221], 0, s[10:11]
	s_addc_u32 s63, s63, 0
	s_add_i32 s64, s88, s68
	global_load_lds_dwordx4 v[188:189], off
	s_mov_b32 m0, s64
	s_nop 0
	global_load_lds_dwordx4 v132, s[62:63]
	s_add_i32 m0, s64, 0x2000
	s_nop 0
	global_load_lds_dwordx4 v128, s[62:63]
	v_lshl_add_u64 v[188:189], v[222:223], 0, s[10:11]
	s_mov_b32 m0, s33
	s_nop 0
	global_load_lds_dwordx4 v[188:189], off
	v_lshl_add_u64 v[188:189], v[224:225], 0, s[10:11]
	s_mov_b32 m0, s74
	s_nop 0
	global_load_lds_dwordx4 v[188:189], off
	s_waitcnt vmcnt(8)
	s_waitcnt lgkmcnt(0)
	s_barrier
	s_setprio 1
	s_waitcnt lgkmcnt(0)
	v_mfma_f32_16x16x32_bf16 v[60:63], v[146:149], v[184:187], v[60:63]
	v_mfma_f32_16x16x32_bf16 v[56:59], v[160:163], v[184:187], v[56:59]
	v_mfma_f32_16x16x32_bf16 v[52:55], v[146:149], v[196:199], v[52:55]
	v_mfma_f32_16x16x32_bf16 v[44:47], v[160:163], v[196:199], v[44:47]
	v_mfma_f32_16x16x32_bf16 v[36:39], v[146:149], v[204:207], v[36:39]
	v_mfma_f32_16x16x32_bf16 v[28:31], v[160:163], v[204:207], v[28:31]
	v_mfma_f32_16x16x32_bf16 v[20:23], v[146:149], v[212:215], v[20:23]
	v_mfma_f32_16x16x32_bf16 v[12:15], v[160:163], v[212:215], v[12:15]
	v_mfma_f32_16x16x32_bf16 v[60:63], v[156:159], v[192:195], v[60:63]
	v_mfma_f32_16x16x32_bf16 v[56:59], v[164:167], v[192:195], v[56:59]
	v_mfma_f32_16x16x32_bf16 v[52:55], v[156:159], v[200:203], v[52:55]
	v_mfma_f32_16x16x32_bf16 v[44:47], v[164:167], v[200:203], v[44:47]
	v_mfma_f32_16x16x32_bf16 v[36:39], v[156:159], v[208:211], v[36:39]
	v_mfma_f32_16x16x32_bf16 v[28:31], v[164:167], v[208:211], v[28:31]
	v_mfma_f32_16x16x32_bf16 v[20:23], v[156:159], v[216:219], v[20:23]
	v_mfma_f32_16x16x32_bf16 v[12:15], v[164:167], v[216:219], v[12:15]
	s_setprio 0
	s_setprio 1
	v_mfma_f32_16x16x32_bf16 v[48:51], v[168:171], v[184:187], v[48:51]
	v_mfma_f32_16x16x32_bf16 v[40:43], v[176:179], v[184:187], v[40:43]
	v_mfma_f32_16x16x32_bf16 v[32:35], v[168:171], v[196:199], v[32:35]
	v_mfma_f32_16x16x32_bf16 v[24:27], v[176:179], v[196:199], v[24:27]
	v_mfma_f32_16x16x32_bf16 v[16:19], v[168:171], v[204:207], v[16:19]
	v_mfma_f32_16x16x32_bf16 v[8:11], v[176:179], v[204:207], v[8:11]
	v_mfma_f32_16x16x32_bf16 v[4:7], v[168:171], v[212:215], v[4:7]
	v_mfma_f32_16x16x32_bf16 v[0:3], v[176:179], v[212:215], v[0:3]
	v_mfma_f32_16x16x32_bf16 v[48:51], v[172:175], v[192:195], v[48:51]
	v_mfma_f32_16x16x32_bf16 v[40:43], v[180:183], v[192:195], v[40:43]
	v_mfma_f32_16x16x32_bf16 v[32:35], v[172:175], v[200:203], v[32:35]
	v_mfma_f32_16x16x32_bf16 v[24:27], v[180:183], v[200:203], v[24:27]
	v_mfma_f32_16x16x32_bf16 v[16:19], v[172:175], v[208:211], v[16:19]
	v_mfma_f32_16x16x32_bf16 v[8:11], v[180:183], v[208:211], v[8:11]
	v_mfma_f32_16x16x32_bf16 v[4:7], v[172:175], v[216:219], v[4:7]
	v_mfma_f32_16x16x32_bf16 v[0:3], v[180:183], v[216:219], v[0:3]
	s_setprio 0
	s_barrier
	s_add_i32 s86, s86, 2
	s_add_u32 s60, s60, 0x100
	s_addc_u32 s61, s61, 0
	s_add_u32 s84, s84, 0x100
	s_addc_u32 s85, s85, 0
	s_cmp_gt_u32 s86, 13
	s_cbranch_scc0 .LBB0_272
	s_and_b64 vcc, exec, s[12:13]
	s_cbranch_vccz .LBB0_277
	s_barrier
	v_lshl_add_u32 v148, s42, 8, v150
	s_cmp_gt_i32 s54, 7
	s_mov_b64 s[42:43], -1
	s_cbranch_scc1 .LBB0_278

.LBB0_292:
	s_add_u32 s10, s46, 0x18000000
	s_addc_u32 s11, s47, 0
	s_lshl_b32 s5, s5, 5
	s_mov_b64 s[12:13], 0x80
	s_and_b32 s5, s5, 0x60
	s_add_i32 m0, s35, 0x18000
	v_lshl_add_u64 v[6:7], v[6:7], 0, s[12:13]
	s_lshl_b32 s18, s15, 13
	s_lshl_b32 s19, s5, 7
	s_waitcnt vmcnt(2)
	s_barrier
	global_load_lds_dwordx4 v[6:7], off
	v_lshl_add_u64 v[4:5], v[4:5], 0, s[12:13]
	s_add_i32 m0, s35, 0x1a000
	s_add_i32 s63, s35, 0x8000
	s_add_i32 s64, s35, 0xa000
	global_load_lds_dwordx4 v[4:5], off
	v_lshl_add_u64 v[0:1], v[0:1], 0, s[12:13]
	s_mov_b32 m0, s63
	s_add_u32 s16, s38, 0x40080
	global_load_lds_dwordx4 v[0:1], off
	v_lshl_add_u64 v[0:1], v[2:3], 0, s[12:13]
	s_mov_b32 m0, s64
	s_addc_u32 s17, s39, 0
	global_load_lds_dwordx4 v[0:1], off
	s_add_i32 m0, s35, 0x1c000
	s_nop 0
	global_load_lds_dwordx4 v130, s[16:17]
	s_add_i32 m0, s35, 0x1e000
	s_cmpk_lt_u32 s14, 0x100
	global_load_lds_dwordx4 v134, s[16:17]
	v_lshrrev_b32_e32 v1, 1, v8
	v_and_b32_e32 v1, 24, v1
	v_and_b32_e32 v0, 15, v8
	v_lshlrev_b32_e32 v2, 1, v1
	v_lshl_or_b32 v146, s15, 6, v0
	v_lshl_or_b32 v0, v0, 6, v2
	v_lshlrev_b32_e32 v2, 2, v8
	v_and_b32_e32 v2, 32, v2
	v_bitop3_b32 v3, v0, s18, v2 bitop3:0xde
	v_bitop3_b32 v147, v0, s19, v2 bitop3:0xde
	v_lshlrev_b32_e32 v0, 14, v9
	v_and_b32_e32 v0, 0xffff8000, v0
	v_or_b32_e32 v148, s5, v1
	v_lshl_add_u32 v0, v10, 11, v0
	v_and_b32_e32 v1, 1, v9
	v_lshl_or_b32 v0, v1, 6, v0
	v_lshl_add_u32 v136, v11, 1, v0
	v_lshlrev_b32_e32 v0, 14, v12
	v_and_b32_e32 v0, 0xffff8000, v0
	s_waitcnt vmcnt(6)
	v_lshl_add_u32 v0, v13, 11, v0
	v_and_b32_e32 v1, 1, v12
	s_cselect_b64 s[14:15], -1, 0
	v_lshl_or_b32 v0, v1, 6, v0
	s_add_i32 s66, 0, 0x10000
	s_add_i32 s67, 0, 0x14000
	s_sext_i32_i16 s54, s4
	s_ashr_i32 s65, s3, 31
	v_mov_b32_e32 v137, v131
	v_lshl_add_u32 v138, v14, 1, v0
	v_mov_b32_e32 v139, v131
	v_mov_b64_e32 v[140:141], 0x200
	v_mov_b64_e32 v[142:143], 0x1ff
	v_add_u32_e32 v149, s66, v147
	v_add_u32_e32 v150, s67, v147
	v_add_u32_e32 v151, 0, v3
	s_mov_b64 s[16:17], 0x800000
	s_mov_b32 s68, 0x800000
	s_mov_b64 s[18:19], 0x900000
	s_mov_b32 s69, 0x900000
	s_mov_b64 s[20:21], 0xa00000
	s_mov_b32 s70, 0xa00000
	s_mov_b64 s[22:23], 0xb00000
	s_mov_b32 s71, 0xb00000
	s_barrier
	s_branch .LBB0_295

.LBB0_302:
	ds_read_b128 v[152:155], v149
	ds_read_b128 v[156:159], v149 offset:1024
	ds_read_b128 v[160:163], v149 offset:2048
	ds_read_b128 v[164:167], v149 offset:3072
	ds_read_b128 v[168:171], v150
	ds_read_b128 v[172:175], v150 offset:1024
	ds_read_b128 v[176:179], v150 offset:2048
	ds_read_b128 v[180:183], v150 offset:3072
	s_add_u32 s38, s36, 0xfffc0080
	s_addc_u32 s39, s37, -1
	s_cmp_eq_u32 s75, 12
	s_cselect_b32 s41, s27, s39
	s_cselect_b32 s40, s55, s38
	s_cselect_b32 s39, s25, s74
	s_cselect_b32 s38, s72, s73
	v_lshl_add_u64 v[144:145], s[36:37], 0, v[136:137]
	s_add_i32 m0, s35, 0xc000
	ds_read_b128 v[184:187], v151
	ds_read_b128 v[192:195], v151 offset:1024
	ds_read_b128 v[196:199], v151 offset:2048
	ds_read_b128 v[200:203], v151 offset:3072
	ds_read_b128 v[204:207], v151 offset:4096
	ds_read_b128 v[208:211], v151 offset:5120
	ds_read_b128 v[212:215], v151 offset:6144
	ds_read_b128 v[216:219], v151 offset:7168
	global_load_lds_dwordx4 v[144:145], off
	s_add_i32 m0, s35, 0xe000
	s_nop 0
	global_load_lds_dwordx4 v138, s[36:37]
	s_waitcnt vmcnt(8)
	s_waitcnt lgkmcnt(0)
	s_barrier
	s_setprio 1
	s_waitcnt lgkmcnt(0)
	v_mfma_f32_16x16x32_bf16 v[124:127], v[152:155], v[184:187], v[124:127]
	v_mfma_f32_16x16x32_bf16 v[120:123], v[160:163], v[184:187], v[120:123]
	v_mfma_f32_16x16x32_bf16 v[116:119], v[152:155], v[196:199], v[116:119]
	v_mfma_f32_16x16x32_bf16 v[108:111], v[160:163], v[196:199], v[108:111]
	v_mfma_f32_16x16x32_bf16 v[100:103], v[152:155], v[204:207], v[100:103]
	v_mfma_f32_16x16x32_bf16 v[92:95], v[160:163], v[204:207], v[92:95]
	v_mfma_f32_16x16x32_bf16 v[84:87], v[152:155], v[212:215], v[84:87]
	v_mfma_f32_16x16x32_bf16 v[76:79], v[160:163], v[212:215], v[76:79]
	v_mfma_f32_16x16x32_bf16 v[124:127], v[156:159], v[192:195], v[124:127]
	v_mfma_f32_16x16x32_bf16 v[120:123], v[164:167], v[192:195], v[120:123]
	v_mfma_f32_16x16x32_bf16 v[116:119], v[156:159], v[200:203], v[116:119]
	v_mfma_f32_16x16x32_bf16 v[108:111], v[164:167], v[200:203], v[108:111]
	v_mfma_f32_16x16x32_bf16 v[100:103], v[156:159], v[208:211], v[100:103]
	v_mfma_f32_16x16x32_bf16 v[92:95], v[164:167], v[208:211], v[92:95]
	v_mfma_f32_16x16x32_bf16 v[84:87], v[156:159], v[216:219], v[84:87]
	v_mfma_f32_16x16x32_bf16 v[76:79], v[164:167], v[216:219], v[76:79]
	s_setprio 0
	s_setprio 1
	v_mfma_f32_16x16x32_bf16 v[112:115], v[168:171], v[184:187], v[112:115]
	v_mfma_f32_16x16x32_bf16 v[104:107], v[176:179], v[184:187], v[104:107]
	v_mfma_f32_16x16x32_bf16 v[96:99], v[168:171], v[196:199], v[96:99]
	v_mfma_f32_16x16x32_bf16 v[88:91], v[176:179], v[196:199], v[88:91]
	v_mfma_f32_16x16x32_bf16 v[80:83], v[168:171], v[204:207], v[80:83]
	v_mfma_f32_16x16x32_bf16 v[72:75], v[176:179], v[204:207], v[72:75]
	v_mfma_f32_16x16x32_bf16 v[68:71], v[168:171], v[212:215], v[68:71]
	v_mfma_f32_16x16x32_bf16 v[64:67], v[176:179], v[212:215], v[64:67]
	v_mfma_f32_16x16x32_bf16 v[112:115], v[172:175], v[192:195], v[112:115]
	v_mfma_f32_16x16x32_bf16 v[104:107], v[180:183], v[192:195], v[104:107]
	v_mfma_f32_16x16x32_bf16 v[96:99], v[172:175], v[200:203], v[96:99]
	v_mfma_f32_16x16x32_bf16 v[88:91], v[180:183], v[200:203], v[88:91]
	v_mfma_f32_16x16x32_bf16 v[80:83], v[172:175], v[208:211], v[80:83]
	v_mfma_f32_16x16x32_bf16 v[72:75], v[180:183], v[208:211], v[72:75]
	v_mfma_f32_16x16x32_bf16 v[68:71], v[172:175], v[216:219], v[68:71]
	v_mfma_f32_16x16x32_bf16 v[64:67], v[180:183], v[216:219], v[64:67]
	s_setprio 0
	s_barrier
	s_add_i32 s76, s66, s53
	v_lshl_add_u64 v[144:145], s[38:39], 0, v[130:131]
	s_mov_b32 m0, s76
	ds_read_b128 v[184:187], v151 offset:16384
	ds_read_b128 v[192:195], v151 offset:17408
	ds_read_b128 v[196:199], v151 offset:18432
	ds_read_b128 v[200:203], v151 offset:19456
	ds_read_b128 v[204:207], v151 offset:20480
	ds_read_b128 v[208:211], v151 offset:21504
	ds_read_b128 v[212:215], v151 offset:22528
	ds_read_b128 v[216:219], v151 offset:23552
	global_load_lds_dwordx4 v[144:145], off
	s_add_i32 m0, s76, 0x2000
	s_add_u32 s76, s38, 0x40000
	v_lshl_add_u64 v[188:189], s[38:39], 0, v[134:135]
	s_addc_u32 s77, s39, 0
	s_add_i32 s80, s67, s53
	global_load_lds_dwordx4 v[188:189], off
	s_mov_b32 m0, s80
	v_lshl_add_u64 v[222:223], s[40:41], 0, v[132:133]
	global_load_lds_dwordx4 v130, s[76:77]
	s_add_i32 m0, s80, 0x2000
	s_nop 0
	global_load_lds_dwordx4 v134, s[76:77]
	v_lshl_add_u64 v[220:221], s[40:41], 0, v[128:129]
	s_mov_b32 m0, s35
	s_nop 0
	global_load_lds_dwordx4 v[220:221], off
	s_mov_b32 m0, s33
	s_nop 0
	global_load_lds_dwordx4 v[222:223], off
	s_waitcnt vmcnt(8)
	s_waitcnt lgkmcnt(0)
	s_barrier
	s_setprio 1
	s_waitcnt lgkmcnt(0)
	v_mfma_f32_16x16x32_bf16 v[60:63], v[152:155], v[184:187], v[60:63]
	v_mfma_f32_16x16x32_bf16 v[56:59], v[160:163], v[184:187], v[56:59]
	v_mfma_f32_16x16x32_bf16 v[52:55], v[152:155], v[196:199], v[52:55]
	v_mfma_f32_16x16x32_bf16 v[44:47], v[160:163], v[196:199], v[44:47]
	v_mfma_f32_16x16x32_bf16 v[36:39], v[152:155], v[204:207], v[36:39]
	v_mfma_f32_16x16x32_bf16 v[28:31], v[160:163], v[204:207], v[28:31]
	v_mfma_f32_16x16x32_bf16 v[20:23], v[152:155], v[212:215], v[20:23]
	v_mfma_f32_16x16x32_bf16 v[12:15], v[160:163], v[212:215], v[12:15]
	v_mfma_f32_16x16x32_bf16 v[60:63], v[156:159], v[192:195], v[60:63]
	v_mfma_f32_16x16x32_bf16 v[56:59], v[164:167], v[192:195], v[56:59]
	v_mfma_f32_16x16x32_bf16 v[52:55], v[156:159], v[200:203], v[52:55]
	v_mfma_f32_16x16x32_bf16 v[44:47], v[164:167], v[200:203], v[44:47]
	v_mfma_f32_16x16x32_bf16 v[36:39], v[156:159], v[208:211], v[36:39]
	v_mfma_f32_16x16x32_bf16 v[28:31], v[164:167], v[208:211], v[28:31]
	v_mfma_f32_16x16x32_bf16 v[20:23], v[156:159], v[216:219], v[20:23]
	v_mfma_f32_16x16x32_bf16 v[12:15], v[164:167], v[216:219], v[12:15]
	s_setprio 0
	s_setprio 1
	v_mfma_f32_16x16x32_bf16 v[48:51], v[168:171], v[184:187], v[48:51]
	v_mfma_f32_16x16x32_bf16 v[40:43], v[176:179], v[184:187], v[40:43]
	v_mfma_f32_16x16x32_bf16 v[32:35], v[168:171], v[196:199], v[32:35]
	v_mfma_f32_16x16x32_bf16 v[24:27], v[176:179], v[196:199], v[24:27]
	v_mfma_f32_16x16x32_bf16 v[16:19], v[168:171], v[204:207], v[16:19]
	v_mfma_f32_16x16x32_bf16 v[8:11], v[176:179], v[204:207], v[8:11]
	v_mfma_f32_16x16x32_bf16 v[4:7], v[168:171], v[212:215], v[4:7]
	v_mfma_f32_16x16x32_bf16 v[0:3], v[176:179], v[212:215], v[0:3]
	v_mfma_f32_16x16x32_bf16 v[48:51], v[172:175], v[192:195], v[48:51]
	v_mfma_f32_16x16x32_bf16 v[40:43], v[180:183], v[192:195], v[40:43]
	v_mfma_f32_16x16x32_bf16 v[32:35], v[172:175], v[200:203], v[32:35]
	v_mfma_f32_16x16x32_bf16 v[24:27], v[180:183], v[200:203], v[24:27]
	v_mfma_f32_16x16x32_bf16 v[16:19], v[172:175], v[208:211], v[16:19]
	v_mfma_f32_16x16x32_bf16 v[8:11], v[180:183], v[208:211], v[8:11]
	v_mfma_f32_16x16x32_bf16 v[4:7], v[172:175], v[216:219], v[4:7]
	v_mfma_f32_16x16x32_bf16 v[0:3], v[180:183], v[216:219], v[0:3]
	s_setprio 0
	s_barrier
	s_add_i32 s76, 0, 0x18000
	s_add_i32 s77, 0, 0x1c000
	v_add_u32_e32 v164, s76, v147
	v_add_u32_e32 v180, s77, v147
	ds_read_b128 v[152:155], v164
	ds_read_b128 v[156:159], v164 offset:1024
	ds_read_b128 v[160:163], v164 offset:2048
	ds_read_b128 v[164:167], v164 offset:3072
	ds_read_b128 v[168:171], v180
	ds_read_b128 v[172:175], v180 offset:1024
	ds_read_b128 v[176:179], v180 offset:2048
	ds_read_b128 v[180:183], v180 offset:3072
	s_add_u32 s40, s40, 0x40000
	s_addc_u32 s41, s41, 0
	s_mov_b32 m0, s60
	ds_read_b128 v[184:187], v151 offset:32768
	ds_read_b128 v[192:195], v151 offset:33792
	ds_read_b128 v[196:199], v151 offset:34816
	ds_read_b128 v[200:203], v151 offset:35840
	ds_read_b128 v[204:207], v151 offset:36864
	ds_read_b128 v[208:211], v151 offset:37888
	ds_read_b128 v[212:215], v151 offset:38912
	ds_read_b128 v[216:219], v151 offset:39936
	global_load_lds_dwordx4 v128, s[40:41]
	s_mov_b32 m0, s61
	s_nop 0
	global_load_lds_dwordx4 v132, s[40:41]
	s_waitcnt vmcnt(8)
	s_waitcnt lgkmcnt(0)
	s_barrier
	s_setprio 1
	s_waitcnt lgkmcnt(0)
	v_mfma_f32_16x16x32_bf16 v[124:127], v[152:155], v[184:187], v[124:127]
	v_mfma_f32_16x16x32_bf16 v[120:123], v[160:163], v[184:187], v[120:123]
	v_mfma_f32_16x16x32_bf16 v[116:119], v[152:155], v[196:199], v[116:119]
	v_mfma_f32_16x16x32_bf16 v[108:111], v[160:163], v[196:199], v[108:111]
	v_mfma_f32_16x16x32_bf16 v[100:103], v[152:155], v[204:207], v[100:103]
	v_mfma_f32_16x16x32_bf16 v[92:95], v[160:163], v[204:207], v[92:95]
	v_mfma_f32_16x16x32_bf16 v[84:87], v[152:155], v[212:215], v[84:87]
	v_mfma_f32_16x16x32_bf16 v[76:79], v[160:163], v[212:215], v[76:79]
	v_mfma_f32_16x16x32_bf16 v[124:127], v[156:159], v[192:195], v[124:127]
	v_mfma_f32_16x16x32_bf16 v[120:123], v[164:167], v[192:195], v[120:123]
	v_mfma_f32_16x16x32_bf16 v[116:119], v[156:159], v[200:203], v[116:119]
	v_mfma_f32_16x16x32_bf16 v[108:111], v[164:167], v[200:203], v[108:111]
	v_mfma_f32_16x16x32_bf16 v[100:103], v[156:159], v[208:211], v[100:103]
	v_mfma_f32_16x16x32_bf16 v[92:95], v[164:167], v[208:211], v[92:95]
	v_mfma_f32_16x16x32_bf16 v[84:87], v[156:159], v[216:219], v[84:87]
	v_mfma_f32_16x16x32_bf16 v[76:79], v[164:167], v[216:219], v[76:79]
	s_setprio 0
	s_setprio 1
	v_mfma_f32_16x16x32_bf16 v[112:115], v[168:171], v[184:187], v[112:115]
	v_mfma_f32_16x16x32_bf16 v[104:107], v[176:179], v[184:187], v[104:107]
	v_mfma_f32_16x16x32_bf16 v[96:99], v[168:171], v[196:199], v[96:99]
	v_mfma_f32_16x16x32_bf16 v[88:91], v[176:179], v[196:199], v[88:91]
	v_mfma_f32_16x16x32_bf16 v[80:83], v[168:171], v[204:207], v[80:83]
	v_mfma_f32_16x16x32_bf16 v[72:75], v[176:179], v[204:207], v[72:75]
	v_mfma_f32_16x16x32_bf16 v[68:71], v[168:171], v[212:215], v[68:71]
	v_mfma_f32_16x16x32_bf16 v[64:67], v[176:179], v[212:215], v[64:67]
	v_mfma_f32_16x16x32_bf16 v[112:115], v[172:175], v[192:195], v[112:115]
	v_mfma_f32_16x16x32_bf16 v[104:107], v[180:183], v[192:195], v[104:107]
	v_mfma_f32_16x16x32_bf16 v[96:99], v[172:175], v[200:203], v[96:99]
	v_mfma_f32_16x16x32_bf16 v[88:91], v[180:183], v[200:203], v[88:91]
	v_mfma_f32_16x16x32_bf16 v[80:83], v[172:175], v[208:211], v[80:83]
	v_mfma_f32_16x16x32_bf16 v[72:75], v[180:183], v[208:211], v[72:75]
	v_mfma_f32_16x16x32_bf16 v[68:71], v[172:175], v[216:219], v[68:71]
	v_mfma_f32_16x16x32_bf16 v[64:67], v[180:183], v[216:219], v[64:67]
	s_setprio 0
	s_barrier
	s_add_i32 s40, s76, s53
	v_lshl_add_u64 v[144:145], v[144:145], 0, s[12:13]
	s_mov_b32 m0, s40
	ds_read_b128 v[184:187], v151 offset:49152
	ds_read_b128 v[192:195], v151 offset:50176
	ds_read_b128 v[196:199], v151 offset:51200
	ds_read_b128 v[200:203], v151 offset:52224
	ds_read_b128 v[204:207], v151 offset:53248
	ds_read_b128 v[208:211], v151 offset:54272
	ds_read_b128 v[212:215], v151 offset:55296
	ds_read_b128 v[216:219], v151 offset:56320
	global_load_lds_dwordx4 v[144:145], off
	s_add_i32 m0, s40, 0x2000
	s_add_u32 s38, s38, 0x40080
	v_lshl_add_u64 v[144:145], v[188:189], 0, s[12:13]
	s_addc_u32 s39, s39, 0
	s_add_i32 s40, s77, s53
	global_load_lds_dwordx4 v[144:145], off
	s_mov_b32 m0, s40
	s_nop 0
	global_load_lds_dwordx4 v130, s[38:39]
	s_add_i32 m0, s40, 0x2000
	s_nop 0
	global_load_lds_dwordx4 v134, s[38:39]
	v_lshl_add_u64 v[144:145], v[220:221], 0, s[12:13]
	s_mov_b32 m0, s63
	s_nop 0
	global_load_lds_dwordx4 v[144:145], off
	v_lshl_add_u64 v[144:145], v[222:223], 0, s[12:13]
	s_mov_b32 m0, s64
	s_nop 0
	global_load_lds_dwordx4 v[144:145], off
	s_waitcnt vmcnt(8)
	s_waitcnt lgkmcnt(0)
	s_barrier
	s_setprio 1
	s_waitcnt lgkmcnt(0)
	v_mfma_f32_16x16x32_bf16 v[60:63], v[152:155], v[184:187], v[60:63]
	v_mfma_f32_16x16x32_bf16 v[56:59], v[160:163], v[184:187], v[56:59]
	v_mfma_f32_16x16x32_bf16 v[52:55], v[152:155], v[196:199], v[52:55]
	v_mfma_f32_16x16x32_bf16 v[44:47], v[160:163], v[196:199], v[44:47]
	v_mfma_f32_16x16x32_bf16 v[36:39], v[152:155], v[204:207], v[36:39]
	v_mfma_f32_16x16x32_bf16 v[28:31], v[160:163], v[204:207], v[28:31]
	v_mfma_f32_16x16x32_bf16 v[20:23], v[152:155], v[212:215], v[20:23]
	v_mfma_f32_16x16x32_bf16 v[12:15], v[160:163], v[212:215], v[12:15]
	v_mfma_f32_16x16x32_bf16 v[60:63], v[156:159], v[192:195], v[60:63]
	v_mfma_f32_16x16x32_bf16 v[56:59], v[164:167], v[192:195], v[56:59]
	v_mfma_f32_16x16x32_bf16 v[52:55], v[156:159], v[200:203], v[52:55]
	v_mfma_f32_16x16x32_bf16 v[44:47], v[164:167], v[200:203], v[44:47]
	v_mfma_f32_16x16x32_bf16 v[36:39], v[156:159], v[208:211], v[36:39]
	v_mfma_f32_16x16x32_bf16 v[28:31], v[164:167], v[208:211], v[28:31]
	v_mfma_f32_16x16x32_bf16 v[20:23], v[156:159], v[216:219], v[20:23]
	v_mfma_f32_16x16x32_bf16 v[12:15], v[164:167], v[216:219], v[12:15]
	s_setprio 0
	s_setprio 1
	v_mfma_f32_16x16x32_bf16 v[48:51], v[168:171], v[184:187], v[48:51]
	v_mfma_f32_16x16x32_bf16 v[40:43], v[176:179], v[184:187], v[40:43]
	v_mfma_f32_16x16x32_bf16 v[32:35], v[168:171], v[196:199], v[32:35]
	v_mfma_f32_16x16x32_bf16 v[24:27], v[176:179], v[196:199], v[24:27]
	v_mfma_f32_16x16x32_bf16 v[16:19], v[168:171], v[204:207], v[16:19]
	v_mfma_f32_16x16x32_bf16 v[8:11], v[176:179], v[204:207], v[8:11]
	v_mfma_f32_16x16x32_bf16 v[4:7], v[168:171], v[212:215], v[4:7]
	v_mfma_f32_16x16x32_bf16 v[0:3], v[176:179], v[212:215], v[0:3]
	v_mfma_f32_16x16x32_bf16 v[48:51], v[172:175], v[192:195], v[48:51]
	v_mfma_f32_16x16x32_bf16 v[40:43], v[180:183], v[192:195], v[40:43]
	v_mfma_f32_16x16x32_bf16 v[32:35], v[172:175], v[200:203], v[32:35]
	v_mfma_f32_16x16x32_bf16 v[24:27], v[180:183], v[200:203], v[24:27]
	v_mfma_f32_16x16x32_bf16 v[16:19], v[172:175], v[208:211], v[16:19]
	v_mfma_f32_16x16x32_bf16 v[8:11], v[180:183], v[208:211], v[8:11]
	v_mfma_f32_16x16x32_bf16 v[4:7], v[172:175], v[216:219], v[4:7]
	v_mfma_f32_16x16x32_bf16 v[0:3], v[180:183], v[216:219], v[0:3]
	s_setprio 0
	s_barrier
	s_add_i32 s75, s75, 2
	s_add_u32 s36, s36, 0x100
	s_addc_u32 s37, s37, 0
	s_add_u32 s73, s73, 0x100
	s_addc_u32 s74, s74, 0
	s_cmp_gt_u32 s75, 13
	s_cbranch_scc0 .LBB0_302
	s_and_b64 vcc, exec, s[14:15]
	s_cbranch_vccz .LBB0_305
	s_barrier

.LBB0_690:
	s_lshl_b32 s5, s5, 5
	s_mov_b64 s[12:13], 0x80
	s_and_b32 s5, s5, 0x60
	s_add_i32 m0, s31, 0x18000
	v_lshl_add_u64 v[6:7], v[6:7], 0, s[12:13]
	s_lshl_b32 s18, s15, 13
	s_lshl_b32 s19, s5, 7
	s_waitcnt vmcnt(2)
	s_barrier
	global_load_lds_dwordx4 v[6:7], off
	v_lshl_add_u64 v[2:3], v[2:3], 0, s[12:13]
	s_add_i32 m0, s31, 0x1a000
	s_add_i32 s63, s31, 0x8000
	s_add_i32 s64, s31, 0xa000
	global_load_lds_dwordx4 v[2:3], off
	v_lshl_add_u64 v[0:1], v[0:1], 0, s[12:13]
	s_mov_b32 m0, s63
	s_add_u32 s16, s38, 0x40080
	global_load_lds_dwordx4 v[0:1], off
	v_lshl_add_u64 v[0:1], v[4:5], 0, s[12:13]
	s_mov_b32 m0, s64
	s_addc_u32 s17, s39, 0
	global_load_lds_dwordx4 v[0:1], off
	s_add_i32 m0, s31, 0x1c000
	s_nop 0
	global_load_lds_dwordx4 v130, s[16:17]
	s_add_i32 m0, s31, 0x1e000
	s_cmpk_lt_u32 s14, 0x100
	global_load_lds_dwordx4 v134, s[16:17]
	v_lshrrev_b32_e32 v1, 1, v8
	v_and_b32_e32 v1, 24, v1
	v_and_b32_e32 v0, 15, v8
	v_lshlrev_b32_e32 v2, 1, v1
	v_lshl_or_b32 v146, s15, 6, v0
	v_lshl_or_b32 v0, v0, 6, v2
	v_lshlrev_b32_e32 v2, 2, v8
	v_and_b32_e32 v2, 32, v2
	v_bitop3_b32 v3, v0, s18, v2 bitop3:0xde
	v_bitop3_b32 v147, v0, s19, v2 bitop3:0xde
	v_lshlrev_b32_e32 v0, 14, v9
	v_and_b32_e32 v0, 0xffff8000, v0
	v_or_b32_e32 v148, s5, v1
	v_lshl_add_u32 v0, v10, 11, v0
	v_and_b32_e32 v1, 1, v9
	v_lshl_or_b32 v0, v1, 6, v0
	v_lshl_add_u32 v136, v11, 1, v0
	v_lshlrev_b32_e32 v0, 14, v12
	v_and_b32_e32 v0, 0xffff8000, v0
	s_waitcnt vmcnt(6)
	v_lshl_add_u32 v0, v13, 11, v0
	v_and_b32_e32 v1, 1, v12
	s_cselect_b64 s[14:15], -1, 0
	v_lshl_or_b32 v0, v1, 6, v0
	s_add_i32 s66, 0, 0x10000
	s_add_i32 s67, 0, 0x14000
	s_sext_i32_i8 s54, s4
	s_ashr_i32 s65, s3, 31
	v_mov_b32_e32 v137, v131
	v_lshl_add_u32 v138, v14, 1, v0
	v_mov_b32_e32 v139, v131
	v_mov_b64_e32 v[140:141], 0x200
	v_mov_b64_e32 v[142:143], 0x1ff
	v_add_u32_e32 v149, s66, v147
	v_add_u32_e32 v150, s67, v147
	v_add_u32_e32 v151, 0, v3
	s_mov_b32 s68, 0x40000
	s_mov_b64 s[16:17], 0x48000
	s_mov_b32 s69, 0x48000
	s_mov_b64 s[18:19], 0x50000
	s_mov_b32 s70, 0x50000
	s_mov_b64 s[20:21], 0x58000
	s_mov_b32 s71, 0x58000
	s_barrier
	s_waitcnt vmcnt(0)
	s_branch .LBB0_693

.LBB0_700:
	ds_read_b128 v[152:155], v149
	ds_read_b128 v[156:159], v149 offset:1024
	ds_read_b128 v[160:163], v149 offset:2048
	ds_read_b128 v[164:167], v149 offset:3072
	ds_read_b128 v[168:171], v150
	ds_read_b128 v[172:175], v150 offset:1024
	ds_read_b128 v[176:179], v150 offset:2048
	ds_read_b128 v[180:183], v150 offset:3072
	s_add_u32 s38, s34, 0xfffc0080
	s_addc_u32 s39, s35, -1
	s_cmp_eq_u32 s75, 12
	s_cselect_b32 s41, s25, s39
	s_cselect_b32 s40, s55, s38
	s_cselect_b32 s39, s23, s74
	s_cselect_b32 s38, s72, s73
	s_add_i32 m0, s31, 0xc000
	ds_read_b128 v[184:187], v151
	ds_read_b128 v[192:195], v151 offset:1024
	ds_read_b128 v[196:199], v151 offset:2048
	ds_read_b128 v[200:203], v151 offset:3072
	ds_read_b128 v[204:207], v151 offset:4096
	ds_read_b128 v[208:211], v151 offset:5120
	ds_read_b128 v[212:215], v151 offset:6144
	ds_read_b128 v[216:219], v151 offset:7168
	global_load_lds_dwordx4 v136, s[34:35]
	s_add_i32 m0, s31, 0xe000
	s_nop 0
	global_load_lds_dwordx4 v138, s[34:35]
	s_waitcnt vmcnt(8)
	s_waitcnt lgkmcnt(0)
	s_barrier
	s_setprio 1
	s_waitcnt lgkmcnt(0)
	v_mfma_f32_16x16x32_bf16 v[124:127], v[152:155], v[184:187], v[124:127]
	v_mfma_f32_16x16x32_bf16 v[120:123], v[160:163], v[184:187], v[120:123]
	v_mfma_f32_16x16x32_bf16 v[116:119], v[152:155], v[196:199], v[116:119]
	v_mfma_f32_16x16x32_bf16 v[108:111], v[160:163], v[196:199], v[108:111]
	v_mfma_f32_16x16x32_bf16 v[100:103], v[152:155], v[204:207], v[100:103]
	v_mfma_f32_16x16x32_bf16 v[92:95], v[160:163], v[204:207], v[92:95]
	v_mfma_f32_16x16x32_bf16 v[84:87], v[152:155], v[212:215], v[84:87]
	v_mfma_f32_16x16x32_bf16 v[76:79], v[160:163], v[212:215], v[76:79]
	v_mfma_f32_16x16x32_bf16 v[124:127], v[156:159], v[192:195], v[124:127]
	v_mfma_f32_16x16x32_bf16 v[120:123], v[164:167], v[192:195], v[120:123]
	v_mfma_f32_16x16x32_bf16 v[116:119], v[156:159], v[200:203], v[116:119]
	v_mfma_f32_16x16x32_bf16 v[108:111], v[164:167], v[200:203], v[108:111]
	v_mfma_f32_16x16x32_bf16 v[100:103], v[156:159], v[208:211], v[100:103]
	v_mfma_f32_16x16x32_bf16 v[92:95], v[164:167], v[208:211], v[92:95]
	v_mfma_f32_16x16x32_bf16 v[84:87], v[156:159], v[216:219], v[84:87]
	v_mfma_f32_16x16x32_bf16 v[76:79], v[164:167], v[216:219], v[76:79]
	s_setprio 0
	s_setprio 1
	v_mfma_f32_16x16x32_bf16 v[112:115], v[168:171], v[184:187], v[112:115]
	v_mfma_f32_16x16x32_bf16 v[104:107], v[176:179], v[184:187], v[104:107]
	v_mfma_f32_16x16x32_bf16 v[96:99], v[168:171], v[196:199], v[96:99]
	v_mfma_f32_16x16x32_bf16 v[88:91], v[176:179], v[196:199], v[88:91]
	v_mfma_f32_16x16x32_bf16 v[80:83], v[168:171], v[204:207], v[80:83]
	v_mfma_f32_16x16x32_bf16 v[72:75], v[176:179], v[204:207], v[72:75]
	v_mfma_f32_16x16x32_bf16 v[68:71], v[168:171], v[212:215], v[68:71]
	v_mfma_f32_16x16x32_bf16 v[64:67], v[176:179], v[212:215], v[64:67]
	v_mfma_f32_16x16x32_bf16 v[112:115], v[172:175], v[192:195], v[112:115]
	v_mfma_f32_16x16x32_bf16 v[104:107], v[180:183], v[192:195], v[104:107]
	v_mfma_f32_16x16x32_bf16 v[96:99], v[172:175], v[200:203], v[96:99]
	v_mfma_f32_16x16x32_bf16 v[88:91], v[180:183], v[200:203], v[88:91]
	v_mfma_f32_16x16x32_bf16 v[80:83], v[172:175], v[208:211], v[80:83]
	v_mfma_f32_16x16x32_bf16 v[72:75], v[180:183], v[208:211], v[72:75]
	v_mfma_f32_16x16x32_bf16 v[68:71], v[172:175], v[216:219], v[68:71]
	v_mfma_f32_16x16x32_bf16 v[64:67], v[180:183], v[216:219], v[64:67]
	s_setprio 0
	s_barrier
	s_add_i32 s76, s66, s53
	v_lshl_add_u64 v[144:145], s[38:39], 0, v[130:131]
	s_mov_b32 m0, s76
	ds_read_b128 v[184:187], v151 offset:16384
	ds_read_b128 v[192:195], v151 offset:17408
	ds_read_b128 v[196:199], v151 offset:18432
	ds_read_b128 v[200:203], v151 offset:19456
	ds_read_b128 v[204:207], v151 offset:20480
	ds_read_b128 v[208:211], v151 offset:21504
	ds_read_b128 v[212:215], v151 offset:22528
	ds_read_b128 v[216:219], v151 offset:23552
	global_load_lds_dwordx4 v[144:145], off
	s_add_i32 m0, s76, 0x2000
	s_add_u32 s76, s38, 0x40000
	v_lshl_add_u64 v[188:189], s[38:39], 0, v[134:135]
	s_addc_u32 s77, s39, 0
	s_add_i32 s79, s67, s53
	global_load_lds_dwordx4 v[188:189], off
	s_mov_b32 m0, s79
	v_lshl_add_u64 v[222:223], s[40:41], 0, v[132:133]
	global_load_lds_dwordx4 v130, s[76:77]
	s_add_i32 m0, s79, 0x2000
	s_nop 0
	global_load_lds_dwordx4 v134, s[76:77]
	v_lshl_add_u64 v[220:221], s[40:41], 0, v[128:129]
	s_mov_b32 m0, s31
	s_nop 0
	global_load_lds_dwordx4 v[220:221], off
	s_mov_b32 m0, s33
	s_nop 0
	global_load_lds_dwordx4 v[222:223], off
	s_waitcnt vmcnt(8)
	s_waitcnt lgkmcnt(0)
	s_barrier
	s_setprio 1
	s_waitcnt lgkmcnt(0)
	v_mfma_f32_16x16x32_bf16 v[60:63], v[152:155], v[184:187], v[60:63]
	v_mfma_f32_16x16x32_bf16 v[56:59], v[160:163], v[184:187], v[56:59]
	v_mfma_f32_16x16x32_bf16 v[52:55], v[152:155], v[196:199], v[52:55]
	v_mfma_f32_16x16x32_bf16 v[44:47], v[160:163], v[196:199], v[44:47]
	v_mfma_f32_16x16x32_bf16 v[36:39], v[152:155], v[204:207], v[36:39]
	v_mfma_f32_16x16x32_bf16 v[28:31], v[160:163], v[204:207], v[28:31]
	v_mfma_f32_16x16x32_bf16 v[20:23], v[152:155], v[212:215], v[20:23]
	v_mfma_f32_16x16x32_bf16 v[12:15], v[160:163], v[212:215], v[12:15]
	v_mfma_f32_16x16x32_bf16 v[60:63], v[156:159], v[192:195], v[60:63]
	v_mfma_f32_16x16x32_bf16 v[56:59], v[164:167], v[192:195], v[56:59]
	v_mfma_f32_16x16x32_bf16 v[52:55], v[156:159], v[200:203], v[52:55]
	v_mfma_f32_16x16x32_bf16 v[44:47], v[164:167], v[200:203], v[44:47]
	v_mfma_f32_16x16x32_bf16 v[36:39], v[156:159], v[208:211], v[36:39]
	v_mfma_f32_16x16x32_bf16 v[28:31], v[164:167], v[208:211], v[28:31]
	v_mfma_f32_16x16x32_bf16 v[20:23], v[156:159], v[216:219], v[20:23]
	v_mfma_f32_16x16x32_bf16 v[12:15], v[164:167], v[216:219], v[12:15]
	s_setprio 0
	s_setprio 1
	v_mfma_f32_16x16x32_bf16 v[48:51], v[168:171], v[184:187], v[48:51]
	v_mfma_f32_16x16x32_bf16 v[40:43], v[176:179], v[184:187], v[40:43]
	v_mfma_f32_16x16x32_bf16 v[32:35], v[168:171], v[196:199], v[32:35]
	v_mfma_f32_16x16x32_bf16 v[24:27], v[176:179], v[196:199], v[24:27]
	v_mfma_f32_16x16x32_bf16 v[16:19], v[168:171], v[204:207], v[16:19]
	v_mfma_f32_16x16x32_bf16 v[8:11], v[176:179], v[204:207], v[8:11]
	v_mfma_f32_16x16x32_bf16 v[4:7], v[168:171], v[212:215], v[4:7]
	v_mfma_f32_16x16x32_bf16 v[0:3], v[176:179], v[212:215], v[0:3]
	v_mfma_f32_16x16x32_bf16 v[48:51], v[172:175], v[192:195], v[48:51]
	v_mfma_f32_16x16x32_bf16 v[40:43], v[180:183], v[192:195], v[40:43]
	v_mfma_f32_16x16x32_bf16 v[32:35], v[172:175], v[200:203], v[32:35]
	v_mfma_f32_16x16x32_bf16 v[24:27], v[180:183], v[200:203], v[24:27]
	v_mfma_f32_16x16x32_bf16 v[16:19], v[172:175], v[208:211], v[16:19]
	v_mfma_f32_16x16x32_bf16 v[8:11], v[180:183], v[208:211], v[8:11]
	v_mfma_f32_16x16x32_bf16 v[4:7], v[172:175], v[216:219], v[4:7]
	v_mfma_f32_16x16x32_bf16 v[0:3], v[180:183], v[216:219], v[0:3]
	s_setprio 0
	s_barrier
	s_add_i32 s76, 0, 0x18000
	s_add_i32 s77, 0, 0x1c000
	v_add_u32_e32 v164, s76, v147
	v_add_u32_e32 v180, s77, v147
	ds_read_b128 v[152:155], v164
	ds_read_b128 v[156:159], v164 offset:1024
	ds_read_b128 v[160:163], v164 offset:2048
	ds_read_b128 v[164:167], v164 offset:3072
	ds_read_b128 v[168:171], v180
	ds_read_b128 v[172:175], v180 offset:1024
	ds_read_b128 v[176:179], v180 offset:2048
	ds_read_b128 v[180:183], v180 offset:3072
	s_add_u32 s40, s40, 0x40000
	s_addc_u32 s41, s41, 0
	s_mov_b32 m0, s60
	ds_read_b128 v[184:187], v151 offset:32768
	ds_read_b128 v[192:195], v151 offset:33792
	ds_read_b128 v[196:199], v151 offset:34816
	ds_read_b128 v[200:203], v151 offset:35840
	ds_read_b128 v[204:207], v151 offset:36864
	ds_read_b128 v[208:211], v151 offset:37888
	ds_read_b128 v[212:215], v151 offset:38912
	ds_read_b128 v[216:219], v151 offset:39936
	global_load_lds_dwordx4 v128, s[40:41]
	s_mov_b32 m0, s61
	s_nop 0
	global_load_lds_dwordx4 v132, s[40:41]
	s_waitcnt vmcnt(8)
	s_waitcnt lgkmcnt(0)
	s_barrier
	s_setprio 1
	s_waitcnt lgkmcnt(0)
	v_mfma_f32_16x16x32_bf16 v[124:127], v[152:155], v[184:187], v[124:127]
	v_mfma_f32_16x16x32_bf16 v[120:123], v[160:163], v[184:187], v[120:123]
	v_mfma_f32_16x16x32_bf16 v[116:119], v[152:155], v[196:199], v[116:119]
	v_mfma_f32_16x16x32_bf16 v[108:111], v[160:163], v[196:199], v[108:111]
	v_mfma_f32_16x16x32_bf16 v[100:103], v[152:155], v[204:207], v[100:103]
	v_mfma_f32_16x16x32_bf16 v[92:95], v[160:163], v[204:207], v[92:95]
	v_mfma_f32_16x16x32_bf16 v[84:87], v[152:155], v[212:215], v[84:87]
	v_mfma_f32_16x16x32_bf16 v[76:79], v[160:163], v[212:215], v[76:79]
	v_mfma_f32_16x16x32_bf16 v[124:127], v[156:159], v[192:195], v[124:127]
	v_mfma_f32_16x16x32_bf16 v[120:123], v[164:167], v[192:195], v[120:123]
	v_mfma_f32_16x16x32_bf16 v[116:119], v[156:159], v[200:203], v[116:119]
	v_mfma_f32_16x16x32_bf16 v[108:111], v[164:167], v[200:203], v[108:111]
	v_mfma_f32_16x16x32_bf16 v[100:103], v[156:159], v[208:211], v[100:103]
	v_mfma_f32_16x16x32_bf16 v[92:95], v[164:167], v[208:211], v[92:95]
	v_mfma_f32_16x16x32_bf16 v[84:87], v[156:159], v[216:219], v[84:87]
	v_mfma_f32_16x16x32_bf16 v[76:79], v[164:167], v[216:219], v[76:79]
	s_setprio 0
	s_setprio 1
	v_mfma_f32_16x16x32_bf16 v[112:115], v[168:171], v[184:187], v[112:115]
	v_mfma_f32_16x16x32_bf16 v[104:107], v[176:179], v[184:187], v[104:107]
	v_mfma_f32_16x16x32_bf16 v[96:99], v[168:171], v[196:199], v[96:99]
	v_mfma_f32_16x16x32_bf16 v[88:91], v[176:179], v[196:199], v[88:91]
	v_mfma_f32_16x16x32_bf16 v[80:83], v[168:171], v[204:207], v[80:83]
	v_mfma_f32_16x16x32_bf16 v[72:75], v[176:179], v[204:207], v[72:75]
	v_mfma_f32_16x16x32_bf16 v[68:71], v[168:171], v[212:215], v[68:71]
	v_mfma_f32_16x16x32_bf16 v[64:67], v[176:179], v[212:215], v[64:67]
	v_mfma_f32_16x16x32_bf16 v[112:115], v[172:175], v[192:195], v[112:115]
	v_mfma_f32_16x16x32_bf16 v[104:107], v[180:183], v[192:195], v[104:107]
	v_mfma_f32_16x16x32_bf16 v[96:99], v[172:175], v[200:203], v[96:99]
	v_mfma_f32_16x16x32_bf16 v[88:91], v[180:183], v[200:203], v[88:91]
	v_mfma_f32_16x16x32_bf16 v[80:83], v[172:175], v[208:211], v[80:83]
	v_mfma_f32_16x16x32_bf16 v[72:75], v[180:183], v[208:211], v[72:75]
	v_mfma_f32_16x16x32_bf16 v[68:71], v[172:175], v[216:219], v[68:71]
	v_mfma_f32_16x16x32_bf16 v[64:67], v[180:183], v[216:219], v[64:67]
	s_setprio 0
	s_barrier
	s_add_i32 s40, s76, s53
	v_lshl_add_u64 v[144:145], v[144:145], 0, s[12:13]
	s_mov_b32 m0, s40
	ds_read_b128 v[184:187], v151 offset:49152
	ds_read_b128 v[192:195], v151 offset:50176
	ds_read_b128 v[196:199], v151 offset:51200
	ds_read_b128 v[200:203], v151 offset:52224
	ds_read_b128 v[204:207], v151 offset:53248
	ds_read_b128 v[208:211], v151 offset:54272
	ds_read_b128 v[212:215], v151 offset:55296
	ds_read_b128 v[216:219], v151 offset:56320
	global_load_lds_dwordx4 v[144:145], off
	s_add_i32 m0, s40, 0x2000
	s_add_u32 s38, s38, 0x40080
	v_lshl_add_u64 v[144:145], v[188:189], 0, s[12:13]
	s_addc_u32 s39, s39, 0
	s_add_i32 s40, s77, s53
	global_load_lds_dwordx4 v[144:145], off
	s_mov_b32 m0, s40
	s_nop 0
	global_load_lds_dwordx4 v130, s[38:39]
	s_add_i32 m0, s40, 0x2000
	s_nop 0
	global_load_lds_dwordx4 v134, s[38:39]
	v_lshl_add_u64 v[144:145], v[220:221], 0, s[12:13]
	s_mov_b32 m0, s63
	s_nop 0
	global_load_lds_dwordx4 v[144:145], off
	v_lshl_add_u64 v[144:145], v[222:223], 0, s[12:13]
	s_mov_b32 m0, s64
	s_nop 0
	global_load_lds_dwordx4 v[144:145], off
	s_waitcnt vmcnt(8)
	s_waitcnt lgkmcnt(0)
	s_barrier
	s_setprio 1
	s_waitcnt lgkmcnt(0)
	v_mfma_f32_16x16x32_bf16 v[60:63], v[152:155], v[184:187], v[60:63]
	v_mfma_f32_16x16x32_bf16 v[56:59], v[160:163], v[184:187], v[56:59]
	v_mfma_f32_16x16x32_bf16 v[52:55], v[152:155], v[196:199], v[52:55]
	v_mfma_f32_16x16x32_bf16 v[44:47], v[160:163], v[196:199], v[44:47]
	v_mfma_f32_16x16x32_bf16 v[36:39], v[152:155], v[204:207], v[36:39]
	v_mfma_f32_16x16x32_bf16 v[28:31], v[160:163], v[204:207], v[28:31]
	v_mfma_f32_16x16x32_bf16 v[20:23], v[152:155], v[212:215], v[20:23]
	v_mfma_f32_16x16x32_bf16 v[12:15], v[160:163], v[212:215], v[12:15]
	v_mfma_f32_16x16x32_bf16 v[60:63], v[156:159], v[192:195], v[60:63]
	v_mfma_f32_16x16x32_bf16 v[56:59], v[164:167], v[192:195], v[56:59]
	v_mfma_f32_16x16x32_bf16 v[52:55], v[156:159], v[200:203], v[52:55]
	v_mfma_f32_16x16x32_bf16 v[44:47], v[164:167], v[200:203], v[44:47]
	v_mfma_f32_16x16x32_bf16 v[36:39], v[156:159], v[208:211], v[36:39]
	v_mfma_f32_16x16x32_bf16 v[28:31], v[164:167], v[208:211], v[28:31]
	v_mfma_f32_16x16x32_bf16 v[20:23], v[156:159], v[216:219], v[20:23]
	v_mfma_f32_16x16x32_bf16 v[12:15], v[164:167], v[216:219], v[12:15]
	s_setprio 0
	s_setprio 1
	v_mfma_f32_16x16x32_bf16 v[48:51], v[168:171], v[184:187], v[48:51]
	v_mfma_f32_16x16x32_bf16 v[40:43], v[176:179], v[184:187], v[40:43]
	v_mfma_f32_16x16x32_bf16 v[32:35], v[168:171], v[196:199], v[32:35]
	v_mfma_f32_16x16x32_bf16 v[24:27], v[176:179], v[196:199], v[24:27]
	v_mfma_f32_16x16x32_bf16 v[16:19], v[168:171], v[204:207], v[16:19]
	v_mfma_f32_16x16x32_bf16 v[8:11], v[176:179], v[204:207], v[8:11]
	v_mfma_f32_16x16x32_bf16 v[4:7], v[168:171], v[212:215], v[4:7]
	v_mfma_f32_16x16x32_bf16 v[0:3], v[176:179], v[212:215], v[0:3]
	v_mfma_f32_16x16x32_bf16 v[48:51], v[172:175], v[192:195], v[48:51]
	v_mfma_f32_16x16x32_bf16 v[40:43], v[180:183], v[192:195], v[40:43]
	v_mfma_f32_16x16x32_bf16 v[32:35], v[172:175], v[200:203], v[32:35]
	v_mfma_f32_16x16x32_bf16 v[24:27], v[180:183], v[200:203], v[24:27]
	v_mfma_f32_16x16x32_bf16 v[16:19], v[172:175], v[208:211], v[16:19]
	v_mfma_f32_16x16x32_bf16 v[8:11], v[180:183], v[208:211], v[8:11]
	v_mfma_f32_16x16x32_bf16 v[4:7], v[172:175], v[216:219], v[4:7]
	v_mfma_f32_16x16x32_bf16 v[0:3], v[180:183], v[216:219], v[0:3]
	s_setprio 0
	s_barrier
	s_add_i32 s75, s75, 2
	s_add_u32 s34, s34, 0x100
	s_addc_u32 s35, s35, 0
	s_add_u32 s73, s73, 0x100
	s_addc_u32 s74, s74, 0
	s_cmp_gt_u32 s75, 13
	s_cbranch_scc0 .LBB0_700
	s_and_b64 vcc, exec, s[14:15]
	s_cbranch_vccz .LBB0_703
	s_barrier

.LBB0_827:
	s_lshl_b32 s10, s10, 5
	s_and_b32 s16, s10, 0x60
	s_mov_b64 s[10:11], 0x80
	s_add_i32 m0, s31, 0x18000
	v_lshl_add_u64 v[6:7], v[6:7], 0, s[10:11]
	s_lshl_b32 s13, s5, 13
	s_lshl_b32 s17, s16, 7
	s_waitcnt vmcnt(2)
	s_barrier
	global_load_lds_dwordx4 v[6:7], off
	v_lshl_add_u64 v[4:5], v[4:5], 0, s[10:11]
	s_add_i32 m0, s31, 0x1a000
	s_add_i32 s52, s31, 0x8000
	s_add_i32 s53, s31, 0xa000
	global_load_lds_dwordx4 v[4:5], off
	v_lshl_add_u64 v[0:1], v[0:1], 0, s[10:11]
	s_mov_b32 m0, s52
	s_add_u32 s14, s40, 0x40080
	global_load_lds_dwordx4 v[0:1], off
	v_lshl_add_u64 v[0:1], v[2:3], 0, s[10:11]
	s_mov_b32 m0, s53
	s_addc_u32 s15, s41, 0
	global_load_lds_dwordx4 v[0:1], off
	s_add_i32 m0, s31, 0x1c000
	s_nop 0
	global_load_lds_dwordx4 v130, s[14:15]
	s_add_i32 m0, s31, 0x1e000
	s_cmpk_lt_u32 s12, 0x100
	global_load_lds_dwordx4 v134, s[14:15]
	v_lshrrev_b32_e32 v1, 1, v8
	v_and_b32_e32 v1, 24, v1
	v_and_b32_e32 v0, 15, v8
	v_lshlrev_b32_e32 v2, 1, v1
	v_lshl_or_b32 v146, s5, 6, v0
	v_lshl_or_b32 v0, v0, 6, v2
	v_lshlrev_b32_e32 v2, 2, v8
	v_and_b32_e32 v2, 32, v2
	v_bitop3_b32 v3, v0, s13, v2 bitop3:0xde
	v_bitop3_b32 v147, v0, s17, v2 bitop3:0xde
	v_lshlrev_b32_e32 v0, 14, v9
	v_and_b32_e32 v0, 0xffff8000, v0
	v_or_b32_e32 v148, s16, v1
	v_lshl_add_u32 v0, v10, 11, v0
	v_and_b32_e32 v1, 1, v9
	v_lshl_or_b32 v0, v1, 6, v0
	v_lshl_add_u32 v136, v11, 1, v0
	v_lshlrev_b32_e32 v0, 14, v12
	v_and_b32_e32 v0, 0xffff8000, v0
	s_waitcnt vmcnt(6)
	v_lshl_add_u32 v0, v13, 11, v0
	v_and_b32_e32 v1, 1, v12
	s_cselect_b64 s[12:13], -1, 0
	v_lshl_or_b32 v0, v1, 6, v0
	s_add_i32 s69, 0, 0x10000
	s_add_i32 s70, 0, 0x14000
	s_sext_i32_i8 s33, s4
	s_ashr_i32 s68, s3, 31
	v_mov_b32_e32 v137, v131
	v_lshl_add_u32 v138, v14, 1, v0
	v_mov_b32_e32 v139, v131
	v_mov_b64_e32 v[140:141], 0x800
	v_mov_b64_e32 v[142:143], 0x7ff
	v_add_u32_e32 v149, s69, v147
	v_add_u32_e32 v150, s70, v147
	v_add_u32_e32 v151, 0, v3
	s_mov_b64 s[14:15], 0x100000
	s_mov_b32 s71, 0x100000
	s_mov_b64 s[16:17], 0x120000
	s_mov_b32 s72, 0x120000
	s_mov_b64 s[18:19], 0x140000
	s_mov_b32 s73, 0x140000
	s_mov_b64 s[20:21], 0x160000
	s_mov_b32 s74, 0x160000
	s_barrier
	s_branch .LBB0_830

.LBB0_837:
	ds_read_b128 v[152:155], v149
	ds_read_b128 v[156:159], v149 offset:1024
	ds_read_b128 v[160:163], v149 offset:2048
	ds_read_b128 v[164:167], v149 offset:3072
	ds_read_b128 v[168:171], v150
	ds_read_b128 v[172:175], v150 offset:1024
	ds_read_b128 v[176:179], v150 offset:2048
	ds_read_b128 v[180:183], v150 offset:3072
	s_add_u32 s40, s34, 0xfffc0080
	s_addc_u32 s41, s35, -1
	s_cmp_eq_u32 s77, 12
	s_cselect_b32 s43, s25, s41
	s_cselect_b32 s42, s54, s40
	s_cselect_b32 s41, s23, s76
	s_cselect_b32 s40, s55, s75
	s_add_i32 m0, s31, 0xc000
	ds_read_b128 v[184:187], v151
	ds_read_b128 v[192:195], v151 offset:1024
	ds_read_b128 v[196:199], v151 offset:2048
	ds_read_b128 v[200:203], v151 offset:3072
	ds_read_b128 v[204:207], v151 offset:4096
	ds_read_b128 v[208:211], v151 offset:5120
	ds_read_b128 v[212:215], v151 offset:6144
	ds_read_b128 v[216:219], v151 offset:7168
	global_load_lds_dwordx4 v136, s[34:35]
	s_add_i32 m0, s31, 0xe000
	s_nop 0
	global_load_lds_dwordx4 v138, s[34:35]
	s_waitcnt vmcnt(8)
	s_waitcnt lgkmcnt(0)
	s_barrier
	s_setprio 1
	s_waitcnt lgkmcnt(0)
	v_mfma_f32_16x16x32_bf16 v[124:127], v[152:155], v[184:187], v[124:127]
	v_mfma_f32_16x16x32_bf16 v[120:123], v[160:163], v[184:187], v[120:123]
	v_mfma_f32_16x16x32_bf16 v[108:111], v[152:155], v[196:199], v[108:111]
	v_mfma_f32_16x16x32_bf16 v[104:107], v[160:163], v[196:199], v[104:107]
	v_mfma_f32_16x16x32_bf16 v[92:95], v[152:155], v[204:207], v[92:95]
	v_mfma_f32_16x16x32_bf16 v[88:91], v[160:163], v[204:207], v[88:91]
	v_mfma_f32_16x16x32_bf16 v[76:79], v[152:155], v[212:215], v[76:79]
	v_mfma_f32_16x16x32_bf16 v[72:75], v[160:163], v[212:215], v[72:75]
	v_mfma_f32_16x16x32_bf16 v[124:127], v[156:159], v[192:195], v[124:127]
	v_mfma_f32_16x16x32_bf16 v[120:123], v[164:167], v[192:195], v[120:123]
	v_mfma_f32_16x16x32_bf16 v[108:111], v[156:159], v[200:203], v[108:111]
	v_mfma_f32_16x16x32_bf16 v[104:107], v[164:167], v[200:203], v[104:107]
	v_mfma_f32_16x16x32_bf16 v[92:95], v[156:159], v[208:211], v[92:95]
	v_mfma_f32_16x16x32_bf16 v[88:91], v[164:167], v[208:211], v[88:91]
	v_mfma_f32_16x16x32_bf16 v[76:79], v[156:159], v[216:219], v[76:79]
	v_mfma_f32_16x16x32_bf16 v[72:75], v[164:167], v[216:219], v[72:75]
	s_setprio 0
	s_setprio 1
	v_mfma_f32_16x16x32_bf16 v[116:119], v[168:171], v[184:187], v[116:119]
	v_mfma_f32_16x16x32_bf16 v[112:115], v[176:179], v[184:187], v[112:115]
	v_mfma_f32_16x16x32_bf16 v[100:103], v[168:171], v[196:199], v[100:103]
	v_mfma_f32_16x16x32_bf16 v[96:99], v[176:179], v[196:199], v[96:99]
	v_mfma_f32_16x16x32_bf16 v[84:87], v[168:171], v[204:207], v[84:87]
	v_mfma_f32_16x16x32_bf16 v[80:83], v[176:179], v[204:207], v[80:83]
	v_mfma_f32_16x16x32_bf16 v[68:71], v[168:171], v[212:215], v[68:71]
	v_mfma_f32_16x16x32_bf16 v[64:67], v[176:179], v[212:215], v[64:67]
	v_mfma_f32_16x16x32_bf16 v[116:119], v[172:175], v[192:195], v[116:119]
	v_mfma_f32_16x16x32_bf16 v[112:115], v[180:183], v[192:195], v[112:115]
	v_mfma_f32_16x16x32_bf16 v[100:103], v[172:175], v[200:203], v[100:103]
	v_mfma_f32_16x16x32_bf16 v[96:99], v[180:183], v[200:203], v[96:99]
	v_mfma_f32_16x16x32_bf16 v[84:87], v[172:175], v[208:211], v[84:87]
	v_mfma_f32_16x16x32_bf16 v[80:83], v[180:183], v[208:211], v[80:83]
	v_mfma_f32_16x16x32_bf16 v[68:71], v[172:175], v[216:219], v[68:71]
	v_mfma_f32_16x16x32_bf16 v[64:67], v[180:183], v[216:219], v[64:67]
	s_setprio 0
	s_barrier
	s_add_i32 s79, s69, s63
	v_lshl_add_u64 v[144:145], s[40:41], 0, v[130:131]
	s_mov_b32 m0, s79
	ds_read_b128 v[184:187], v151 offset:16384
	ds_read_b128 v[192:195], v151 offset:17408
	ds_read_b128 v[196:199], v151 offset:18432
	ds_read_b128 v[200:203], v151 offset:19456
	ds_read_b128 v[204:207], v151 offset:20480
	ds_read_b128 v[208:211], v151 offset:21504
	ds_read_b128 v[212:215], v151 offset:22528
	ds_read_b128 v[216:219], v151 offset:23552
	global_load_lds_dwordx4 v[144:145], off
	s_add_i32 m0, s79, 0x2000
	s_add_u32 s80, s40, 0x40000
	v_lshl_add_u64 v[188:189], s[40:41], 0, v[134:135]
	s_addc_u32 s81, s41, 0
	s_add_i32 s79, s70, s63
	global_load_lds_dwordx4 v[188:189], off
	s_mov_b32 m0, s79
	v_lshl_add_u64 v[222:223], s[42:43], 0, v[132:133]
	global_load_lds_dwordx4 v130, s[80:81]
	s_add_i32 m0, s79, 0x2000
	s_nop 0
	global_load_lds_dwordx4 v134, s[80:81]
	v_lshl_add_u64 v[220:221], s[42:43], 0, v[128:129]
	s_mov_b32 m0, s31
	s_nop 0
	global_load_lds_dwordx4 v[220:221], off
	s_mov_b32 m0, s64
	s_nop 0
	global_load_lds_dwordx4 v[222:223], off
	s_waitcnt vmcnt(8)
	s_waitcnt lgkmcnt(0)
	s_barrier
	s_setprio 1
	s_waitcnt lgkmcnt(0)
	v_mfma_f32_16x16x32_bf16 v[60:63], v[152:155], v[184:187], v[60:63]
	v_mfma_f32_16x16x32_bf16 v[56:59], v[160:163], v[184:187], v[56:59]
	v_mfma_f32_16x16x32_bf16 v[44:47], v[152:155], v[196:199], v[44:47]
	v_mfma_f32_16x16x32_bf16 v[40:43], v[160:163], v[196:199], v[40:43]
	v_mfma_f32_16x16x32_bf16 v[28:31], v[152:155], v[204:207], v[28:31]
	v_mfma_f32_16x16x32_bf16 v[24:27], v[160:163], v[204:207], v[24:27]
	v_mfma_f32_16x16x32_bf16 v[12:15], v[152:155], v[212:215], v[12:15]
	v_mfma_f32_16x16x32_bf16 v[8:11], v[160:163], v[212:215], v[8:11]
	v_mfma_f32_16x16x32_bf16 v[60:63], v[156:159], v[192:195], v[60:63]
	v_mfma_f32_16x16x32_bf16 v[56:59], v[164:167], v[192:195], v[56:59]
	v_mfma_f32_16x16x32_bf16 v[44:47], v[156:159], v[200:203], v[44:47]
	v_mfma_f32_16x16x32_bf16 v[40:43], v[164:167], v[200:203], v[40:43]
	v_mfma_f32_16x16x32_bf16 v[28:31], v[156:159], v[208:211], v[28:31]
	v_mfma_f32_16x16x32_bf16 v[24:27], v[164:167], v[208:211], v[24:27]
	v_mfma_f32_16x16x32_bf16 v[12:15], v[156:159], v[216:219], v[12:15]
	v_mfma_f32_16x16x32_bf16 v[8:11], v[164:167], v[216:219], v[8:11]
	s_setprio 0
	s_setprio 1
	v_mfma_f32_16x16x32_bf16 v[52:55], v[168:171], v[184:187], v[52:55]
	v_mfma_f32_16x16x32_bf16 v[48:51], v[176:179], v[184:187], v[48:51]
	v_mfma_f32_16x16x32_bf16 v[36:39], v[168:171], v[196:199], v[36:39]
	v_mfma_f32_16x16x32_bf16 v[32:35], v[176:179], v[196:199], v[32:35]
	v_mfma_f32_16x16x32_bf16 v[20:23], v[168:171], v[204:207], v[20:23]
	v_mfma_f32_16x16x32_bf16 v[16:19], v[176:179], v[204:207], v[16:19]
	v_mfma_f32_16x16x32_bf16 v[4:7], v[168:171], v[212:215], v[4:7]
	v_mfma_f32_16x16x32_bf16 v[0:3], v[176:179], v[212:215], v[0:3]
	v_mfma_f32_16x16x32_bf16 v[52:55], v[172:175], v[192:195], v[52:55]
	v_mfma_f32_16x16x32_bf16 v[48:51], v[180:183], v[192:195], v[48:51]
	v_mfma_f32_16x16x32_bf16 v[36:39], v[172:175], v[200:203], v[36:39]
	v_mfma_f32_16x16x32_bf16 v[32:35], v[180:183], v[200:203], v[32:35]
	v_mfma_f32_16x16x32_bf16 v[20:23], v[172:175], v[208:211], v[20:23]
	v_mfma_f32_16x16x32_bf16 v[16:19], v[180:183], v[208:211], v[16:19]
	v_mfma_f32_16x16x32_bf16 v[4:7], v[172:175], v[216:219], v[4:7]
	v_mfma_f32_16x16x32_bf16 v[0:3], v[180:183], v[216:219], v[0:3]
	s_setprio 0
	s_barrier
	s_add_i32 s79, 0, 0x18000
	s_add_i32 s80, 0, 0x1c000
	v_add_u32_e32 v164, s79, v147
	v_add_u32_e32 v180, s80, v147
	ds_read_b128 v[152:155], v164
	ds_read_b128 v[156:159], v164 offset:1024
	ds_read_b128 v[160:163], v164 offset:2048
	ds_read_b128 v[164:167], v164 offset:3072
	ds_read_b128 v[168:171], v180
	ds_read_b128 v[172:175], v180 offset:1024
	ds_read_b128 v[176:179], v180 offset:2048
	ds_read_b128 v[180:183], v180 offset:3072
	s_add_u32 s42, s42, 0x40000
	s_addc_u32 s43, s43, 0
	s_mov_b32 m0, s65
	ds_read_b128 v[184:187], v151 offset:32768
	ds_read_b128 v[192:195], v151 offset:33792
	ds_read_b128 v[196:199], v151 offset:34816
	ds_read_b128 v[200:203], v151 offset:35840
	ds_read_b128 v[204:207], v151 offset:36864
	ds_read_b128 v[208:211], v151 offset:37888
	ds_read_b128 v[212:215], v151 offset:38912
	ds_read_b128 v[216:219], v151 offset:39936
	global_load_lds_dwordx4 v128, s[42:43]
	s_mov_b32 m0, s66
	s_nop 0
	global_load_lds_dwordx4 v132, s[42:43]
	s_waitcnt vmcnt(8)
	s_waitcnt lgkmcnt(0)
	s_barrier
	s_setprio 1
	s_waitcnt lgkmcnt(0)
	v_mfma_f32_16x16x32_bf16 v[124:127], v[152:155], v[184:187], v[124:127]
	v_mfma_f32_16x16x32_bf16 v[120:123], v[160:163], v[184:187], v[120:123]
	v_mfma_f32_16x16x32_bf16 v[108:111], v[152:155], v[196:199], v[108:111]
	v_mfma_f32_16x16x32_bf16 v[104:107], v[160:163], v[196:199], v[104:107]
	v_mfma_f32_16x16x32_bf16 v[92:95], v[152:155], v[204:207], v[92:95]
	v_mfma_f32_16x16x32_bf16 v[88:91], v[160:163], v[204:207], v[88:91]
	v_mfma_f32_16x16x32_bf16 v[76:79], v[152:155], v[212:215], v[76:79]
	v_mfma_f32_16x16x32_bf16 v[72:75], v[160:163], v[212:215], v[72:75]
	v_mfma_f32_16x16x32_bf16 v[124:127], v[156:159], v[192:195], v[124:127]
	v_mfma_f32_16x16x32_bf16 v[120:123], v[164:167], v[192:195], v[120:123]
	v_mfma_f32_16x16x32_bf16 v[108:111], v[156:159], v[200:203], v[108:111]
	v_mfma_f32_16x16x32_bf16 v[104:107], v[164:167], v[200:203], v[104:107]
	v_mfma_f32_16x16x32_bf16 v[92:95], v[156:159], v[208:211], v[92:95]
	v_mfma_f32_16x16x32_bf16 v[88:91], v[164:167], v[208:211], v[88:91]
	v_mfma_f32_16x16x32_bf16 v[76:79], v[156:159], v[216:219], v[76:79]
	v_mfma_f32_16x16x32_bf16 v[72:75], v[164:167], v[216:219], v[72:75]
	s_setprio 0
	s_setprio 1
	v_mfma_f32_16x16x32_bf16 v[116:119], v[168:171], v[184:187], v[116:119]
	v_mfma_f32_16x16x32_bf16 v[112:115], v[176:179], v[184:187], v[112:115]
	v_mfma_f32_16x16x32_bf16 v[100:103], v[168:171], v[196:199], v[100:103]
	v_mfma_f32_16x16x32_bf16 v[96:99], v[176:179], v[196:199], v[96:99]
	v_mfma_f32_16x16x32_bf16 v[84:87], v[168:171], v[204:207], v[84:87]
	v_mfma_f32_16x16x32_bf16 v[80:83], v[176:179], v[204:207], v[80:83]
	v_mfma_f32_16x16x32_bf16 v[68:71], v[168:171], v[212:215], v[68:71]
	v_mfma_f32_16x16x32_bf16 v[64:67], v[176:179], v[212:215], v[64:67]
	v_mfma_f32_16x16x32_bf16 v[116:119], v[172:175], v[192:195], v[116:119]
	v_mfma_f32_16x16x32_bf16 v[112:115], v[180:183], v[192:195], v[112:115]
	v_mfma_f32_16x16x32_bf16 v[100:103], v[172:175], v[200:203], v[100:103]
	v_mfma_f32_16x16x32_bf16 v[96:99], v[180:183], v[200:203], v[96:99]
	v_mfma_f32_16x16x32_bf16 v[84:87], v[172:175], v[208:211], v[84:87]
	v_mfma_f32_16x16x32_bf16 v[80:83], v[180:183], v[208:211], v[80:83]
	v_mfma_f32_16x16x32_bf16 v[68:71], v[172:175], v[216:219], v[68:71]
	v_mfma_f32_16x16x32_bf16 v[64:67], v[180:183], v[216:219], v[64:67]
	s_setprio 0
	s_barrier
	s_add_i32 s42, s79, s63
	v_lshl_add_u64 v[144:145], v[144:145], 0, s[10:11]
	s_mov_b32 m0, s42
	ds_read_b128 v[184:187], v151 offset:49152
	ds_read_b128 v[192:195], v151 offset:50176
	ds_read_b128 v[196:199], v151 offset:51200
	ds_read_b128 v[200:203], v151 offset:52224
	ds_read_b128 v[204:207], v151 offset:53248
	ds_read_b128 v[208:211], v151 offset:54272
	ds_read_b128 v[212:215], v151 offset:55296
	ds_read_b128 v[216:219], v151 offset:56320
	global_load_lds_dwordx4 v[144:145], off
	s_add_i32 m0, s42, 0x2000
	s_add_u32 s40, s40, 0x40080
	v_lshl_add_u64 v[144:145], v[188:189], 0, s[10:11]
	s_addc_u32 s41, s41, 0
	s_add_i32 s42, s80, s63
	global_load_lds_dwordx4 v[144:145], off
	s_mov_b32 m0, s42
	s_nop 0
	global_load_lds_dwordx4 v130, s[40:41]
	s_add_i32 m0, s42, 0x2000
	s_nop 0
	global_load_lds_dwordx4 v134, s[40:41]
	v_lshl_add_u64 v[144:145], v[220:221], 0, s[10:11]
	s_mov_b32 m0, s52
	s_nop 0
	global_load_lds_dwordx4 v[144:145], off
	v_lshl_add_u64 v[144:145], v[222:223], 0, s[10:11]
	s_mov_b32 m0, s53
	s_nop 0
	global_load_lds_dwordx4 v[144:145], off
	s_waitcnt vmcnt(8)
	s_waitcnt lgkmcnt(0)
	s_barrier
	s_setprio 1
	s_waitcnt lgkmcnt(0)
	v_mfma_f32_16x16x32_bf16 v[60:63], v[152:155], v[184:187], v[60:63]
	v_mfma_f32_16x16x32_bf16 v[56:59], v[160:163], v[184:187], v[56:59]
	v_mfma_f32_16x16x32_bf16 v[44:47], v[152:155], v[196:199], v[44:47]
	v_mfma_f32_16x16x32_bf16 v[40:43], v[160:163], v[196:199], v[40:43]
	v_mfma_f32_16x16x32_bf16 v[28:31], v[152:155], v[204:207], v[28:31]
	v_mfma_f32_16x16x32_bf16 v[24:27], v[160:163], v[204:207], v[24:27]
	v_mfma_f32_16x16x32_bf16 v[12:15], v[152:155], v[212:215], v[12:15]
	v_mfma_f32_16x16x32_bf16 v[8:11], v[160:163], v[212:215], v[8:11]
	v_mfma_f32_16x16x32_bf16 v[60:63], v[156:159], v[192:195], v[60:63]
	v_mfma_f32_16x16x32_bf16 v[56:59], v[164:167], v[192:195], v[56:59]
	v_mfma_f32_16x16x32_bf16 v[44:47], v[156:159], v[200:203], v[44:47]
	v_mfma_f32_16x16x32_bf16 v[40:43], v[164:167], v[200:203], v[40:43]
	v_mfma_f32_16x16x32_bf16 v[28:31], v[156:159], v[208:211], v[28:31]
	v_mfma_f32_16x16x32_bf16 v[24:27], v[164:167], v[208:211], v[24:27]
	v_mfma_f32_16x16x32_bf16 v[12:15], v[156:159], v[216:219], v[12:15]
	v_mfma_f32_16x16x32_bf16 v[8:11], v[164:167], v[216:219], v[8:11]
	s_setprio 0
	s_setprio 1
	v_mfma_f32_16x16x32_bf16 v[52:55], v[168:171], v[184:187], v[52:55]
	v_mfma_f32_16x16x32_bf16 v[48:51], v[176:179], v[184:187], v[48:51]
	v_mfma_f32_16x16x32_bf16 v[36:39], v[168:171], v[196:199], v[36:39]
	v_mfma_f32_16x16x32_bf16 v[32:35], v[176:179], v[196:199], v[32:35]
	v_mfma_f32_16x16x32_bf16 v[20:23], v[168:171], v[204:207], v[20:23]
	v_mfma_f32_16x16x32_bf16 v[16:19], v[176:179], v[204:207], v[16:19]
	v_mfma_f32_16x16x32_bf16 v[4:7], v[168:171], v[212:215], v[4:7]
	v_mfma_f32_16x16x32_bf16 v[0:3], v[176:179], v[212:215], v[0:3]
	v_mfma_f32_16x16x32_bf16 v[52:55], v[172:175], v[192:195], v[52:55]
	v_mfma_f32_16x16x32_bf16 v[48:51], v[180:183], v[192:195], v[48:51]
	v_mfma_f32_16x16x32_bf16 v[36:39], v[172:175], v[200:203], v[36:39]
	v_mfma_f32_16x16x32_bf16 v[32:35], v[180:183], v[200:203], v[32:35]
	v_mfma_f32_16x16x32_bf16 v[20:23], v[172:175], v[208:211], v[20:23]
	v_mfma_f32_16x16x32_bf16 v[16:19], v[180:183], v[208:211], v[16:19]
	v_mfma_f32_16x16x32_bf16 v[4:7], v[172:175], v[216:219], v[4:7]
	v_mfma_f32_16x16x32_bf16 v[0:3], v[180:183], v[216:219], v[0:3]
	s_setprio 0
	s_barrier
	s_add_i32 s77, s77, 2
	s_add_u32 s34, s34, 0x100
	s_addc_u32 s35, s35, 0
	s_add_u32 s75, s75, 0x100
	s_addc_u32 s76, s76, 0
	s_cmp_gt_u32 s77, 13
	s_cbranch_scc0 .LBB0_837
	s_and_b64 vcc, exec, s[12:13]
	s_cbranch_vccz .LBB0_840
	s_barrier

.LBB0_906:
	s_lshl_b32 s5, s5, 5
	s_mov_b64 s[10:11], 0x80
	s_and_b32 s5, s5, 0x60
	s_add_i32 m0, s31, 0x18000
	v_lshl_add_u64 v[6:7], v[6:7], 0, s[10:11]
	s_lshl_b32 s16, s13, 13
	s_lshl_b32 s17, s5, 7
	s_waitcnt vmcnt(2)
	s_barrier
	global_load_lds_dwordx4 v[6:7], off
	v_lshl_add_u64 v[4:5], v[4:5], 0, s[10:11]
	s_add_i32 m0, s31, 0x1a000
	s_add_i32 s65, s31, 0x8000
	s_add_i32 s66, s31, 0xa000
	global_load_lds_dwordx4 v[4:5], off
	v_lshl_add_u64 v[0:1], v[0:1], 0, s[10:11]
	s_mov_b32 m0, s65
	s_add_u32 s14, s40, 0x100080
	global_load_lds_dwordx4 v[0:1], off
	v_lshl_add_u64 v[0:1], v[2:3], 0, s[10:11]
	s_mov_b32 m0, s66
	s_addc_u32 s15, s41, 0
	global_load_lds_dwordx4 v[0:1], off
	s_add_i32 m0, s31, 0x1c000
	s_nop 0
	global_load_lds_dwordx4 v130, s[14:15]
	s_add_i32 m0, s31, 0x1e000
	s_cmpk_lt_u32 s12, 0x100
	global_load_lds_dwordx4 v134, s[14:15]
	v_lshrrev_b32_e32 v1, 1, v8
	v_and_b32_e32 v1, 24, v1
	v_and_b32_e32 v0, 15, v8
	v_lshlrev_b32_e32 v2, 1, v1
	v_lshl_or_b32 v146, s13, 6, v0
	v_lshl_or_b32 v0, v0, 6, v2
	v_lshlrev_b32_e32 v2, 2, v8
	v_and_b32_e32 v2, 32, v2
	v_bitop3_b32 v3, v0, s16, v2 bitop3:0xde
	v_bitop3_b32 v147, v0, s17, v2 bitop3:0xde
	v_lshlrev_b32_e32 v0, 16, v9
	v_and_b32_e32 v0, 0xfffe0000, v0
	v_or_b32_e32 v148, s5, v1
	v_lshl_add_u32 v0, v10, 13, v0
	v_and_b32_e32 v1, 1, v9
	v_lshl_or_b32 v0, v1, 6, v0
	v_lshl_add_u32 v136, v11, 1, v0
	v_lshlrev_b32_e32 v0, 16, v12
	v_and_b32_e32 v0, 0xfffe0000, v0
	s_waitcnt vmcnt(6)
	v_lshl_add_u32 v0, v13, 13, v0
	v_and_b32_e32 v1, 1, v12
	s_cselect_b64 s[12:13], -1, 0
	v_lshl_or_b32 v0, v1, 6, v0
	s_add_i32 s68, 0, 0x10000
	s_add_i32 s69, 0, 0x14000
	s_sext_i32_i8 s54, s4
	s_ashr_i32 s67, s3, 31
	v_mov_b32_e32 v137, v131
	v_lshl_add_u32 v138, v14, 1, v0
	v_mov_b32_e32 v139, v131
	v_mov_b64_e32 v[140:141], 0x200
	v_mov_b64_e32 v[142:143], 0x1ff
	v_add_u32_e32 v149, s68, v147
	v_add_u32_e32 v150, s69, v147
	v_add_u32_e32 v151, 0, v3
	s_mov_b64 s[14:15], 0x40000
	s_mov_b32 s70, 0x40000
	s_mov_b64 s[16:17], 0x48000
	s_mov_b32 s71, 0x48000
	s_mov_b64 s[18:19], 0x50000
	s_mov_b32 s72, 0x50000
	s_mov_b64 s[20:21], 0x58000
	s_mov_b32 s73, 0x58000
	s_barrier
	s_branch .LBB0_909

.LBB0_916:
	ds_read_b128 v[152:155], v149
	ds_read_b128 v[156:159], v149 offset:1024
	ds_read_b128 v[160:163], v149 offset:2048
	ds_read_b128 v[164:167], v149 offset:3072
	ds_read_b128 v[168:171], v150
	ds_read_b128 v[172:175], v150 offset:1024
	ds_read_b128 v[176:179], v150 offset:2048
	ds_read_b128 v[180:183], v150 offset:3072
	s_add_u32 s40, s34, 0xfff00080
	s_addc_u32 s41, s35, -1
	s_cmp_eq_u32 s77, 60
	s_cselect_b32 s43, s25, s41
	s_cselect_b32 s42, s55, s40
	s_cselect_b32 s41, s23, s76
	s_cselect_b32 s40, s74, s75
	s_add_i32 m0, s31, 0xc000
	ds_read_b128 v[184:187], v151
	ds_read_b128 v[192:195], v151 offset:1024
	ds_read_b128 v[196:199], v151 offset:2048
	ds_read_b128 v[200:203], v151 offset:3072
	ds_read_b128 v[204:207], v151 offset:4096
	ds_read_b128 v[208:211], v151 offset:5120
	ds_read_b128 v[212:215], v151 offset:6144
	ds_read_b128 v[216:219], v151 offset:7168
	global_load_lds_dwordx4 v136, s[34:35]
	s_add_i32 m0, s31, 0xe000
	s_nop 0
	global_load_lds_dwordx4 v138, s[34:35]
	s_waitcnt vmcnt(8)
	s_waitcnt lgkmcnt(0)
	s_barrier
	s_setprio 1
	s_waitcnt lgkmcnt(0)
	v_mfma_f32_16x16x32_bf16 v[124:127], v[152:155], v[184:187], v[124:127]
	v_mfma_f32_16x16x32_bf16 v[120:123], v[160:163], v[184:187], v[120:123]
	v_mfma_f32_16x16x32_bf16 v[116:119], v[152:155], v[196:199], v[116:119]
	v_mfma_f32_16x16x32_bf16 v[108:111], v[160:163], v[196:199], v[108:111]
	v_mfma_f32_16x16x32_bf16 v[100:103], v[152:155], v[204:207], v[100:103]
	v_mfma_f32_16x16x32_bf16 v[92:95], v[160:163], v[204:207], v[92:95]
	v_mfma_f32_16x16x32_bf16 v[84:87], v[152:155], v[212:215], v[84:87]
	v_mfma_f32_16x16x32_bf16 v[76:79], v[160:163], v[212:215], v[76:79]
	v_mfma_f32_16x16x32_bf16 v[124:127], v[156:159], v[192:195], v[124:127]
	v_mfma_f32_16x16x32_bf16 v[120:123], v[164:167], v[192:195], v[120:123]
	v_mfma_f32_16x16x32_bf16 v[116:119], v[156:159], v[200:203], v[116:119]
	v_mfma_f32_16x16x32_bf16 v[108:111], v[164:167], v[200:203], v[108:111]
	v_mfma_f32_16x16x32_bf16 v[100:103], v[156:159], v[208:211], v[100:103]
	v_mfma_f32_16x16x32_bf16 v[92:95], v[164:167], v[208:211], v[92:95]
	v_mfma_f32_16x16x32_bf16 v[84:87], v[156:159], v[216:219], v[84:87]
	v_mfma_f32_16x16x32_bf16 v[76:79], v[164:167], v[216:219], v[76:79]
	s_setprio 0
	s_setprio 1
	v_mfma_f32_16x16x32_bf16 v[112:115], v[168:171], v[184:187], v[112:115]
	v_mfma_f32_16x16x32_bf16 v[104:107], v[176:179], v[184:187], v[104:107]
	v_mfma_f32_16x16x32_bf16 v[96:99], v[168:171], v[196:199], v[96:99]
	v_mfma_f32_16x16x32_bf16 v[88:91], v[176:179], v[196:199], v[88:91]
	v_mfma_f32_16x16x32_bf16 v[80:83], v[168:171], v[204:207], v[80:83]
	v_mfma_f32_16x16x32_bf16 v[72:75], v[176:179], v[204:207], v[72:75]
	v_mfma_f32_16x16x32_bf16 v[68:71], v[168:171], v[212:215], v[68:71]
	v_mfma_f32_16x16x32_bf16 v[64:67], v[176:179], v[212:215], v[64:67]
	v_mfma_f32_16x16x32_bf16 v[112:115], v[172:175], v[192:195], v[112:115]
	v_mfma_f32_16x16x32_bf16 v[104:107], v[180:183], v[192:195], v[104:107]
	v_mfma_f32_16x16x32_bf16 v[96:99], v[172:175], v[200:203], v[96:99]
	v_mfma_f32_16x16x32_bf16 v[88:91], v[180:183], v[200:203], v[88:91]
	v_mfma_f32_16x16x32_bf16 v[80:83], v[172:175], v[208:211], v[80:83]
	v_mfma_f32_16x16x32_bf16 v[72:75], v[180:183], v[208:211], v[72:75]
	v_mfma_f32_16x16x32_bf16 v[68:71], v[172:175], v[216:219], v[68:71]
	v_mfma_f32_16x16x32_bf16 v[64:67], v[180:183], v[216:219], v[64:67]
	s_setprio 0
	s_barrier
	s_add_i32 s79, s68, s61
	v_lshl_add_u64 v[144:145], s[40:41], 0, v[130:131]
	s_mov_b32 m0, s79
	ds_read_b128 v[184:187], v151 offset:16384
	ds_read_b128 v[192:195], v151 offset:17408
	ds_read_b128 v[196:199], v151 offset:18432
	ds_read_b128 v[200:203], v151 offset:19456
	ds_read_b128 v[204:207], v151 offset:20480
	ds_read_b128 v[208:211], v151 offset:21504
	ds_read_b128 v[212:215], v151 offset:22528
	ds_read_b128 v[216:219], v151 offset:23552
	global_load_lds_dwordx4 v[144:145], off
	s_add_i32 m0, s79, 0x2000
	s_add_u32 s80, s40, 0x100000
	v_lshl_add_u64 v[188:189], s[40:41], 0, v[134:135]
	s_addc_u32 s81, s41, 0
	s_add_i32 s79, s69, s61
	global_load_lds_dwordx4 v[188:189], off
	s_mov_b32 m0, s79
	v_lshl_add_u64 v[222:223], s[42:43], 0, v[132:133]
	global_load_lds_dwordx4 v130, s[80:81]
	s_add_i32 m0, s79, 0x2000
	s_nop 0
	global_load_lds_dwordx4 v134, s[80:81]
	v_lshl_add_u64 v[220:221], s[42:43], 0, v[128:129]
	s_mov_b32 m0, s31
	s_nop 0
	global_load_lds_dwordx4 v[220:221], off
	s_mov_b32 m0, s33
	s_nop 0
	global_load_lds_dwordx4 v[222:223], off
	s_waitcnt vmcnt(8)
	s_waitcnt lgkmcnt(0)
	s_barrier
	s_setprio 1
	s_waitcnt lgkmcnt(0)
	v_mfma_f32_16x16x32_bf16 v[60:63], v[152:155], v[184:187], v[60:63]
	v_mfma_f32_16x16x32_bf16 v[56:59], v[160:163], v[184:187], v[56:59]
	v_mfma_f32_16x16x32_bf16 v[52:55], v[152:155], v[196:199], v[52:55]
	v_mfma_f32_16x16x32_bf16 v[44:47], v[160:163], v[196:199], v[44:47]
	v_mfma_f32_16x16x32_bf16 v[36:39], v[152:155], v[204:207], v[36:39]
	v_mfma_f32_16x16x32_bf16 v[28:31], v[160:163], v[204:207], v[28:31]
	v_mfma_f32_16x16x32_bf16 v[20:23], v[152:155], v[212:215], v[20:23]
	v_mfma_f32_16x16x32_bf16 v[12:15], v[160:163], v[212:215], v[12:15]
	v_mfma_f32_16x16x32_bf16 v[60:63], v[156:159], v[192:195], v[60:63]
	v_mfma_f32_16x16x32_bf16 v[56:59], v[164:167], v[192:195], v[56:59]
	v_mfma_f32_16x16x32_bf16 v[52:55], v[156:159], v[200:203], v[52:55]
	v_mfma_f32_16x16x32_bf16 v[44:47], v[164:167], v[200:203], v[44:47]
	v_mfma_f32_16x16x32_bf16 v[36:39], v[156:159], v[208:211], v[36:39]
	v_mfma_f32_16x16x32_bf16 v[28:31], v[164:167], v[208:211], v[28:31]
	v_mfma_f32_16x16x32_bf16 v[20:23], v[156:159], v[216:219], v[20:23]
	v_mfma_f32_16x16x32_bf16 v[12:15], v[164:167], v[216:219], v[12:15]
	s_setprio 0
	s_setprio 1
	v_mfma_f32_16x16x32_bf16 v[48:51], v[168:171], v[184:187], v[48:51]
	v_mfma_f32_16x16x32_bf16 v[40:43], v[176:179], v[184:187], v[40:43]
	v_mfma_f32_16x16x32_bf16 v[32:35], v[168:171], v[196:199], v[32:35]
	v_mfma_f32_16x16x32_bf16 v[24:27], v[176:179], v[196:199], v[24:27]
	v_mfma_f32_16x16x32_bf16 v[16:19], v[168:171], v[204:207], v[16:19]
	v_mfma_f32_16x16x32_bf16 v[8:11], v[176:179], v[204:207], v[8:11]
	v_mfma_f32_16x16x32_bf16 v[4:7], v[168:171], v[212:215], v[4:7]
	v_mfma_f32_16x16x32_bf16 v[0:3], v[176:179], v[212:215], v[0:3]
	v_mfma_f32_16x16x32_bf16 v[48:51], v[172:175], v[192:195], v[48:51]
	v_mfma_f32_16x16x32_bf16 v[40:43], v[180:183], v[192:195], v[40:43]
	v_mfma_f32_16x16x32_bf16 v[32:35], v[172:175], v[200:203], v[32:35]
	v_mfma_f32_16x16x32_bf16 v[24:27], v[180:183], v[200:203], v[24:27]
	v_mfma_f32_16x16x32_bf16 v[16:19], v[172:175], v[208:211], v[16:19]
	v_mfma_f32_16x16x32_bf16 v[8:11], v[180:183], v[208:211], v[8:11]
	v_mfma_f32_16x16x32_bf16 v[4:7], v[172:175], v[216:219], v[4:7]
	v_mfma_f32_16x16x32_bf16 v[0:3], v[180:183], v[216:219], v[0:3]
	s_setprio 0
	s_barrier
	s_add_i32 s79, 0, 0x18000
	s_add_i32 s80, 0, 0x1c000
	v_add_u32_e32 v164, s79, v147
	v_add_u32_e32 v180, s80, v147
	ds_read_b128 v[152:155], v164
	ds_read_b128 v[156:159], v164 offset:1024
	ds_read_b128 v[160:163], v164 offset:2048
	ds_read_b128 v[164:167], v164 offset:3072
	ds_read_b128 v[168:171], v180
	ds_read_b128 v[172:175], v180 offset:1024
	ds_read_b128 v[176:179], v180 offset:2048
	ds_read_b128 v[180:183], v180 offset:3072
	s_add_u32 s42, s42, 0x100000
	s_addc_u32 s43, s43, 0
	s_mov_b32 m0, s62
	ds_read_b128 v[184:187], v151 offset:32768
	ds_read_b128 v[192:195], v151 offset:33792
	ds_read_b128 v[196:199], v151 offset:34816
	ds_read_b128 v[200:203], v151 offset:35840
	ds_read_b128 v[204:207], v151 offset:36864
	ds_read_b128 v[208:211], v151 offset:37888
	ds_read_b128 v[212:215], v151 offset:38912
	ds_read_b128 v[216:219], v151 offset:39936
	global_load_lds_dwordx4 v128, s[42:43]
	s_mov_b32 m0, s63
	s_nop 0
	global_load_lds_dwordx4 v132, s[42:43]
	s_waitcnt vmcnt(8)
	s_waitcnt lgkmcnt(0)
	s_barrier
	s_setprio 1
	s_waitcnt lgkmcnt(0)
	v_mfma_f32_16x16x32_bf16 v[124:127], v[152:155], v[184:187], v[124:127]
	v_mfma_f32_16x16x32_bf16 v[120:123], v[160:163], v[184:187], v[120:123]
	v_mfma_f32_16x16x32_bf16 v[116:119], v[152:155], v[196:199], v[116:119]
	v_mfma_f32_16x16x32_bf16 v[108:111], v[160:163], v[196:199], v[108:111]
	v_mfma_f32_16x16x32_bf16 v[100:103], v[152:155], v[204:207], v[100:103]
	v_mfma_f32_16x16x32_bf16 v[92:95], v[160:163], v[204:207], v[92:95]
	v_mfma_f32_16x16x32_bf16 v[84:87], v[152:155], v[212:215], v[84:87]
	v_mfma_f32_16x16x32_bf16 v[76:79], v[160:163], v[212:215], v[76:79]
	v_mfma_f32_16x16x32_bf16 v[124:127], v[156:159], v[192:195], v[124:127]
	v_mfma_f32_16x16x32_bf16 v[120:123], v[164:167], v[192:195], v[120:123]
	v_mfma_f32_16x16x32_bf16 v[116:119], v[156:159], v[200:203], v[116:119]
	v_mfma_f32_16x16x32_bf16 v[108:111], v[164:167], v[200:203], v[108:111]
	v_mfma_f32_16x16x32_bf16 v[100:103], v[156:159], v[208:211], v[100:103]
	v_mfma_f32_16x16x32_bf16 v[92:95], v[164:167], v[208:211], v[92:95]
	v_mfma_f32_16x16x32_bf16 v[84:87], v[156:159], v[216:219], v[84:87]
	v_mfma_f32_16x16x32_bf16 v[76:79], v[164:167], v[216:219], v[76:79]
	s_setprio 0
	s_setprio 1
	v_mfma_f32_16x16x32_bf16 v[112:115], v[168:171], v[184:187], v[112:115]
	v_mfma_f32_16x16x32_bf16 v[104:107], v[176:179], v[184:187], v[104:107]
	v_mfma_f32_16x16x32_bf16 v[96:99], v[168:171], v[196:199], v[96:99]
	v_mfma_f32_16x16x32_bf16 v[88:91], v[176:179], v[196:199], v[88:91]
	v_mfma_f32_16x16x32_bf16 v[80:83], v[168:171], v[204:207], v[80:83]
	v_mfma_f32_16x16x32_bf16 v[72:75], v[176:179], v[204:207], v[72:75]
	v_mfma_f32_16x16x32_bf16 v[68:71], v[168:171], v[212:215], v[68:71]
	v_mfma_f32_16x16x32_bf16 v[64:67], v[176:179], v[212:215], v[64:67]
	v_mfma_f32_16x16x32_bf16 v[112:115], v[172:175], v[192:195], v[112:115]
	v_mfma_f32_16x16x32_bf16 v[104:107], v[180:183], v[192:195], v[104:107]
	v_mfma_f32_16x16x32_bf16 v[96:99], v[172:175], v[200:203], v[96:99]
	v_mfma_f32_16x16x32_bf16 v[88:91], v[180:183], v[200:203], v[88:91]
	v_mfma_f32_16x16x32_bf16 v[80:83], v[172:175], v[208:211], v[80:83]
	v_mfma_f32_16x16x32_bf16 v[72:75], v[180:183], v[208:211], v[72:75]
	v_mfma_f32_16x16x32_bf16 v[68:71], v[172:175], v[216:219], v[68:71]
	v_mfma_f32_16x16x32_bf16 v[64:67], v[180:183], v[216:219], v[64:67]
	s_setprio 0
	s_barrier
	s_add_i32 s42, s79, s61
	v_lshl_add_u64 v[144:145], v[144:145], 0, s[10:11]
	s_mov_b32 m0, s42
	ds_read_b128 v[184:187], v151 offset:49152
	ds_read_b128 v[192:195], v151 offset:50176
	ds_read_b128 v[196:199], v151 offset:51200
	ds_read_b128 v[200:203], v151 offset:52224
	ds_read_b128 v[204:207], v151 offset:53248
	ds_read_b128 v[208:211], v151 offset:54272
	ds_read_b128 v[212:215], v151 offset:55296
	ds_read_b128 v[216:219], v151 offset:56320
	global_load_lds_dwordx4 v[144:145], off
	s_add_i32 m0, s42, 0x2000
	s_add_u32 s40, s40, 0x100080
	v_lshl_add_u64 v[144:145], v[188:189], 0, s[10:11]
	s_addc_u32 s41, s41, 0
	s_add_i32 s42, s80, s61
	global_load_lds_dwordx4 v[144:145], off
	s_mov_b32 m0, s42
	s_nop 0
	global_load_lds_dwordx4 v130, s[40:41]
	s_add_i32 m0, s42, 0x2000
	s_nop 0
	global_load_lds_dwordx4 v134, s[40:41]
	v_lshl_add_u64 v[144:145], v[220:221], 0, s[10:11]
	s_mov_b32 m0, s65
	s_nop 0
	global_load_lds_dwordx4 v[144:145], off
	v_lshl_add_u64 v[144:145], v[222:223], 0, s[10:11]
	s_mov_b32 m0, s66
	s_nop 0
	global_load_lds_dwordx4 v[144:145], off
	s_waitcnt vmcnt(8)
	s_waitcnt lgkmcnt(0)
	s_barrier
	s_setprio 1
	s_waitcnt lgkmcnt(0)
	v_mfma_f32_16x16x32_bf16 v[60:63], v[152:155], v[184:187], v[60:63]
	v_mfma_f32_16x16x32_bf16 v[56:59], v[160:163], v[184:187], v[56:59]
	v_mfma_f32_16x16x32_bf16 v[52:55], v[152:155], v[196:199], v[52:55]
	v_mfma_f32_16x16x32_bf16 v[44:47], v[160:163], v[196:199], v[44:47]
	v_mfma_f32_16x16x32_bf16 v[36:39], v[152:155], v[204:207], v[36:39]
	v_mfma_f32_16x16x32_bf16 v[28:31], v[160:163], v[204:207], v[28:31]
	v_mfma_f32_16x16x32_bf16 v[20:23], v[152:155], v[212:215], v[20:23]
	v_mfma_f32_16x16x32_bf16 v[12:15], v[160:163], v[212:215], v[12:15]
	v_mfma_f32_16x16x32_bf16 v[60:63], v[156:159], v[192:195], v[60:63]
	v_mfma_f32_16x16x32_bf16 v[56:59], v[164:167], v[192:195], v[56:59]
	v_mfma_f32_16x16x32_bf16 v[52:55], v[156:159], v[200:203], v[52:55]
	v_mfma_f32_16x16x32_bf16 v[44:47], v[164:167], v[200:203], v[44:47]
	v_mfma_f32_16x16x32_bf16 v[36:39], v[156:159], v[208:211], v[36:39]
	v_mfma_f32_16x16x32_bf16 v[28:31], v[164:167], v[208:211], v[28:31]
	v_mfma_f32_16x16x32_bf16 v[20:23], v[156:159], v[216:219], v[20:23]
	v_mfma_f32_16x16x32_bf16 v[12:15], v[164:167], v[216:219], v[12:15]
	s_setprio 0
	s_setprio 1
	v_mfma_f32_16x16x32_bf16 v[48:51], v[168:171], v[184:187], v[48:51]
	v_mfma_f32_16x16x32_bf16 v[40:43], v[176:179], v[184:187], v[40:43]
	v_mfma_f32_16x16x32_bf16 v[32:35], v[168:171], v[196:199], v[32:35]
	v_mfma_f32_16x16x32_bf16 v[24:27], v[176:179], v[196:199], v[24:27]
	v_mfma_f32_16x16x32_bf16 v[16:19], v[168:171], v[204:207], v[16:19]
	v_mfma_f32_16x16x32_bf16 v[8:11], v[176:179], v[204:207], v[8:11]
	v_mfma_f32_16x16x32_bf16 v[4:7], v[168:171], v[212:215], v[4:7]
	v_mfma_f32_16x16x32_bf16 v[0:3], v[176:179], v[212:215], v[0:3]
	v_mfma_f32_16x16x32_bf16 v[48:51], v[172:175], v[192:195], v[48:51]
	v_mfma_f32_16x16x32_bf16 v[40:43], v[180:183], v[192:195], v[40:43]
	v_mfma_f32_16x16x32_bf16 v[32:35], v[172:175], v[200:203], v[32:35]
	v_mfma_f32_16x16x32_bf16 v[24:27], v[180:183], v[200:203], v[24:27]
	v_mfma_f32_16x16x32_bf16 v[16:19], v[172:175], v[208:211], v[16:19]
	v_mfma_f32_16x16x32_bf16 v[8:11], v[180:183], v[208:211], v[8:11]
	v_mfma_f32_16x16x32_bf16 v[4:7], v[172:175], v[216:219], v[4:7]
	v_mfma_f32_16x16x32_bf16 v[0:3], v[180:183], v[216:219], v[0:3]
	s_setprio 0
	s_barrier
	s_add_i32 s77, s77, 2
	s_add_u32 s34, s34, 0x100
	s_addc_u32 s35, s35, 0
	s_add_u32 s75, s75, 0x100
	s_addc_u32 s76, s76, 0
	s_cmp_gt_u32 s77, 61
	s_cbranch_scc0 .LBB0_916
	s_and_b64 vcc, exec, s[12:13]
	s_cbranch_vccz .LBB0_919
	s_barrier

.LBB0_1043:
	s_lshl_b32 s5, s5, 5
	s_mov_b64 s[12:13], 0x80
	s_and_b32 s5, s5, 0x60
	s_add_i32 m0, s35, 0x18000
	v_lshl_add_u64 v[6:7], v[6:7], 0, s[12:13]
	s_lshl_b32 s18, s15, 13
	s_lshl_b32 s19, s5, 7
	s_waitcnt vmcnt(2)
	s_barrier
	global_load_lds_dwordx4 v[6:7], off
	v_lshl_add_u64 v[4:5], v[4:5], 0, s[12:13]
	s_add_i32 m0, s35, 0x1a000
	s_add_i32 s69, s35, 0x8000
	s_add_i32 s70, s35, 0xa000
	global_load_lds_dwordx4 v[4:5], off
	v_lshl_add_u64 v[0:1], v[0:1], 0, s[12:13]
	s_mov_b32 m0, s69
	s_add_u32 s16, s60, 0x40080
	global_load_lds_dwordx4 v[0:1], off
	v_lshl_add_u64 v[0:1], v[2:3], 0, s[12:13]
	s_mov_b32 m0, s70
	s_addc_u32 s17, s61, 0
	global_load_lds_dwordx4 v[0:1], off
	s_add_i32 m0, s35, 0x1c000
	s_nop 0
	global_load_lds_dwordx4 v130, s[16:17]
	s_add_i32 m0, s35, 0x1e000
	s_cmpk_lt_u32 s14, 0x100
	global_load_lds_dwordx4 v134, s[16:17]
	v_lshrrev_b32_e32 v1, 1, v8
	v_and_b32_e32 v1, 24, v1
	v_and_b32_e32 v0, 15, v8
	v_lshlrev_b32_e32 v2, 1, v1
	v_lshl_or_b32 v146, s15, 6, v0
	v_lshl_or_b32 v0, v0, 6, v2
	v_lshlrev_b32_e32 v2, 2, v8
	v_and_b32_e32 v2, 32, v2
	v_bitop3_b32 v3, v0, s18, v2 bitop3:0xde
	v_bitop3_b32 v147, v0, s19, v2 bitop3:0xde
	v_lshlrev_b32_e32 v0, 14, v9
	v_and_b32_e32 v0, 0xffff8000, v0
	v_or_b32_e32 v148, s5, v1
	v_lshl_add_u32 v0, v10, 11, v0
	v_and_b32_e32 v1, 1, v9
	v_lshl_or_b32 v0, v1, 6, v0
	v_lshl_add_u32 v136, v11, 1, v0
	v_lshlrev_b32_e32 v0, 14, v12
	v_and_b32_e32 v0, 0xffff8000, v0
	s_waitcnt vmcnt(6)
	v_lshl_add_u32 v0, v13, 11, v0
	v_and_b32_e32 v1, 1, v12
	s_cselect_b64 s[14:15], -1, 0
	v_lshl_or_b32 v0, v1, 6, v0
	s_add_i32 s72, 0, 0x10000
	s_add_i32 s73, 0, 0x14000
	s_sext_i32_i8 s54, s4
	s_ashr_i32 s71, s3, 31
	v_mov_b32_e32 v137, v131
	v_lshl_add_u32 v138, v14, 1, v0
	v_mov_b32_e32 v139, v131
	v_mov_b64_e32 v[140:141], 0x100
	v_mov_b64_e32 v[142:143], 0xff
	v_add_u32_e32 v149, s72, v147
	v_add_u32_e32 v150, s73, v147
	v_add_u32_e32 v151, 0, v3
	s_mov_b64 s[16:17], 0x20000
	s_mov_b32 s74, 0x20000
	s_mov_b64 s[18:19], 0x24000
	s_mov_b32 s75, 0x24000
	s_mov_b64 s[20:21], 0x28000
	s_mov_b32 s76, 0x28000
	s_mov_b64 s[22:23], 0x2c000
	s_mov_b32 s77, 0x2c000
	s_barrier
	s_branch .LBB0_1046

.LBB0_1053:
	ds_read_b128 v[152:155], v149
	ds_read_b128 v[156:159], v149 offset:1024
	ds_read_b128 v[160:163], v149 offset:2048
	ds_read_b128 v[164:167], v149 offset:3072
	ds_read_b128 v[168:171], v150
	ds_read_b128 v[172:175], v150 offset:1024
	ds_read_b128 v[176:179], v150 offset:2048
	ds_read_b128 v[180:183], v150 offset:3072
	s_add_u32 s60, s42, 0xfffc0080
	s_addc_u32 s61, s43, -1
	s_cmp_eq_u32 s82, 12
	s_cselect_b32 s63, s27, s61
	s_cselect_b32 s62, s55, s60
	s_cselect_b32 s61, s25, s81
	s_cselect_b32 s60, s79, s80
	s_add_i32 m0, s35, 0xc000
	ds_read_b128 v[184:187], v151
	ds_read_b128 v[192:195], v151 offset:1024
	ds_read_b128 v[196:199], v151 offset:2048
	ds_read_b128 v[200:203], v151 offset:3072
	ds_read_b128 v[204:207], v151 offset:4096
	ds_read_b128 v[208:211], v151 offset:5120
	ds_read_b128 v[212:215], v151 offset:6144
	ds_read_b128 v[216:219], v151 offset:7168
	global_load_lds_dwordx4 v136, s[42:43]
	s_add_i32 m0, s35, 0xe000
	s_nop 0
	global_load_lds_dwordx4 v138, s[42:43]
	s_waitcnt vmcnt(8)
	s_waitcnt lgkmcnt(0)
	s_barrier
	s_setprio 1
	s_waitcnt lgkmcnt(0)
	v_mfma_f32_16x16x32_bf16 v[124:127], v[152:155], v[184:187], v[124:127]
	v_mfma_f32_16x16x32_bf16 v[120:123], v[160:163], v[184:187], v[120:123]
	v_mfma_f32_16x16x32_bf16 v[116:119], v[152:155], v[196:199], v[116:119]
	v_mfma_f32_16x16x32_bf16 v[108:111], v[160:163], v[196:199], v[108:111]
	v_mfma_f32_16x16x32_bf16 v[100:103], v[152:155], v[204:207], v[100:103]
	v_mfma_f32_16x16x32_bf16 v[92:95], v[160:163], v[204:207], v[92:95]
	v_mfma_f32_16x16x32_bf16 v[84:87], v[152:155], v[212:215], v[84:87]
	v_mfma_f32_16x16x32_bf16 v[76:79], v[160:163], v[212:215], v[76:79]
	v_mfma_f32_16x16x32_bf16 v[124:127], v[156:159], v[192:195], v[124:127]
	v_mfma_f32_16x16x32_bf16 v[120:123], v[164:167], v[192:195], v[120:123]
	v_mfma_f32_16x16x32_bf16 v[116:119], v[156:159], v[200:203], v[116:119]
	v_mfma_f32_16x16x32_bf16 v[108:111], v[164:167], v[200:203], v[108:111]
	v_mfma_f32_16x16x32_bf16 v[100:103], v[156:159], v[208:211], v[100:103]
	v_mfma_f32_16x16x32_bf16 v[92:95], v[164:167], v[208:211], v[92:95]
	v_mfma_f32_16x16x32_bf16 v[84:87], v[156:159], v[216:219], v[84:87]
	v_mfma_f32_16x16x32_bf16 v[76:79], v[164:167], v[216:219], v[76:79]
	s_setprio 0
	s_setprio 1
	v_mfma_f32_16x16x32_bf16 v[112:115], v[168:171], v[184:187], v[112:115]
	v_mfma_f32_16x16x32_bf16 v[104:107], v[176:179], v[184:187], v[104:107]
	v_mfma_f32_16x16x32_bf16 v[96:99], v[168:171], v[196:199], v[96:99]
	v_mfma_f32_16x16x32_bf16 v[88:91], v[176:179], v[196:199], v[88:91]
	v_mfma_f32_16x16x32_bf16 v[80:83], v[168:171], v[204:207], v[80:83]
	v_mfma_f32_16x16x32_bf16 v[72:75], v[176:179], v[204:207], v[72:75]
	v_mfma_f32_16x16x32_bf16 v[68:71], v[168:171], v[212:215], v[68:71]
	v_mfma_f32_16x16x32_bf16 v[64:67], v[176:179], v[212:215], v[64:67]
	v_mfma_f32_16x16x32_bf16 v[112:115], v[172:175], v[192:195], v[112:115]
	v_mfma_f32_16x16x32_bf16 v[104:107], v[180:183], v[192:195], v[104:107]
	v_mfma_f32_16x16x32_bf16 v[96:99], v[172:175], v[200:203], v[96:99]
	v_mfma_f32_16x16x32_bf16 v[88:91], v[180:183], v[200:203], v[88:91]
	v_mfma_f32_16x16x32_bf16 v[80:83], v[172:175], v[208:211], v[80:83]
	v_mfma_f32_16x16x32_bf16 v[72:75], v[180:183], v[208:211], v[72:75]
	v_mfma_f32_16x16x32_bf16 v[68:71], v[172:175], v[216:219], v[68:71]
	v_mfma_f32_16x16x32_bf16 v[64:67], v[180:183], v[216:219], v[64:67]
	s_setprio 0
	s_barrier
	s_add_i32 s83, s72, s65
	v_lshl_add_u64 v[144:145], s[60:61], 0, v[130:131]
	s_mov_b32 m0, s83
	ds_read_b128 v[184:187], v151 offset:16384
	ds_read_b128 v[192:195], v151 offset:17408
	ds_read_b128 v[196:199], v151 offset:18432
	ds_read_b128 v[200:203], v151 offset:19456
	ds_read_b128 v[204:207], v151 offset:20480
	ds_read_b128 v[208:211], v151 offset:21504
	ds_read_b128 v[212:215], v151 offset:22528
	ds_read_b128 v[216:219], v151 offset:23552
	global_load_lds_dwordx4 v[144:145], off
	s_add_i32 m0, s83, 0x2000
	s_add_u32 s84, s60, 0x40000
	v_lshl_add_u64 v[188:189], s[60:61], 0, v[134:135]
	s_addc_u32 s85, s61, 0
	s_add_i32 s83, s73, s65
	global_load_lds_dwordx4 v[188:189], off
	s_mov_b32 m0, s83
	v_lshl_add_u64 v[222:223], s[62:63], 0, v[132:133]
	global_load_lds_dwordx4 v130, s[84:85]
	s_add_i32 m0, s83, 0x2000
	s_nop 0
	global_load_lds_dwordx4 v134, s[84:85]
	v_lshl_add_u64 v[220:221], s[62:63], 0, v[128:129]
	s_mov_b32 m0, s35
	s_nop 0
	global_load_lds_dwordx4 v[220:221], off
	s_mov_b32 m0, s33
	s_nop 0
	global_load_lds_dwordx4 v[222:223], off
	s_waitcnt vmcnt(8)
	s_waitcnt lgkmcnt(0)
	s_barrier
	s_setprio 1
	s_waitcnt lgkmcnt(0)
	v_mfma_f32_16x16x32_bf16 v[60:63], v[152:155], v[184:187], v[60:63]
	v_mfma_f32_16x16x32_bf16 v[56:59], v[160:163], v[184:187], v[56:59]
	v_mfma_f32_16x16x32_bf16 v[52:55], v[152:155], v[196:199], v[52:55]
	v_mfma_f32_16x16x32_bf16 v[44:47], v[160:163], v[196:199], v[44:47]
	v_mfma_f32_16x16x32_bf16 v[36:39], v[152:155], v[204:207], v[36:39]
	v_mfma_f32_16x16x32_bf16 v[28:31], v[160:163], v[204:207], v[28:31]
	v_mfma_f32_16x16x32_bf16 v[20:23], v[152:155], v[212:215], v[20:23]
	v_mfma_f32_16x16x32_bf16 v[12:15], v[160:163], v[212:215], v[12:15]
	v_mfma_f32_16x16x32_bf16 v[60:63], v[156:159], v[192:195], v[60:63]
	v_mfma_f32_16x16x32_bf16 v[56:59], v[164:167], v[192:195], v[56:59]
	v_mfma_f32_16x16x32_bf16 v[52:55], v[156:159], v[200:203], v[52:55]
	v_mfma_f32_16x16x32_bf16 v[44:47], v[164:167], v[200:203], v[44:47]
	v_mfma_f32_16x16x32_bf16 v[36:39], v[156:159], v[208:211], v[36:39]
	v_mfma_f32_16x16x32_bf16 v[28:31], v[164:167], v[208:211], v[28:31]
	v_mfma_f32_16x16x32_bf16 v[20:23], v[156:159], v[216:219], v[20:23]
	v_mfma_f32_16x16x32_bf16 v[12:15], v[164:167], v[216:219], v[12:15]
	s_setprio 0
	s_setprio 1
	v_mfma_f32_16x16x32_bf16 v[48:51], v[168:171], v[184:187], v[48:51]
	v_mfma_f32_16x16x32_bf16 v[40:43], v[176:179], v[184:187], v[40:43]
	v_mfma_f32_16x16x32_bf16 v[32:35], v[168:171], v[196:199], v[32:35]
	v_mfma_f32_16x16x32_bf16 v[24:27], v[176:179], v[196:199], v[24:27]
	v_mfma_f32_16x16x32_bf16 v[16:19], v[168:171], v[204:207], v[16:19]
	v_mfma_f32_16x16x32_bf16 v[8:11], v[176:179], v[204:207], v[8:11]
	v_mfma_f32_16x16x32_bf16 v[4:7], v[168:171], v[212:215], v[4:7]
	v_mfma_f32_16x16x32_bf16 v[0:3], v[176:179], v[212:215], v[0:3]
	v_mfma_f32_16x16x32_bf16 v[48:51], v[172:175], v[192:195], v[48:51]
	v_mfma_f32_16x16x32_bf16 v[40:43], v[180:183], v[192:195], v[40:43]
	v_mfma_f32_16x16x32_bf16 v[32:35], v[172:175], v[200:203], v[32:35]
	v_mfma_f32_16x16x32_bf16 v[24:27], v[180:183], v[200:203], v[24:27]
	v_mfma_f32_16x16x32_bf16 v[16:19], v[172:175], v[208:211], v[16:19]
	v_mfma_f32_16x16x32_bf16 v[8:11], v[180:183], v[208:211], v[8:11]
	v_mfma_f32_16x16x32_bf16 v[4:7], v[172:175], v[216:219], v[4:7]
	v_mfma_f32_16x16x32_bf16 v[0:3], v[180:183], v[216:219], v[0:3]
	s_setprio 0
	s_barrier
	s_add_i32 s83, 0, 0x18000
	s_add_i32 s84, 0, 0x1c000
	v_add_u32_e32 v164, s83, v147
	v_add_u32_e32 v180, s84, v147
	ds_read_b128 v[152:155], v164
	ds_read_b128 v[156:159], v164 offset:1024
	ds_read_b128 v[160:163], v164 offset:2048
	ds_read_b128 v[164:167], v164 offset:3072
	ds_read_b128 v[168:171], v180
	ds_read_b128 v[172:175], v180 offset:1024
	ds_read_b128 v[176:179], v180 offset:2048
	ds_read_b128 v[180:183], v180 offset:3072
	s_add_u32 s62, s62, 0x40000
	s_addc_u32 s63, s63, 0
	s_mov_b32 m0, s66
	ds_read_b128 v[184:187], v151 offset:32768
	ds_read_b128 v[192:195], v151 offset:33792
	ds_read_b128 v[196:199], v151 offset:34816
	ds_read_b128 v[200:203], v151 offset:35840
	ds_read_b128 v[204:207], v151 offset:36864
	ds_read_b128 v[208:211], v151 offset:37888
	ds_read_b128 v[212:215], v151 offset:38912
	ds_read_b128 v[216:219], v151 offset:39936
	global_load_lds_dwordx4 v128, s[62:63]
	s_mov_b32 m0, s67
	s_nop 0
	global_load_lds_dwordx4 v132, s[62:63]
	s_waitcnt vmcnt(8)
	s_waitcnt lgkmcnt(0)
	s_barrier
	s_setprio 1
	s_waitcnt lgkmcnt(0)
	v_mfma_f32_16x16x32_bf16 v[124:127], v[152:155], v[184:187], v[124:127]
	v_mfma_f32_16x16x32_bf16 v[120:123], v[160:163], v[184:187], v[120:123]
	v_mfma_f32_16x16x32_bf16 v[116:119], v[152:155], v[196:199], v[116:119]
	v_mfma_f32_16x16x32_bf16 v[108:111], v[160:163], v[196:199], v[108:111]
	v_mfma_f32_16x16x32_bf16 v[100:103], v[152:155], v[204:207], v[100:103]
	v_mfma_f32_16x16x32_bf16 v[92:95], v[160:163], v[204:207], v[92:95]
	v_mfma_f32_16x16x32_bf16 v[84:87], v[152:155], v[212:215], v[84:87]
	v_mfma_f32_16x16x32_bf16 v[76:79], v[160:163], v[212:215], v[76:79]
	v_mfma_f32_16x16x32_bf16 v[124:127], v[156:159], v[192:195], v[124:127]
	v_mfma_f32_16x16x32_bf16 v[120:123], v[164:167], v[192:195], v[120:123]
	v_mfma_f32_16x16x32_bf16 v[116:119], v[156:159], v[200:203], v[116:119]
	v_mfma_f32_16x16x32_bf16 v[108:111], v[164:167], v[200:203], v[108:111]
	v_mfma_f32_16x16x32_bf16 v[100:103], v[156:159], v[208:211], v[100:103]
	v_mfma_f32_16x16x32_bf16 v[92:95], v[164:167], v[208:211], v[92:95]
	v_mfma_f32_16x16x32_bf16 v[84:87], v[156:159], v[216:219], v[84:87]
	v_mfma_f32_16x16x32_bf16 v[76:79], v[164:167], v[216:219], v[76:79]
	s_setprio 0
	s_setprio 1
	v_mfma_f32_16x16x32_bf16 v[112:115], v[168:171], v[184:187], v[112:115]
	v_mfma_f32_16x16x32_bf16 v[104:107], v[176:179], v[184:187], v[104:107]
	v_mfma_f32_16x16x32_bf16 v[96:99], v[168:171], v[196:199], v[96:99]
	v_mfma_f32_16x16x32_bf16 v[88:91], v[176:179], v[196:199], v[88:91]
	v_mfma_f32_16x16x32_bf16 v[80:83], v[168:171], v[204:207], v[80:83]
	v_mfma_f32_16x16x32_bf16 v[72:75], v[176:179], v[204:207], v[72:75]
	v_mfma_f32_16x16x32_bf16 v[68:71], v[168:171], v[212:215], v[68:71]
	v_mfma_f32_16x16x32_bf16 v[64:67], v[176:179], v[212:215], v[64:67]
	v_mfma_f32_16x16x32_bf16 v[112:115], v[172:175], v[192:195], v[112:115]
	v_mfma_f32_16x16x32_bf16 v[104:107], v[180:183], v[192:195], v[104:107]
	v_mfma_f32_16x16x32_bf16 v[96:99], v[172:175], v[200:203], v[96:99]
	v_mfma_f32_16x16x32_bf16 v[88:91], v[180:183], v[200:203], v[88:91]
	v_mfma_f32_16x16x32_bf16 v[80:83], v[172:175], v[208:211], v[80:83]
	v_mfma_f32_16x16x32_bf16 v[72:75], v[180:183], v[208:211], v[72:75]
	v_mfma_f32_16x16x32_bf16 v[68:71], v[172:175], v[216:219], v[68:71]
	v_mfma_f32_16x16x32_bf16 v[64:67], v[180:183], v[216:219], v[64:67]
	s_setprio 0
	s_barrier
	s_add_i32 s62, s83, s65
	v_lshl_add_u64 v[144:145], v[144:145], 0, s[12:13]
	s_mov_b32 m0, s62
	ds_read_b128 v[184:187], v151 offset:49152
	ds_read_b128 v[192:195], v151 offset:50176
	ds_read_b128 v[196:199], v151 offset:51200
	ds_read_b128 v[200:203], v151 offset:52224
	ds_read_b128 v[204:207], v151 offset:53248
	ds_read_b128 v[208:211], v151 offset:54272
	ds_read_b128 v[212:215], v151 offset:55296
	ds_read_b128 v[216:219], v151 offset:56320
	global_load_lds_dwordx4 v[144:145], off
	s_add_i32 m0, s62, 0x2000
	s_add_u32 s60, s60, 0x40080
	v_lshl_add_u64 v[144:145], v[188:189], 0, s[12:13]
	s_addc_u32 s61, s61, 0
	s_add_i32 s62, s84, s65
	global_load_lds_dwordx4 v[144:145], off
	s_mov_b32 m0, s62
	s_nop 0
	global_load_lds_dwordx4 v130, s[60:61]
	s_add_i32 m0, s62, 0x2000
	s_nop 0
	global_load_lds_dwordx4 v134, s[60:61]
	v_lshl_add_u64 v[144:145], v[220:221], 0, s[12:13]
	s_mov_b32 m0, s69
	s_nop 0
	global_load_lds_dwordx4 v[144:145], off
	v_lshl_add_u64 v[144:145], v[222:223], 0, s[12:13]
	s_mov_b32 m0, s70
	s_nop 0
	global_load_lds_dwordx4 v[144:145], off
	s_waitcnt vmcnt(8)
	s_waitcnt lgkmcnt(0)
	s_barrier
	s_setprio 1
	s_waitcnt lgkmcnt(0)
	v_mfma_f32_16x16x32_bf16 v[60:63], v[152:155], v[184:187], v[60:63]
	v_mfma_f32_16x16x32_bf16 v[56:59], v[160:163], v[184:187], v[56:59]
	v_mfma_f32_16x16x32_bf16 v[52:55], v[152:155], v[196:199], v[52:55]
	v_mfma_f32_16x16x32_bf16 v[44:47], v[160:163], v[196:199], v[44:47]
	v_mfma_f32_16x16x32_bf16 v[36:39], v[152:155], v[204:207], v[36:39]
	v_mfma_f32_16x16x32_bf16 v[28:31], v[160:163], v[204:207], v[28:31]
	v_mfma_f32_16x16x32_bf16 v[20:23], v[152:155], v[212:215], v[20:23]
	v_mfma_f32_16x16x32_bf16 v[12:15], v[160:163], v[212:215], v[12:15]
	v_mfma_f32_16x16x32_bf16 v[60:63], v[156:159], v[192:195], v[60:63]
	v_mfma_f32_16x16x32_bf16 v[56:59], v[164:167], v[192:195], v[56:59]
	v_mfma_f32_16x16x32_bf16 v[52:55], v[156:159], v[200:203], v[52:55]
	v_mfma_f32_16x16x32_bf16 v[44:47], v[164:167], v[200:203], v[44:47]
	v_mfma_f32_16x16x32_bf16 v[36:39], v[156:159], v[208:211], v[36:39]
	v_mfma_f32_16x16x32_bf16 v[28:31], v[164:167], v[208:211], v[28:31]
	v_mfma_f32_16x16x32_bf16 v[20:23], v[156:159], v[216:219], v[20:23]
	v_mfma_f32_16x16x32_bf16 v[12:15], v[164:167], v[216:219], v[12:15]
	s_setprio 0
	s_setprio 1
	v_mfma_f32_16x16x32_bf16 v[48:51], v[168:171], v[184:187], v[48:51]
	v_mfma_f32_16x16x32_bf16 v[40:43], v[176:179], v[184:187], v[40:43]
	v_mfma_f32_16x16x32_bf16 v[32:35], v[168:171], v[196:199], v[32:35]
	v_mfma_f32_16x16x32_bf16 v[24:27], v[176:179], v[196:199], v[24:27]
	v_mfma_f32_16x16x32_bf16 v[16:19], v[168:171], v[204:207], v[16:19]
	v_mfma_f32_16x16x32_bf16 v[8:11], v[176:179], v[204:207], v[8:11]
	v_mfma_f32_16x16x32_bf16 v[4:7], v[168:171], v[212:215], v[4:7]
	v_mfma_f32_16x16x32_bf16 v[0:3], v[176:179], v[212:215], v[0:3]
	v_mfma_f32_16x16x32_bf16 v[48:51], v[172:175], v[192:195], v[48:51]
	v_mfma_f32_16x16x32_bf16 v[40:43], v[180:183], v[192:195], v[40:43]
	v_mfma_f32_16x16x32_bf16 v[32:35], v[172:175], v[200:203], v[32:35]
	v_mfma_f32_16x16x32_bf16 v[24:27], v[180:183], v[200:203], v[24:27]
	v_mfma_f32_16x16x32_bf16 v[16:19], v[172:175], v[208:211], v[16:19]
	v_mfma_f32_16x16x32_bf16 v[8:11], v[180:183], v[208:211], v[8:11]
	v_mfma_f32_16x16x32_bf16 v[4:7], v[172:175], v[216:219], v[4:7]
	v_mfma_f32_16x16x32_bf16 v[0:3], v[180:183], v[216:219], v[0:3]
	s_setprio 0
	s_barrier
	s_add_i32 s82, s82, 2
	s_add_u32 s42, s42, 0x100
	s_addc_u32 s43, s43, 0
	s_add_u32 s80, s80, 0x100
	s_addc_u32 s81, s81, 0
	s_cmp_gt_u32 s82, 13
	s_cbranch_scc0 .LBB0_1053
	s_and_b64 vcc, exec, s[14:15]
	s_cbranch_vccz .LBB0_1056
	s_barrier

.LBB0_1067:
	s_add_u32 s10, s46, 0x12000000
	s_addc_u32 s11, s47, 0
	s_lshl_b32 s5, s5, 5
	s_mov_b64 s[12:13], 0x80
	s_and_b32 s5, s5, 0x60
	s_add_i32 m0, s35, 0x18000
	v_lshl_add_u64 v[6:7], v[6:7], 0, s[12:13]
	s_lshl_b32 s18, s15, 13
	s_lshl_b32 s19, s5, 7
	s_waitcnt vmcnt(2)
	s_barrier
	global_load_lds_dwordx4 v[6:7], off
	v_lshl_add_u64 v[4:5], v[4:5], 0, s[12:13]
	s_add_i32 m0, s35, 0x1a000
	s_add_i32 s69, s35, 0x8000
	s_add_i32 s70, s35, 0xa000
	global_load_lds_dwordx4 v[4:5], off
	v_lshl_add_u64 v[0:1], v[0:1], 0, s[12:13]
	s_mov_b32 m0, s69
	s_add_u32 s16, s60, 0x40080
	global_load_lds_dwordx4 v[0:1], off
	v_lshl_add_u64 v[0:1], v[2:3], 0, s[12:13]
	s_mov_b32 m0, s70
	s_addc_u32 s17, s61, 0
	global_load_lds_dwordx4 v[0:1], off
	s_add_i32 m0, s35, 0x1c000
	s_nop 0
	global_load_lds_dwordx4 v130, s[16:17]
	s_add_i32 m0, s35, 0x1e000
	s_cmpk_lt_u32 s14, 0x100
	global_load_lds_dwordx4 v134, s[16:17]
	v_lshrrev_b32_e32 v1, 1, v8
	v_and_b32_e32 v1, 24, v1
	v_and_b32_e32 v0, 15, v8
	v_lshlrev_b32_e32 v2, 1, v1
	v_lshl_or_b32 v146, s15, 6, v0
	v_lshl_or_b32 v0, v0, 6, v2
	v_lshlrev_b32_e32 v2, 2, v8
	v_and_b32_e32 v2, 32, v2
	v_bitop3_b32 v3, v0, s18, v2 bitop3:0xde
	v_bitop3_b32 v147, v0, s19, v2 bitop3:0xde
	v_lshlrev_b32_e32 v0, 14, v9
	v_and_b32_e32 v0, 0xffff8000, v0
	v_or_b32_e32 v148, s5, v1
	v_lshl_add_u32 v0, v10, 11, v0
	v_and_b32_e32 v1, 1, v9
	v_lshl_or_b32 v0, v1, 6, v0
	v_lshl_add_u32 v136, v11, 1, v0
	v_lshlrev_b32_e32 v0, 14, v12
	v_and_b32_e32 v0, 0xffff8000, v0
	s_waitcnt vmcnt(6)
	v_lshl_add_u32 v0, v13, 11, v0
	v_and_b32_e32 v1, 1, v12
	s_cselect_b64 s[14:15], -1, 0
	v_lshl_or_b32 v0, v1, 6, v0
	s_add_i32 s72, 0, 0x10000
	s_add_i32 s73, 0, 0x14000
	s_sext_i32_i8 s54, s4
	s_ashr_i32 s71, s3, 31
	v_mov_b32_e32 v137, v131
	v_lshl_add_u32 v138, v14, 1, v0
	v_mov_b32_e32 v139, v131
	v_mov_b64_e32 v[140:141], 0x100
	v_mov_b64_e32 v[142:143], 0xff
	v_add_u32_e32 v149, s72, v147
	v_add_u32_e32 v150, s73, v147
	v_add_u32_e32 v151, 0, v3
	s_mov_b64 s[16:17], 0x20000
	s_mov_b32 s74, 0x20000
	s_mov_b64 s[18:19], 0x24000
	s_mov_b32 s75, 0x24000
	s_mov_b64 s[20:21], 0x28000
	s_mov_b32 s76, 0x28000
	s_mov_b64 s[22:23], 0x2c000
	s_mov_b32 s77, 0x2c000
	s_barrier
	s_branch .LBB0_1070

.LBB0_1212:
	s_add_u32 s10, s46, 0x16c00000
	s_addc_u32 s11, s47, 0
	s_lshl_b32 s1, s1, 5
	s_mov_b64 s[12:13], 0x80
	s_and_b32 s1, s1, 0x60
	s_add_i32 m0, s27, 0x18000
	v_lshl_add_u64 v[6:7], v[6:7], 0, s[12:13]
	s_lshl_b32 s18, s15, 13
	s_lshl_b32 s19, s1, 7
	s_waitcnt vmcnt(2)
	s_barrier
	global_load_lds_dwordx4 v[6:7], off
	v_lshl_add_u64 v[4:5], v[4:5], 0, s[12:13]
	s_add_i32 m0, s27, 0x1a000
	s_add_i32 s77, s27, 0x8000
	s_add_i32 s79, s27, 0xa000
	global_load_lds_dwordx4 v[4:5], off
	v_lshl_add_u64 v[0:1], v[0:1], 0, s[12:13]
	s_mov_b32 m0, s77
	s_add_u32 s16, s28, 0x10080
	global_load_lds_dwordx4 v[0:1], off
	v_lshl_add_u64 v[0:1], v[2:3], 0, s[12:13]
	s_mov_b32 m0, s79
	s_addc_u32 s17, s29, 0
	global_load_lds_dwordx4 v[0:1], off
	s_add_i32 m0, s27, 0x1c000
	s_nop 0
	global_load_lds_dwordx4 v130, s[16:17]
	s_add_i32 m0, s27, 0x1e000
	s_cmpk_lt_u32 s14, 0x100
	global_load_lds_dwordx4 v134, s[16:17]
	v_lshrrev_b32_e32 v1, 1, v8
	v_and_b32_e32 v1, 24, v1
	v_and_b32_e32 v0, 15, v8
	v_lshlrev_b32_e32 v2, 1, v1
	v_lshl_or_b32 v142, s15, 6, v0
	v_lshl_or_b32 v0, v0, 6, v2
	v_lshlrev_b32_e32 v2, 2, v8
	v_and_b32_e32 v2, 32, v2
	s_waitcnt vmcnt(6)
	v_bitop3_b32 v3, v0, s18, v2 bitop3:0xde
	v_bitop3_b32 v143, v0, s19, v2 bitop3:0xde
	s_cselect_b64 s[14:15], -1, 0
	s_add_i32 s81, 0, 0x10000
	s_add_i32 s82, 0, 0x14000
	s_sext_i32_i8 s54, s0
	s_ashr_i32 s80, s3, 31
	v_or_b32_e32 v144, s1, v1
	v_mov_b64_e32 v[136:137], 0x200
	v_mov_b64_e32 v[138:139], 0x1ff
	v_add_u32_e32 v145, s81, v143
	v_add_u32_e32 v146, s82, v143
	v_add_u32_e32 v147, 0, v3
	s_mov_b32 s83, 0x50000
	s_mov_b64 s[16:17], 0x58000
	s_mov_b32 s84, 0x58000
	s_barrier
	s_branch .LBB0_1215

.LBB0_1222:
	s_add_u32 s61, s30, s60
	s_addc_u32 s66, s31, 0
	s_add_u32 s64, s61, 0x100
	s_addc_u32 s65, s66, 0
	s_and_b64 s[62:63], s[42:43], exec
	s_cselect_b32 s63, s21, s65
	s_cselect_b32 s62, s55, s64
	s_add_u32 s60, s28, s60
	s_addc_u32 s64, s29, 0
	s_add_u32 s60, s60, 0x100
	s_addc_u32 s64, s64, 0
	s_and_b64 s[42:43], s[42:43], exec
	s_cselect_b32 s65, s19, s64
	s_cselect_b32 s64, s85, s60
	s_add_u32 s68, s61, 0x10080
	ds_read_b128 v[148:151], v145
	ds_read_b128 v[152:155], v145 offset:1024
	ds_read_b128 v[156:159], v145 offset:2048
	ds_read_b128 v[160:163], v145 offset:3072
	ds_read_b128 v[164:167], v146
	ds_read_b128 v[168:171], v146 offset:1024
	ds_read_b128 v[172:175], v146 offset:2048
	ds_read_b128 v[176:179], v146 offset:3072
	s_addc_u32 s69, s66, 0
	s_add_i32 s95, s81, s73
	s_add_i32 m0, s27, 0xc000
	s_add_i32 s96, s27, 0xe000
	s_add_i32 s92, s95, 0x2000
	s_add_u32 s66, s64, 0x10000
	s_addc_u32 s67, s65, 0
	s_add_i32 s94, s82, s73
	s_add_i32 s93, s94, 0x2000
	s_add_i32 s91, 0, 0x18000
	s_add_i32 s90, 0, 0x1c000
	s_add_u32 s60, s62, 0x10000
	s_addc_u32 s61, s63, 0
	s_add_i32 s89, s91, s73
	s_add_i32 s87, s89, 0x2000
	s_add_u32 s42, s64, 0x10080
	s_addc_u32 s43, s65, 0
	s_add_i32 s88, s90, s73
	s_add_i32 s86, s88, 0x2000
	ds_read_b128 v[180:183], v147
	ds_read_b128 v[184:187], v147 offset:1024
	ds_read_b128 v[192:195], v147 offset:2048
	ds_read_b128 v[196:199], v147 offset:3072
	ds_read_b128 v[200:203], v147 offset:4096
	ds_read_b128 v[204:207], v147 offset:5120
	ds_read_b128 v[208:211], v147 offset:6144
	ds_read_b128 v[212:215], v147 offset:7168
	global_load_lds_dwordx4 v128, s[68:69]
	s_mov_b32 m0, s96
	s_nop 0
	global_load_lds_dwordx4 v132, s[68:69]
	s_waitcnt vmcnt(8)
	s_waitcnt lgkmcnt(0)
	s_barrier
	s_setprio 1
	s_waitcnt lgkmcnt(0)
	v_mfma_f32_16x16x32_bf16 v[124:127], v[148:151], v[180:183], v[124:127]
	v_mfma_f32_16x16x32_bf16 v[120:123], v[156:159], v[180:183], v[120:123]
	v_mfma_f32_16x16x32_bf16 v[116:119], v[148:151], v[192:195], v[116:119]
	v_mfma_f32_16x16x32_bf16 v[108:111], v[156:159], v[192:195], v[108:111]
	v_mfma_f32_16x16x32_bf16 v[100:103], v[148:151], v[200:203], v[100:103]
	v_mfma_f32_16x16x32_bf16 v[92:95], v[156:159], v[200:203], v[92:95]
	v_mfma_f32_16x16x32_bf16 v[84:87], v[148:151], v[208:211], v[84:87]
	v_mfma_f32_16x16x32_bf16 v[76:79], v[156:159], v[208:211], v[76:79]
	v_mfma_f32_16x16x32_bf16 v[124:127], v[152:155], v[184:187], v[124:127]
	v_mfma_f32_16x16x32_bf16 v[120:123], v[160:163], v[184:187], v[120:123]
	v_mfma_f32_16x16x32_bf16 v[116:119], v[152:155], v[196:199], v[116:119]
	v_mfma_f32_16x16x32_bf16 v[108:111], v[160:163], v[196:199], v[108:111]
	v_mfma_f32_16x16x32_bf16 v[100:103], v[152:155], v[204:207], v[100:103]
	v_mfma_f32_16x16x32_bf16 v[92:95], v[160:163], v[204:207], v[92:95]
	v_mfma_f32_16x16x32_bf16 v[84:87], v[152:155], v[212:215], v[84:87]
	v_mfma_f32_16x16x32_bf16 v[76:79], v[160:163], v[212:215], v[76:79]
	s_setprio 0
	s_setprio 1
	v_mfma_f32_16x16x32_bf16 v[112:115], v[164:167], v[180:183], v[112:115]
	v_mfma_f32_16x16x32_bf16 v[104:107], v[172:175], v[180:183], v[104:107]
	v_mfma_f32_16x16x32_bf16 v[96:99], v[164:167], v[192:195], v[96:99]
	v_mfma_f32_16x16x32_bf16 v[88:91], v[172:175], v[192:195], v[88:91]
	v_mfma_f32_16x16x32_bf16 v[80:83], v[164:167], v[200:203], v[80:83]
	v_mfma_f32_16x16x32_bf16 v[72:75], v[172:175], v[200:203], v[72:75]
	v_mfma_f32_16x16x32_bf16 v[68:71], v[164:167], v[208:211], v[68:71]
	v_mfma_f32_16x16x32_bf16 v[64:67], v[172:175], v[208:211], v[64:67]
	v_mfma_f32_16x16x32_bf16 v[112:115], v[168:171], v[184:187], v[112:115]
	v_mfma_f32_16x16x32_bf16 v[104:107], v[176:179], v[184:187], v[104:107]
	v_mfma_f32_16x16x32_bf16 v[96:99], v[168:171], v[196:199], v[96:99]
	v_mfma_f32_16x16x32_bf16 v[88:91], v[176:179], v[196:199], v[88:91]
	v_mfma_f32_16x16x32_bf16 v[80:83], v[168:171], v[204:207], v[80:83]
	v_mfma_f32_16x16x32_bf16 v[72:75], v[176:179], v[204:207], v[72:75]
	v_mfma_f32_16x16x32_bf16 v[68:71], v[168:171], v[212:215], v[68:71]
	v_mfma_f32_16x16x32_bf16 v[64:67], v[176:179], v[212:215], v[64:67]
	s_setprio 0
	s_barrier
	s_mov_b32 m0, s95
	v_lshl_add_u64 v[140:141], s[64:65], 0, v[130:131]
	ds_read_b128 v[180:183], v147 offset:16384
	ds_read_b128 v[184:187], v147 offset:17408
	ds_read_b128 v[192:195], v147 offset:18432
	ds_read_b128 v[196:199], v147 offset:19456
	ds_read_b128 v[200:203], v147 offset:20480
	ds_read_b128 v[204:207], v147 offset:21504
	ds_read_b128 v[208:211], v147 offset:22528
	ds_read_b128 v[212:215], v147 offset:23552
	global_load_lds_dwordx4 v[140:141], off
	v_lshl_add_u64 v[188:189], s[64:65], 0, v[134:135]
	s_mov_b32 m0, s92
	s_nop 0
	global_load_lds_dwordx4 v[188:189], off
	s_mov_b32 m0, s94
	v_lshl_add_u64 v[218:219], s[62:63], 0, v[132:133]
	global_load_lds_dwordx4 v130, s[66:67]
	s_mov_b32 m0, s93
	s_nop 0
	global_load_lds_dwordx4 v134, s[66:67]
	v_lshl_add_u64 v[216:217], s[62:63], 0, v[128:129]
	s_mov_b32 m0, s27
	s_nop 0
	global_load_lds_dwordx4 v[216:217], off
	s_mov_b32 m0, s33
	s_nop 0
	global_load_lds_dwordx4 v[218:219], off
	s_waitcnt vmcnt(8)
	s_waitcnt lgkmcnt(0)
	s_barrier
	s_setprio 1
	s_waitcnt lgkmcnt(0)
	v_mfma_f32_16x16x32_bf16 v[60:63], v[148:151], v[180:183], v[60:63]
	v_mfma_f32_16x16x32_bf16 v[56:59], v[156:159], v[180:183], v[56:59]
	v_mfma_f32_16x16x32_bf16 v[52:55], v[148:151], v[192:195], v[52:55]
	v_mfma_f32_16x16x32_bf16 v[44:47], v[156:159], v[192:195], v[44:47]
	v_mfma_f32_16x16x32_bf16 v[36:39], v[148:151], v[200:203], v[36:39]
	v_mfma_f32_16x16x32_bf16 v[28:31], v[156:159], v[200:203], v[28:31]
	v_mfma_f32_16x16x32_bf16 v[20:23], v[148:151], v[208:211], v[20:23]
	v_mfma_f32_16x16x32_bf16 v[12:15], v[156:159], v[208:211], v[12:15]
	v_mfma_f32_16x16x32_bf16 v[60:63], v[152:155], v[184:187], v[60:63]
	v_mfma_f32_16x16x32_bf16 v[56:59], v[160:163], v[184:187], v[56:59]
	v_mfma_f32_16x16x32_bf16 v[52:55], v[152:155], v[196:199], v[52:55]
	v_mfma_f32_16x16x32_bf16 v[44:47], v[160:163], v[196:199], v[44:47]
	v_mfma_f32_16x16x32_bf16 v[36:39], v[152:155], v[204:207], v[36:39]
	v_mfma_f32_16x16x32_bf16 v[28:31], v[160:163], v[204:207], v[28:31]
	v_mfma_f32_16x16x32_bf16 v[20:23], v[152:155], v[212:215], v[20:23]
	v_mfma_f32_16x16x32_bf16 v[12:15], v[160:163], v[212:215], v[12:15]
	s_setprio 0
	s_setprio 1
	v_mfma_f32_16x16x32_bf16 v[48:51], v[164:167], v[180:183], v[48:51]
	v_mfma_f32_16x16x32_bf16 v[40:43], v[172:175], v[180:183], v[40:43]
	v_mfma_f32_16x16x32_bf16 v[32:35], v[164:167], v[192:195], v[32:35]
	v_mfma_f32_16x16x32_bf16 v[24:27], v[172:175], v[192:195], v[24:27]
	v_mfma_f32_16x16x32_bf16 v[16:19], v[164:167], v[200:203], v[16:19]
	v_mfma_f32_16x16x32_bf16 v[8:11], v[172:175], v[200:203], v[8:11]
	v_mfma_f32_16x16x32_bf16 v[4:7], v[164:167], v[208:211], v[4:7]
	v_mfma_f32_16x16x32_bf16 v[0:3], v[172:175], v[208:211], v[0:3]
	v_mfma_f32_16x16x32_bf16 v[48:51], v[168:171], v[184:187], v[48:51]
	v_mfma_f32_16x16x32_bf16 v[40:43], v[176:179], v[184:187], v[40:43]
	v_mfma_f32_16x16x32_bf16 v[32:35], v[168:171], v[196:199], v[32:35]
	v_mfma_f32_16x16x32_bf16 v[24:27], v[176:179], v[196:199], v[24:27]
	v_mfma_f32_16x16x32_bf16 v[16:19], v[168:171], v[204:207], v[16:19]
	v_mfma_f32_16x16x32_bf16 v[8:11], v[176:179], v[204:207], v[8:11]
	v_mfma_f32_16x16x32_bf16 v[4:7], v[168:171], v[212:215], v[4:7]
	v_mfma_f32_16x16x32_bf16 v[0:3], v[176:179], v[212:215], v[0:3]
	s_setprio 0
	s_barrier
	v_add_u32_e32 v160, s91, v143
	v_add_u32_e32 v176, s90, v143
	ds_read_b128 v[148:151], v160
	ds_read_b128 v[152:155], v160 offset:1024
	ds_read_b128 v[156:159], v160 offset:2048
	ds_read_b128 v[160:163], v160 offset:3072
	ds_read_b128 v[164:167], v176
	ds_read_b128 v[168:171], v176 offset:1024
	ds_read_b128 v[172:175], v176 offset:2048
	ds_read_b128 v[176:179], v176 offset:3072
	s_mov_b32 m0, s74
	ds_read_b128 v[180:183], v147 offset:32768
	ds_read_b128 v[184:187], v147 offset:33792
	ds_read_b128 v[192:195], v147 offset:34816
	ds_read_b128 v[196:199], v147 offset:35840
	ds_read_b128 v[200:203], v147 offset:36864
	ds_read_b128 v[204:207], v147 offset:37888
	ds_read_b128 v[208:211], v147 offset:38912
	ds_read_b128 v[212:215], v147 offset:39936
	global_load_lds_dwordx4 v128, s[60:61]
	s_mov_b32 m0, s75
	s_nop 0
	global_load_lds_dwordx4 v132, s[60:61]
	s_waitcnt vmcnt(8)
	s_waitcnt lgkmcnt(0)
	s_barrier
	s_setprio 1
	s_waitcnt lgkmcnt(0)
	v_mfma_f32_16x16x32_bf16 v[124:127], v[148:151], v[180:183], v[124:127]
	v_mfma_f32_16x16x32_bf16 v[120:123], v[156:159], v[180:183], v[120:123]
	v_mfma_f32_16x16x32_bf16 v[116:119], v[148:151], v[192:195], v[116:119]
	v_mfma_f32_16x16x32_bf16 v[108:111], v[156:159], v[192:195], v[108:111]
	v_mfma_f32_16x16x32_bf16 v[100:103], v[148:151], v[200:203], v[100:103]
	v_mfma_f32_16x16x32_bf16 v[92:95], v[156:159], v[200:203], v[92:95]
	v_mfma_f32_16x16x32_bf16 v[84:87], v[148:151], v[208:211], v[84:87]
	v_mfma_f32_16x16x32_bf16 v[76:79], v[156:159], v[208:211], v[76:79]
	v_mfma_f32_16x16x32_bf16 v[124:127], v[152:155], v[184:187], v[124:127]
	v_mfma_f32_16x16x32_bf16 v[120:123], v[160:163], v[184:187], v[120:123]
	v_mfma_f32_16x16x32_bf16 v[116:119], v[152:155], v[196:199], v[116:119]
	v_mfma_f32_16x16x32_bf16 v[108:111], v[160:163], v[196:199], v[108:111]
	v_mfma_f32_16x16x32_bf16 v[100:103], v[152:155], v[204:207], v[100:103]
	v_mfma_f32_16x16x32_bf16 v[92:95], v[160:163], v[204:207], v[92:95]
	v_mfma_f32_16x16x32_bf16 v[84:87], v[152:155], v[212:215], v[84:87]
	v_mfma_f32_16x16x32_bf16 v[76:79], v[160:163], v[212:215], v[76:79]
	s_setprio 0
	s_setprio 1
	v_mfma_f32_16x16x32_bf16 v[112:115], v[164:167], v[180:183], v[112:115]
	v_mfma_f32_16x16x32_bf16 v[104:107], v[172:175], v[180:183], v[104:107]
	v_mfma_f32_16x16x32_bf16 v[96:99], v[164:167], v[192:195], v[96:99]
	v_mfma_f32_16x16x32_bf16 v[88:91], v[172:175], v[192:195], v[88:91]
	v_mfma_f32_16x16x32_bf16 v[80:83], v[164:167], v[200:203], v[80:83]
	v_mfma_f32_16x16x32_bf16 v[72:75], v[172:175], v[200:203], v[72:75]
	v_mfma_f32_16x16x32_bf16 v[68:71], v[164:167], v[208:211], v[68:71]
	v_mfma_f32_16x16x32_bf16 v[64:67], v[172:175], v[208:211], v[64:67]
	v_mfma_f32_16x16x32_bf16 v[112:115], v[168:171], v[184:187], v[112:115]
	v_mfma_f32_16x16x32_bf16 v[104:107], v[176:179], v[184:187], v[104:107]
	v_mfma_f32_16x16x32_bf16 v[96:99], v[168:171], v[196:199], v[96:99]
	v_mfma_f32_16x16x32_bf16 v[88:91], v[176:179], v[196:199], v[88:91]
	v_mfma_f32_16x16x32_bf16 v[80:83], v[168:171], v[204:207], v[80:83]
	v_mfma_f32_16x16x32_bf16 v[72:75], v[176:179], v[204:207], v[72:75]
	v_mfma_f32_16x16x32_bf16 v[68:71], v[168:171], v[212:215], v[68:71]
	v_mfma_f32_16x16x32_bf16 v[64:67], v[176:179], v[212:215], v[64:67]
	s_setprio 0
	s_barrier
	s_mov_b32 m0, s89
	v_lshl_add_u64 v[140:141], v[140:141], 0, s[12:13]
	ds_read_b128 v[180:183], v147 offset:49152
	ds_read_b128 v[184:187], v147 offset:50176
	ds_read_b128 v[192:195], v147 offset:51200
	ds_read_b128 v[196:199], v147 offset:52224
	ds_read_b128 v[200:203], v147 offset:53248
	ds_read_b128 v[204:207], v147 offset:54272
	ds_read_b128 v[208:211], v147 offset:55296
	ds_read_b128 v[212:215], v147 offset:56320
	global_load_lds_dwordx4 v[140:141], off
	v_lshl_add_u64 v[140:141], v[188:189], 0, s[12:13]
	s_mov_b32 m0, s87
	s_nop 0
	global_load_lds_dwordx4 v[140:141], off
	s_mov_b32 m0, s88
	s_nop 0
	global_load_lds_dwordx4 v130, s[42:43]
	s_mov_b32 m0, s86
	s_nop 0
	global_load_lds_dwordx4 v134, s[42:43]
	v_lshl_add_u64 v[140:141], v[216:217], 0, s[12:13]
	s_mov_b32 m0, s77
	s_nop 0
	global_load_lds_dwordx4 v[140:141], off
	v_lshl_add_u64 v[140:141], v[218:219], 0, s[12:13]
	s_mov_b32 m0, s79
	s_nop 0
	global_load_lds_dwordx4 v[140:141], off
	s_waitcnt vmcnt(8)
	s_waitcnt lgkmcnt(0)
	s_barrier
	s_setprio 1
	s_waitcnt lgkmcnt(0)
	v_mfma_f32_16x16x32_bf16 v[60:63], v[148:151], v[180:183], v[60:63]
	v_mfma_f32_16x16x32_bf16 v[56:59], v[156:159], v[180:183], v[56:59]
	v_mfma_f32_16x16x32_bf16 v[52:55], v[148:151], v[192:195], v[52:55]
	v_mfma_f32_16x16x32_bf16 v[44:47], v[156:159], v[192:195], v[44:47]
	v_mfma_f32_16x16x32_bf16 v[36:39], v[148:151], v[200:203], v[36:39]
	v_mfma_f32_16x16x32_bf16 v[28:31], v[156:159], v[200:203], v[28:31]
	v_mfma_f32_16x16x32_bf16 v[20:23], v[148:151], v[208:211], v[20:23]
	v_mfma_f32_16x16x32_bf16 v[12:15], v[156:159], v[208:211], v[12:15]
	v_mfma_f32_16x16x32_bf16 v[60:63], v[152:155], v[184:187], v[60:63]
	v_mfma_f32_16x16x32_bf16 v[56:59], v[160:163], v[184:187], v[56:59]
	v_mfma_f32_16x16x32_bf16 v[52:55], v[152:155], v[196:199], v[52:55]
	v_mfma_f32_16x16x32_bf16 v[44:47], v[160:163], v[196:199], v[44:47]
	v_mfma_f32_16x16x32_bf16 v[36:39], v[152:155], v[204:207], v[36:39]
	v_mfma_f32_16x16x32_bf16 v[28:31], v[160:163], v[204:207], v[28:31]
	v_mfma_f32_16x16x32_bf16 v[20:23], v[152:155], v[212:215], v[20:23]
	v_mfma_f32_16x16x32_bf16 v[12:15], v[160:163], v[212:215], v[12:15]
	s_setprio 0
	s_setprio 1
	v_mfma_f32_16x16x32_bf16 v[48:51], v[164:167], v[180:183], v[48:51]
	v_mfma_f32_16x16x32_bf16 v[40:43], v[172:175], v[180:183], v[40:43]
	v_mfma_f32_16x16x32_bf16 v[32:35], v[164:167], v[192:195], v[32:35]
	v_mfma_f32_16x16x32_bf16 v[24:27], v[172:175], v[192:195], v[24:27]
	v_mfma_f32_16x16x32_bf16 v[16:19], v[164:167], v[200:203], v[16:19]
	v_mfma_f32_16x16x32_bf16 v[8:11], v[172:175], v[200:203], v[8:11]
	v_mfma_f32_16x16x32_bf16 v[4:7], v[164:167], v[208:211], v[4:7]
	v_mfma_f32_16x16x32_bf16 v[0:3], v[172:175], v[208:211], v[0:3]
	v_mfma_f32_16x16x32_bf16 v[48:51], v[168:171], v[184:187], v[48:51]
	v_mfma_f32_16x16x32_bf16 v[40:43], v[176:179], v[184:187], v[40:43]
	v_mfma_f32_16x16x32_bf16 v[32:35], v[168:171], v[196:199], v[32:35]
	v_mfma_f32_16x16x32_bf16 v[24:27], v[176:179], v[196:199], v[24:27]
	v_mfma_f32_16x16x32_bf16 v[16:19], v[168:171], v[204:207], v[16:19]
	v_mfma_f32_16x16x32_bf16 v[8:11], v[176:179], v[204:207], v[8:11]
	v_mfma_f32_16x16x32_bf16 v[4:7], v[168:171], v[212:215], v[4:7]
	v_mfma_f32_16x16x32_bf16 v[0:3], v[176:179], v[212:215], v[0:3]
	s_setprio 0
	s_barrier
	s_movk_i32 s60, 0x100
	s_andn2_b64 vcc, exec, s[34:35]
	s_mov_b64 s[42:43], -1
	s_mov_b64 s[34:35], 0
	s_cbranch_vccz .LBB0_1222
	s_and_b64 vcc, exec, s[14:15]
	s_cbranch_vccz .LBB0_1225
	s_barrier

.LBB0_1236:
	s_add_u32 s8, s46, 0x1ac00000
	s_addc_u32 s9, s47, 0
	s_lshl_b32 s1, s1, 5
	s_mov_b64 s[10:11], 0x80
	s_and_b32 s1, s1, 0x60
	s_add_i32 m0, s27, 0x18000
	v_lshl_add_u64 v[6:7], v[6:7], 0, s[10:11]
	s_lshl_b32 s16, s13, 13
	s_lshl_b32 s17, s1, 7
	s_waitcnt vmcnt(2)
	s_barrier
	global_load_lds_dwordx4 v[6:7], off
	v_lshl_add_u64 v[4:5], v[4:5], 0, s[10:11]
	s_add_i32 m0, s27, 0x1a000
	s_add_i32 s77, s27, 0x8000
	s_add_i32 s79, s27, 0xa000
	global_load_lds_dwordx4 v[4:5], off
	v_lshl_add_u64 v[0:1], v[0:1], 0, s[10:11]
	s_mov_b32 m0, s77
	s_add_u32 s14, s28, 0x10080
	global_load_lds_dwordx4 v[0:1], off
	v_lshl_add_u64 v[0:1], v[2:3], 0, s[10:11]
	s_mov_b32 m0, s79
	s_addc_u32 s15, s29, 0
	global_load_lds_dwordx4 v[0:1], off
	s_add_i32 m0, s27, 0x1c000
	s_nop 0
	global_load_lds_dwordx4 v130, s[14:15]
	s_add_i32 m0, s27, 0x1e000
	s_cmpk_lt_u32 s12, 0x100
	global_load_lds_dwordx4 v134, s[14:15]
	v_lshrrev_b32_e32 v1, 1, v8
	v_and_b32_e32 v1, 24, v1
	v_and_b32_e32 v0, 15, v8
	v_lshlrev_b32_e32 v2, 1, v1
	v_lshl_or_b32 v142, s13, 6, v0
	v_lshl_or_b32 v0, v0, 6, v2
	v_lshlrev_b32_e32 v2, 2, v8
	v_and_b32_e32 v2, 32, v2
	s_waitcnt vmcnt(6)
	v_bitop3_b32 v3, v0, s16, v2 bitop3:0xde
	v_bitop3_b32 v143, v0, s17, v2 bitop3:0xde
	s_cselect_b64 s[12:13], -1, 0
	s_add_i32 s81, 0, 0x10000
	s_add_i32 s82, 0, 0x14000
	s_sext_i32_i16 s54, s0
	s_ashr_i32 s80, s3, 31
	v_or_b32_e32 v144, s1, v1
	v_mov_b64_e32 v[136:137], 0x200
	v_mov_b64_e32 v[138:139], 0x1ff
	v_add_u32_e32 v145, s81, v143
	v_add_u32_e32 v146, s82, v143
	v_add_u32_e32 v147, 0, v3
	s_mov_b32 s83, 0x990000
	s_mov_b64 s[14:15], 0xaa0000
	s_mov_b32 s84, 0xaa0000
	s_mov_b64 s[16:17], 0xbb0000
	s_mov_b32 s85, 0xbb0000
	s_barrier
	s_branch .LBB0_1239

.LBB0_1246:
	s_add_u32 s61, s30, s60
	s_addc_u32 s66, s31, 0
	s_add_u32 s64, s61, 0x100
	s_addc_u32 s65, s66, 0
	s_and_b64 s[62:63], s[42:43], exec
	s_cselect_b32 s63, s21, s65
	s_cselect_b32 s62, s55, s64
	s_add_u32 s60, s28, s60
	s_addc_u32 s64, s29, 0
	s_add_u32 s60, s60, 0x100
	s_addc_u32 s64, s64, 0
	s_and_b64 s[42:43], s[42:43], exec
	s_cselect_b32 s65, s19, s64
	s_cselect_b32 s64, s86, s60
	s_add_u32 s68, s61, 0x10080
	ds_read_b128 v[148:151], v145
	ds_read_b128 v[152:155], v145 offset:1024
	ds_read_b128 v[156:159], v145 offset:2048
	ds_read_b128 v[160:163], v145 offset:3072
	ds_read_b128 v[164:167], v146
	ds_read_b128 v[168:171], v146 offset:1024
	ds_read_b128 v[172:175], v146 offset:2048
	ds_read_b128 v[176:179], v146 offset:3072
	s_addc_u32 s69, s66, 0
	s_add_i32 s96, s81, s73
	s_add_i32 m0, s27, 0xc000
	s_add_i32 s97, s27, 0xe000
	s_add_i32 s93, s96, 0x2000
	s_add_u32 s66, s64, 0x10000
	s_addc_u32 s67, s65, 0
	s_add_i32 s95, s82, s73
	s_add_i32 s94, s95, 0x2000
	s_add_i32 s92, 0, 0x18000
	s_add_i32 s91, 0, 0x1c000
	s_add_u32 s60, s62, 0x10000
	s_addc_u32 s61, s63, 0
	s_add_i32 s90, s92, s73
	s_add_i32 s88, s90, 0x2000
	s_add_u32 s42, s64, 0x10080
	s_addc_u32 s43, s65, 0
	s_add_i32 s89, s91, s73
	s_add_i32 s87, s89, 0x2000
	ds_read_b128 v[180:183], v147
	ds_read_b128 v[184:187], v147 offset:1024
	ds_read_b128 v[192:195], v147 offset:2048
	ds_read_b128 v[196:199], v147 offset:3072
	ds_read_b128 v[200:203], v147 offset:4096
	ds_read_b128 v[204:207], v147 offset:5120
	ds_read_b128 v[208:211], v147 offset:6144
	ds_read_b128 v[212:215], v147 offset:7168
	global_load_lds_dwordx4 v128, s[68:69]
	s_mov_b32 m0, s97
	s_nop 0
	global_load_lds_dwordx4 v132, s[68:69]
	s_waitcnt vmcnt(8)
	s_waitcnt lgkmcnt(0)
	s_barrier
	s_setprio 1
	s_waitcnt lgkmcnt(0)
	v_mfma_f32_16x16x32_bf16 v[124:127], v[148:151], v[180:183], v[124:127]
	v_mfma_f32_16x16x32_bf16 v[120:123], v[156:159], v[180:183], v[120:123]
	v_mfma_f32_16x16x32_bf16 v[116:119], v[148:151], v[192:195], v[116:119]
	v_mfma_f32_16x16x32_bf16 v[108:111], v[156:159], v[192:195], v[108:111]
	v_mfma_f32_16x16x32_bf16 v[100:103], v[148:151], v[200:203], v[100:103]
	v_mfma_f32_16x16x32_bf16 v[92:95], v[156:159], v[200:203], v[92:95]
	v_mfma_f32_16x16x32_bf16 v[84:87], v[148:151], v[208:211], v[84:87]
	v_mfma_f32_16x16x32_bf16 v[76:79], v[156:159], v[208:211], v[76:79]
	v_mfma_f32_16x16x32_bf16 v[124:127], v[152:155], v[184:187], v[124:127]
	v_mfma_f32_16x16x32_bf16 v[120:123], v[160:163], v[184:187], v[120:123]
	v_mfma_f32_16x16x32_bf16 v[116:119], v[152:155], v[196:199], v[116:119]
	v_mfma_f32_16x16x32_bf16 v[108:111], v[160:163], v[196:199], v[108:111]
	v_mfma_f32_16x16x32_bf16 v[100:103], v[152:155], v[204:207], v[100:103]
	v_mfma_f32_16x16x32_bf16 v[92:95], v[160:163], v[204:207], v[92:95]
	v_mfma_f32_16x16x32_bf16 v[84:87], v[152:155], v[212:215], v[84:87]
	v_mfma_f32_16x16x32_bf16 v[76:79], v[160:163], v[212:215], v[76:79]
	s_setprio 0
	s_setprio 1
	v_mfma_f32_16x16x32_bf16 v[112:115], v[164:167], v[180:183], v[112:115]
	v_mfma_f32_16x16x32_bf16 v[104:107], v[172:175], v[180:183], v[104:107]
	v_mfma_f32_16x16x32_bf16 v[96:99], v[164:167], v[192:195], v[96:99]
	v_mfma_f32_16x16x32_bf16 v[88:91], v[172:175], v[192:195], v[88:91]
	v_mfma_f32_16x16x32_bf16 v[80:83], v[164:167], v[200:203], v[80:83]
	v_mfma_f32_16x16x32_bf16 v[72:75], v[172:175], v[200:203], v[72:75]
	v_mfma_f32_16x16x32_bf16 v[68:71], v[164:167], v[208:211], v[68:71]
	v_mfma_f32_16x16x32_bf16 v[64:67], v[172:175], v[208:211], v[64:67]
	v_mfma_f32_16x16x32_bf16 v[112:115], v[168:171], v[184:187], v[112:115]
	v_mfma_f32_16x16x32_bf16 v[104:107], v[176:179], v[184:187], v[104:107]
	v_mfma_f32_16x16x32_bf16 v[96:99], v[168:171], v[196:199], v[96:99]
	v_mfma_f32_16x16x32_bf16 v[88:91], v[176:179], v[196:199], v[88:91]
	v_mfma_f32_16x16x32_bf16 v[80:83], v[168:171], v[204:207], v[80:83]
	v_mfma_f32_16x16x32_bf16 v[72:75], v[176:179], v[204:207], v[72:75]
	v_mfma_f32_16x16x32_bf16 v[68:71], v[168:171], v[212:215], v[68:71]
	v_mfma_f32_16x16x32_bf16 v[64:67], v[176:179], v[212:215], v[64:67]
	s_setprio 0
	s_barrier
	s_mov_b32 m0, s96
	v_lshl_add_u64 v[140:141], s[64:65], 0, v[130:131]
	ds_read_b128 v[180:183], v147 offset:16384
	ds_read_b128 v[184:187], v147 offset:17408
	ds_read_b128 v[192:195], v147 offset:18432
	ds_read_b128 v[196:199], v147 offset:19456
	ds_read_b128 v[200:203], v147 offset:20480
	ds_read_b128 v[204:207], v147 offset:21504
	ds_read_b128 v[208:211], v147 offset:22528
	ds_read_b128 v[212:215], v147 offset:23552
	global_load_lds_dwordx4 v[140:141], off
	v_lshl_add_u64 v[188:189], s[64:65], 0, v[134:135]
	s_mov_b32 m0, s93
	s_nop 0
	global_load_lds_dwordx4 v[188:189], off
	s_mov_b32 m0, s95
	v_lshl_add_u64 v[218:219], s[62:63], 0, v[132:133]
	global_load_lds_dwordx4 v130, s[66:67]
	s_mov_b32 m0, s94
	s_nop 0
	global_load_lds_dwordx4 v134, s[66:67]
	v_lshl_add_u64 v[216:217], s[62:63], 0, v[128:129]
	s_mov_b32 m0, s27
	s_nop 0
	global_load_lds_dwordx4 v[216:217], off
	s_mov_b32 m0, s33
	s_nop 0
	global_load_lds_dwordx4 v[218:219], off
	s_waitcnt vmcnt(8)
	s_waitcnt lgkmcnt(0)
	s_barrier
	s_setprio 1
	s_waitcnt lgkmcnt(0)
	v_mfma_f32_16x16x32_bf16 v[60:63], v[148:151], v[180:183], v[60:63]
	v_mfma_f32_16x16x32_bf16 v[56:59], v[156:159], v[180:183], v[56:59]
	v_mfma_f32_16x16x32_bf16 v[52:55], v[148:151], v[192:195], v[52:55]
	v_mfma_f32_16x16x32_bf16 v[44:47], v[156:159], v[192:195], v[44:47]
	v_mfma_f32_16x16x32_bf16 v[36:39], v[148:151], v[200:203], v[36:39]
	v_mfma_f32_16x16x32_bf16 v[28:31], v[156:159], v[200:203], v[28:31]
	v_mfma_f32_16x16x32_bf16 v[20:23], v[148:151], v[208:211], v[20:23]
	v_mfma_f32_16x16x32_bf16 v[12:15], v[156:159], v[208:211], v[12:15]
	v_mfma_f32_16x16x32_bf16 v[60:63], v[152:155], v[184:187], v[60:63]
	v_mfma_f32_16x16x32_bf16 v[56:59], v[160:163], v[184:187], v[56:59]
	v_mfma_f32_16x16x32_bf16 v[52:55], v[152:155], v[196:199], v[52:55]
	v_mfma_f32_16x16x32_bf16 v[44:47], v[160:163], v[196:199], v[44:47]
	v_mfma_f32_16x16x32_bf16 v[36:39], v[152:155], v[204:207], v[36:39]
	v_mfma_f32_16x16x32_bf16 v[28:31], v[160:163], v[204:207], v[28:31]
	v_mfma_f32_16x16x32_bf16 v[20:23], v[152:155], v[212:215], v[20:23]
	v_mfma_f32_16x16x32_bf16 v[12:15], v[160:163], v[212:215], v[12:15]
	s_setprio 0
	s_setprio 1
	v_mfma_f32_16x16x32_bf16 v[48:51], v[164:167], v[180:183], v[48:51]
	v_mfma_f32_16x16x32_bf16 v[40:43], v[172:175], v[180:183], v[40:43]
	v_mfma_f32_16x16x32_bf16 v[32:35], v[164:167], v[192:195], v[32:35]
	v_mfma_f32_16x16x32_bf16 v[24:27], v[172:175], v[192:195], v[24:27]
	v_mfma_f32_16x16x32_bf16 v[16:19], v[164:167], v[200:203], v[16:19]
	v_mfma_f32_16x16x32_bf16 v[8:11], v[172:175], v[200:203], v[8:11]
	v_mfma_f32_16x16x32_bf16 v[4:7], v[164:167], v[208:211], v[4:7]
	v_mfma_f32_16x16x32_bf16 v[0:3], v[172:175], v[208:211], v[0:3]
	v_mfma_f32_16x16x32_bf16 v[48:51], v[168:171], v[184:187], v[48:51]
	v_mfma_f32_16x16x32_bf16 v[40:43], v[176:179], v[184:187], v[40:43]
	v_mfma_f32_16x16x32_bf16 v[32:35], v[168:171], v[196:199], v[32:35]
	v_mfma_f32_16x16x32_bf16 v[24:27], v[176:179], v[196:199], v[24:27]
	v_mfma_f32_16x16x32_bf16 v[16:19], v[168:171], v[204:207], v[16:19]
	v_mfma_f32_16x16x32_bf16 v[8:11], v[176:179], v[204:207], v[8:11]
	v_mfma_f32_16x16x32_bf16 v[4:7], v[168:171], v[212:215], v[4:7]
	v_mfma_f32_16x16x32_bf16 v[0:3], v[176:179], v[212:215], v[0:3]
	s_setprio 0
	s_barrier
	v_add_u32_e32 v160, s92, v143
	v_add_u32_e32 v176, s91, v143
	ds_read_b128 v[148:151], v160
	ds_read_b128 v[152:155], v160 offset:1024
	ds_read_b128 v[156:159], v160 offset:2048
	ds_read_b128 v[160:163], v160 offset:3072
	ds_read_b128 v[164:167], v176
	ds_read_b128 v[168:171], v176 offset:1024
	ds_read_b128 v[172:175], v176 offset:2048
	ds_read_b128 v[176:179], v176 offset:3072
	s_mov_b32 m0, s74
	ds_read_b128 v[180:183], v147 offset:32768
	ds_read_b128 v[184:187], v147 offset:33792
	ds_read_b128 v[192:195], v147 offset:34816
	ds_read_b128 v[196:199], v147 offset:35840
	ds_read_b128 v[200:203], v147 offset:36864
	ds_read_b128 v[204:207], v147 offset:37888
	ds_read_b128 v[208:211], v147 offset:38912
	ds_read_b128 v[212:215], v147 offset:39936
	global_load_lds_dwordx4 v128, s[60:61]
	s_mov_b32 m0, s75
	s_nop 0
	global_load_lds_dwordx4 v132, s[60:61]
	s_waitcnt vmcnt(8)
	s_waitcnt lgkmcnt(0)
	s_barrier
	s_setprio 1
	s_waitcnt lgkmcnt(0)
	v_mfma_f32_16x16x32_bf16 v[124:127], v[148:151], v[180:183], v[124:127]
	v_mfma_f32_16x16x32_bf16 v[120:123], v[156:159], v[180:183], v[120:123]
	v_mfma_f32_16x16x32_bf16 v[116:119], v[148:151], v[192:195], v[116:119]
	v_mfma_f32_16x16x32_bf16 v[108:111], v[156:159], v[192:195], v[108:111]
	v_mfma_f32_16x16x32_bf16 v[100:103], v[148:151], v[200:203], v[100:103]
	v_mfma_f32_16x16x32_bf16 v[92:95], v[156:159], v[200:203], v[92:95]
	v_mfma_f32_16x16x32_bf16 v[84:87], v[148:151], v[208:211], v[84:87]
	v_mfma_f32_16x16x32_bf16 v[76:79], v[156:159], v[208:211], v[76:79]
	v_mfma_f32_16x16x32_bf16 v[124:127], v[152:155], v[184:187], v[124:127]
	v_mfma_f32_16x16x32_bf16 v[120:123], v[160:163], v[184:187], v[120:123]
	v_mfma_f32_16x16x32_bf16 v[116:119], v[152:155], v[196:199], v[116:119]
	v_mfma_f32_16x16x32_bf16 v[108:111], v[160:163], v[196:199], v[108:111]
	v_mfma_f32_16x16x32_bf16 v[100:103], v[152:155], v[204:207], v[100:103]
	v_mfma_f32_16x16x32_bf16 v[92:95], v[160:163], v[204:207], v[92:95]
	v_mfma_f32_16x16x32_bf16 v[84:87], v[152:155], v[212:215], v[84:87]
	v_mfma_f32_16x16x32_bf16 v[76:79], v[160:163], v[212:215], v[76:79]
	s_setprio 0
	s_setprio 1
	v_mfma_f32_16x16x32_bf16 v[112:115], v[164:167], v[180:183], v[112:115]
	v_mfma_f32_16x16x32_bf16 v[104:107], v[172:175], v[180:183], v[104:107]
	v_mfma_f32_16x16x32_bf16 v[96:99], v[164:167], v[192:195], v[96:99]
	v_mfma_f32_16x16x32_bf16 v[88:91], v[172:175], v[192:195], v[88:91]
	v_mfma_f32_16x16x32_bf16 v[80:83], v[164:167], v[200:203], v[80:83]
	v_mfma_f32_16x16x32_bf16 v[72:75], v[172:175], v[200:203], v[72:75]
	v_mfma_f32_16x16x32_bf16 v[68:71], v[164:167], v[208:211], v[68:71]
	v_mfma_f32_16x16x32_bf16 v[64:67], v[172:175], v[208:211], v[64:67]
	v_mfma_f32_16x16x32_bf16 v[112:115], v[168:171], v[184:187], v[112:115]
	v_mfma_f32_16x16x32_bf16 v[104:107], v[176:179], v[184:187], v[104:107]
	v_mfma_f32_16x16x32_bf16 v[96:99], v[168:171], v[196:199], v[96:99]
	v_mfma_f32_16x16x32_bf16 v[88:91], v[176:179], v[196:199], v[88:91]
	v_mfma_f32_16x16x32_bf16 v[80:83], v[168:171], v[204:207], v[80:83]
	v_mfma_f32_16x16x32_bf16 v[72:75], v[176:179], v[204:207], v[72:75]
	v_mfma_f32_16x16x32_bf16 v[68:71], v[168:171], v[212:215], v[68:71]
	v_mfma_f32_16x16x32_bf16 v[64:67], v[176:179], v[212:215], v[64:67]
	s_setprio 0
	s_barrier
	s_mov_b32 m0, s90
	v_lshl_add_u64 v[140:141], v[140:141], 0, s[10:11]
	ds_read_b128 v[180:183], v147 offset:49152
	ds_read_b128 v[184:187], v147 offset:50176
	ds_read_b128 v[192:195], v147 offset:51200
	ds_read_b128 v[196:199], v147 offset:52224
	ds_read_b128 v[200:203], v147 offset:53248
	ds_read_b128 v[204:207], v147 offset:54272
	ds_read_b128 v[208:211], v147 offset:55296
	ds_read_b128 v[212:215], v147 offset:56320
	global_load_lds_dwordx4 v[140:141], off
	v_lshl_add_u64 v[140:141], v[188:189], 0, s[10:11]
	s_mov_b32 m0, s88
	s_nop 0
	global_load_lds_dwordx4 v[140:141], off
	s_mov_b32 m0, s89
	s_nop 0
	global_load_lds_dwordx4 v130, s[42:43]
	s_mov_b32 m0, s87
	s_nop 0
	global_load_lds_dwordx4 v134, s[42:43]
	v_lshl_add_u64 v[140:141], v[216:217], 0, s[10:11]
	s_mov_b32 m0, s77
	s_nop 0
	global_load_lds_dwordx4 v[140:141], off
	v_lshl_add_u64 v[140:141], v[218:219], 0, s[10:11]
	s_mov_b32 m0, s79
	s_nop 0
	global_load_lds_dwordx4 v[140:141], off
	s_waitcnt vmcnt(8)
	s_waitcnt lgkmcnt(0)
	s_barrier
	s_setprio 1
	s_waitcnt lgkmcnt(0)
	v_mfma_f32_16x16x32_bf16 v[60:63], v[148:151], v[180:183], v[60:63]
	v_mfma_f32_16x16x32_bf16 v[56:59], v[156:159], v[180:183], v[56:59]
	v_mfma_f32_16x16x32_bf16 v[52:55], v[148:151], v[192:195], v[52:55]
	v_mfma_f32_16x16x32_bf16 v[44:47], v[156:159], v[192:195], v[44:47]
	v_mfma_f32_16x16x32_bf16 v[36:39], v[148:151], v[200:203], v[36:39]
	v_mfma_f32_16x16x32_bf16 v[28:31], v[156:159], v[200:203], v[28:31]
	v_mfma_f32_16x16x32_bf16 v[20:23], v[148:151], v[208:211], v[20:23]
	v_mfma_f32_16x16x32_bf16 v[12:15], v[156:159], v[208:211], v[12:15]
	v_mfma_f32_16x16x32_bf16 v[60:63], v[152:155], v[184:187], v[60:63]
	v_mfma_f32_16x16x32_bf16 v[56:59], v[160:163], v[184:187], v[56:59]
	v_mfma_f32_16x16x32_bf16 v[52:55], v[152:155], v[196:199], v[52:55]
	v_mfma_f32_16x16x32_bf16 v[44:47], v[160:163], v[196:199], v[44:47]
	v_mfma_f32_16x16x32_bf16 v[36:39], v[152:155], v[204:207], v[36:39]
	v_mfma_f32_16x16x32_bf16 v[28:31], v[160:163], v[204:207], v[28:31]
	v_mfma_f32_16x16x32_bf16 v[20:23], v[152:155], v[212:215], v[20:23]
	v_mfma_f32_16x16x32_bf16 v[12:15], v[160:163], v[212:215], v[12:15]
	s_setprio 0
	s_setprio 1
	v_mfma_f32_16x16x32_bf16 v[48:51], v[164:167], v[180:183], v[48:51]
	v_mfma_f32_16x16x32_bf16 v[40:43], v[172:175], v[180:183], v[40:43]
	v_mfma_f32_16x16x32_bf16 v[32:35], v[164:167], v[192:195], v[32:35]
	v_mfma_f32_16x16x32_bf16 v[24:27], v[172:175], v[192:195], v[24:27]
	v_mfma_f32_16x16x32_bf16 v[16:19], v[164:167], v[200:203], v[16:19]
	v_mfma_f32_16x16x32_bf16 v[8:11], v[172:175], v[200:203], v[8:11]
	v_mfma_f32_16x16x32_bf16 v[4:7], v[164:167], v[208:211], v[4:7]
	v_mfma_f32_16x16x32_bf16 v[0:3], v[172:175], v[208:211], v[0:3]
	v_mfma_f32_16x16x32_bf16 v[48:51], v[168:171], v[184:187], v[48:51]
	v_mfma_f32_16x16x32_bf16 v[40:43], v[176:179], v[184:187], v[40:43]
	v_mfma_f32_16x16x32_bf16 v[32:35], v[168:171], v[196:199], v[32:35]
	v_mfma_f32_16x16x32_bf16 v[24:27], v[176:179], v[196:199], v[24:27]
	v_mfma_f32_16x16x32_bf16 v[16:19], v[168:171], v[204:207], v[16:19]
	v_mfma_f32_16x16x32_bf16 v[8:11], v[176:179], v[204:207], v[8:11]
	v_mfma_f32_16x16x32_bf16 v[4:7], v[168:171], v[212:215], v[4:7]
	v_mfma_f32_16x16x32_bf16 v[0:3], v[176:179], v[212:215], v[0:3]
	s_setprio 0
	s_barrier
	s_movk_i32 s60, 0x100
	s_andn2_b64 vcc, exec, s[34:35]
	s_mov_b64 s[42:43], -1
	s_mov_b64 s[34:35], 0
	s_cbranch_vccz .LBB0_1246
	s_and_b64 vcc, exec, s[12:13]
	s_cbranch_vccz .LBB0_1249
	s_barrier

.LBB0_1256:
	s_lshl_b32 s5, s5, 5
	s_mov_b64 s[10:11], 0x80
	s_and_b32 s20, s5, 0x60
	s_add_i32 m0, s31, 0x18000
	v_lshl_add_u64 v[6:7], v[6:7], 0, s[10:11]
	s_lshl_b32 s13, s4, 13
	s_lshl_b32 s5, s20, 7
	s_waitcnt vmcnt(2)
	s_barrier
	global_load_lds_dwordx4 v[6:7], off
	v_lshl_add_u64 v[4:5], v[4:5], 0, s[10:11]
	s_add_i32 m0, s31, 0x1a000
	s_add_i32 s43, s31, 0x8000
	s_add_i32 s52, s31, 0xa000
	global_load_lds_dwordx4 v[4:5], off
	v_lshl_add_u64 v[0:1], v[0:1], 0, s[10:11]
	s_mov_b32 m0, s43
	s_add_u32 s14, s18, 0x18080
	global_load_lds_dwordx4 v[0:1], off
	v_lshl_add_u64 v[0:1], v[2:3], 0, s[10:11]
	s_mov_b32 m0, s52
	s_addc_u32 s15, s19, 0
	global_load_lds_dwordx4 v[0:1], off
	s_add_i32 m0, s31, 0x1c000
	s_nop 0
	global_load_lds_dwordx4 v132, s[14:15]
	s_add_i32 m0, s31, 0x1e000
	s_cmpk_lt_u32 s0, 0x100
	global_load_lds_dwordx4 v128, s[14:15]
	v_lshrrev_b32_e32 v1, 1, v9
	v_and_b32_e32 v1, 24, v1
	v_and_b32_e32 v0, 15, v9
	v_lshlrev_b32_e32 v2, 1, v1
	v_lshl_or_b32 v148, s4, 6, v0
	v_lshl_or_b32 v0, v0, 6, v2
	v_lshlrev_b32_e32 v2, 2, v9
	v_and_b32_e32 v2, 32, v2
	v_bitop3_b32 v3, v0, s13, v2 bitop3:0xde
	v_bitop3_b32 v149, v0, s5, v2 bitop3:0xde
	v_or_b32_e32 v150, s20, v1
	v_lshrrev_b32_e32 v1, 1, v14
	v_mul_lo_u32 v0, v13, s1
	s_movk_i32 s0, 0x1800
	v_mad_u64_u32 v[0:1], s[14:15], v1, s0, v[0:1]
	v_or_b32_e32 v0, v0, v15
	s_mov_b64 s[4:5], 0x18080
	v_add_lshl_u32 v0, v0, v16, 1
	v_mov_b32_e32 v1, v133
	v_lshl_add_u64 v[136:137], v[0:1], 0, s[4:5]
	v_lshrrev_b32_e32 v1, 1, v8
	v_mul_lo_u32 v0, v10, s1
	v_mad_u64_u32 v[0:1], s[0:1], v1, s0, v[0:1]
	s_waitcnt vmcnt(6)
	v_or_b32_e32 v0, v0, v11
	s_sext_i32_i8 s64, s12
	s_cselect_b64 s[12:13], -1, 0
	v_add_lshl_u32 v0, v0, v12, 1
	v_mov_b32_e32 v1, v133
	s_add_i32 s60, 0, 0x10000
	s_add_i32 s61, 0, 0x14000
	s_ashr_i32 s53, s3, 31
	v_lshl_add_u64 v[138:139], v[0:1], 0, s[4:5]
	v_mov_b64_e32 v[140:141], 0x300
	v_mov_b64_e32 v[142:143], 0x2ff
	v_add_u32_e32 v151, s60, v149
	v_add_u32_e32 v152, s61, v149
	v_add_u32_e32 v153, 0, v3
	s_movk_i32 s62, 0xc00
	s_barrier
	s_branch .LBB0_1259

.LBB0_1266:
	ds_read_b128 v[144:147], v151
	ds_read_b128 v[154:157], v151 offset:1024
	ds_read_b128 v[158:161], v151 offset:2048
	ds_read_b128 v[162:165], v151 offset:3072
	ds_read_b128 v[166:169], v152
	ds_read_b128 v[170:173], v152 offset:1024
	ds_read_b128 v[174:177], v152 offset:2048
	ds_read_b128 v[178:181], v152 offset:3072
	s_add_u32 s18, s16, 0x100
	s_addc_u32 s19, s17, 0
	s_cmp_eq_u32 s67, 2
	s_cselect_b32 s23, s5, s19
	s_cselect_b32 s22, s4, s18
	s_cselect_b32 s21, s15, s66
	s_cselect_b32 s20, s14, s65
	v_lshl_add_u64 v[216:217], s[16:17], 0, v[136:137]
	s_add_i32 m0, s31, 0xc000
	ds_read_b128 v[182:185], v153
	ds_read_b128 v[186:189], v153 offset:1024
	ds_read_b128 v[192:195], v153 offset:2048
	ds_read_b128 v[196:199], v153 offset:3072
	ds_read_b128 v[200:203], v153 offset:4096
	ds_read_b128 v[204:207], v153 offset:5120
	ds_read_b128 v[208:211], v153 offset:6144
	ds_read_b128 v[212:215], v153 offset:7168
	global_load_lds_dwordx4 v[216:217], off
	v_lshl_add_u64 v[216:217], s[16:17], 0, v[138:139]
	s_add_i32 m0, s31, 0xe000
	s_nop 0
	global_load_lds_dwordx4 v[216:217], off
	s_waitcnt vmcnt(8)
	s_waitcnt lgkmcnt(0)
	s_barrier
	s_setprio 1
	s_waitcnt lgkmcnt(0)
	v_mfma_f32_16x16x32_bf16 v[124:127], v[144:147], v[182:185], v[124:127]
	v_mfma_f32_16x16x32_bf16 v[120:123], v[158:161], v[182:185], v[120:123]
	v_mfma_f32_16x16x32_bf16 v[116:119], v[144:147], v[192:195], v[116:119]
	v_mfma_f32_16x16x32_bf16 v[108:111], v[158:161], v[192:195], v[108:111]
	v_mfma_f32_16x16x32_bf16 v[100:103], v[144:147], v[200:203], v[100:103]
	v_mfma_f32_16x16x32_bf16 v[92:95], v[158:161], v[200:203], v[92:95]
	v_mfma_f32_16x16x32_bf16 v[84:87], v[144:147], v[208:211], v[84:87]
	v_mfma_f32_16x16x32_bf16 v[76:79], v[158:161], v[208:211], v[76:79]
	v_mfma_f32_16x16x32_bf16 v[124:127], v[154:157], v[186:189], v[124:127]
	v_mfma_f32_16x16x32_bf16 v[120:123], v[162:165], v[186:189], v[120:123]
	v_mfma_f32_16x16x32_bf16 v[116:119], v[154:157], v[196:199], v[116:119]
	v_mfma_f32_16x16x32_bf16 v[108:111], v[162:165], v[196:199], v[108:111]
	v_mfma_f32_16x16x32_bf16 v[100:103], v[154:157], v[204:207], v[100:103]
	v_mfma_f32_16x16x32_bf16 v[92:95], v[162:165], v[204:207], v[92:95]
	v_mfma_f32_16x16x32_bf16 v[84:87], v[154:157], v[212:215], v[84:87]
	v_mfma_f32_16x16x32_bf16 v[76:79], v[162:165], v[212:215], v[76:79]
	s_setprio 0
	s_setprio 1
	v_mfma_f32_16x16x32_bf16 v[112:115], v[166:169], v[182:185], v[112:115]
	v_mfma_f32_16x16x32_bf16 v[104:107], v[174:177], v[182:185], v[104:107]
	v_mfma_f32_16x16x32_bf16 v[96:99], v[166:169], v[192:195], v[96:99]
	v_mfma_f32_16x16x32_bf16 v[88:91], v[174:177], v[192:195], v[88:91]
	v_mfma_f32_16x16x32_bf16 v[80:83], v[166:169], v[200:203], v[80:83]
	v_mfma_f32_16x16x32_bf16 v[72:75], v[174:177], v[200:203], v[72:75]
	v_mfma_f32_16x16x32_bf16 v[68:71], v[166:169], v[208:211], v[68:71]
	v_mfma_f32_16x16x32_bf16 v[64:67], v[174:177], v[208:211], v[64:67]
	v_mfma_f32_16x16x32_bf16 v[112:115], v[170:173], v[186:189], v[112:115]
	v_mfma_f32_16x16x32_bf16 v[104:107], v[178:181], v[186:189], v[104:107]
	v_mfma_f32_16x16x32_bf16 v[96:99], v[170:173], v[196:199], v[96:99]
	v_mfma_f32_16x16x32_bf16 v[88:91], v[178:181], v[196:199], v[88:91]
	v_mfma_f32_16x16x32_bf16 v[80:83], v[170:173], v[204:207], v[80:83]
	v_mfma_f32_16x16x32_bf16 v[72:75], v[178:181], v[204:207], v[72:75]
	v_mfma_f32_16x16x32_bf16 v[68:71], v[170:173], v[212:215], v[68:71]
	v_mfma_f32_16x16x32_bf16 v[64:67], v[178:181], v[212:215], v[64:67]
	s_setprio 0
	s_barrier
	s_add_i32 s16, s60, s28
	v_lshl_add_u64 v[216:217], s[20:21], 0, v[132:133]
	s_mov_b32 m0, s16
	ds_read_b128 v[182:185], v153 offset:16384
	ds_read_b128 v[186:189], v153 offset:17408
	ds_read_b128 v[192:195], v153 offset:18432
	ds_read_b128 v[196:199], v153 offset:19456
	ds_read_b128 v[200:203], v153 offset:20480
	ds_read_b128 v[204:207], v153 offset:21504
	ds_read_b128 v[208:211], v153 offset:22528
	ds_read_b128 v[212:215], v153 offset:23552
	global_load_lds_dwordx4 v[216:217], off
	s_add_i32 m0, s16, 0x2000
	s_add_u32 s16, s20, 0x18000
	v_lshl_add_u64 v[218:219], s[20:21], 0, v[128:129]
	s_addc_u32 s17, s21, 0
	s_add_i32 s68, s61, s28
	global_load_lds_dwordx4 v[218:219], off
	s_mov_b32 m0, s68
	v_lshl_add_u64 v[222:223], s[22:23], 0, v[130:131]
	global_load_lds_dwordx4 v132, s[16:17]
	s_add_i32 m0, s68, 0x2000
	s_nop 0
	global_load_lds_dwordx4 v128, s[16:17]
	v_lshl_add_u64 v[220:221], s[22:23], 0, v[134:135]
	s_mov_b32 m0, s31
	s_nop 0
	global_load_lds_dwordx4 v[220:221], off
	s_mov_b32 m0, s33
	s_nop 0
	global_load_lds_dwordx4 v[222:223], off
	s_waitcnt vmcnt(8)
	s_waitcnt lgkmcnt(0)
	s_barrier
	s_setprio 1
	s_waitcnt lgkmcnt(0)
	v_mfma_f32_16x16x32_bf16 v[60:63], v[144:147], v[182:185], v[60:63]
	v_mfma_f32_16x16x32_bf16 v[56:59], v[158:161], v[182:185], v[56:59]
	v_mfma_f32_16x16x32_bf16 v[52:55], v[144:147], v[192:195], v[52:55]
	v_mfma_f32_16x16x32_bf16 v[44:47], v[158:161], v[192:195], v[44:47]
	v_mfma_f32_16x16x32_bf16 v[36:39], v[144:147], v[200:203], v[36:39]
	v_mfma_f32_16x16x32_bf16 v[28:31], v[158:161], v[200:203], v[28:31]
	v_mfma_f32_16x16x32_bf16 v[20:23], v[144:147], v[208:211], v[20:23]
	v_mfma_f32_16x16x32_bf16 v[12:15], v[158:161], v[208:211], v[12:15]
	v_mfma_f32_16x16x32_bf16 v[60:63], v[154:157], v[186:189], v[60:63]
	v_mfma_f32_16x16x32_bf16 v[56:59], v[162:165], v[186:189], v[56:59]
	v_mfma_f32_16x16x32_bf16 v[52:55], v[154:157], v[196:199], v[52:55]
	v_mfma_f32_16x16x32_bf16 v[44:47], v[162:165], v[196:199], v[44:47]
	v_mfma_f32_16x16x32_bf16 v[36:39], v[154:157], v[204:207], v[36:39]
	v_mfma_f32_16x16x32_bf16 v[28:31], v[162:165], v[204:207], v[28:31]
	v_mfma_f32_16x16x32_bf16 v[20:23], v[154:157], v[212:215], v[20:23]
	v_mfma_f32_16x16x32_bf16 v[12:15], v[162:165], v[212:215], v[12:15]
	s_setprio 0
	s_setprio 1
	v_mfma_f32_16x16x32_bf16 v[48:51], v[166:169], v[182:185], v[48:51]
	v_mfma_f32_16x16x32_bf16 v[40:43], v[174:177], v[182:185], v[40:43]
	v_mfma_f32_16x16x32_bf16 v[32:35], v[166:169], v[192:195], v[32:35]
	v_mfma_f32_16x16x32_bf16 v[24:27], v[174:177], v[192:195], v[24:27]
	v_mfma_f32_16x16x32_bf16 v[16:19], v[166:169], v[200:203], v[16:19]
	v_mfma_f32_16x16x32_bf16 v[8:11], v[174:177], v[200:203], v[8:11]
	v_mfma_f32_16x16x32_bf16 v[4:7], v[166:169], v[208:211], v[4:7]
	v_mfma_f32_16x16x32_bf16 v[0:3], v[174:177], v[208:211], v[0:3]
	v_mfma_f32_16x16x32_bf16 v[48:51], v[170:173], v[186:189], v[48:51]
	v_mfma_f32_16x16x32_bf16 v[40:43], v[178:181], v[186:189], v[40:43]
	v_mfma_f32_16x16x32_bf16 v[32:35], v[170:173], v[196:199], v[32:35]
	v_mfma_f32_16x16x32_bf16 v[24:27], v[178:181], v[196:199], v[24:27]
	v_mfma_f32_16x16x32_bf16 v[16:19], v[170:173], v[204:207], v[16:19]
	v_mfma_f32_16x16x32_bf16 v[8:11], v[178:181], v[204:207], v[8:11]
	v_mfma_f32_16x16x32_bf16 v[4:7], v[170:173], v[212:215], v[4:7]
	v_mfma_f32_16x16x32_bf16 v[0:3], v[178:181], v[212:215], v[0:3]
	s_setprio 0
	s_barrier
	s_add_i32 s68, 0, 0x18000
	s_add_i32 s69, 0, 0x1c000
	v_add_u32_e32 v162, s68, v149
	v_add_u32_e32 v178, s69, v149
	ds_read_b128 v[144:147], v162
	ds_read_b128 v[154:157], v162 offset:1024
	ds_read_b128 v[158:161], v162 offset:2048
	ds_read_b128 v[162:165], v162 offset:3072
	ds_read_b128 v[166:169], v178
	ds_read_b128 v[170:173], v178 offset:1024
	ds_read_b128 v[174:177], v178 offset:2048
	ds_read_b128 v[178:181], v178 offset:3072
	s_add_u32 s16, s22, 0x18000
	s_addc_u32 s17, s23, 0
	s_mov_b32 m0, s34
	ds_read_b128 v[182:185], v153 offset:32768
	ds_read_b128 v[186:189], v153 offset:33792
	ds_read_b128 v[192:195], v153 offset:34816
	ds_read_b128 v[196:199], v153 offset:35840
	ds_read_b128 v[200:203], v153 offset:36864
	ds_read_b128 v[204:207], v153 offset:37888
	ds_read_b128 v[208:211], v153 offset:38912
	ds_read_b128 v[212:215], v153 offset:39936
	global_load_lds_dwordx4 v134, s[16:17]
	s_mov_b32 m0, s35
	s_nop 0
	global_load_lds_dwordx4 v130, s[16:17]
	s_waitcnt vmcnt(8)
	s_waitcnt lgkmcnt(0)
	s_barrier
	s_setprio 1
	s_waitcnt lgkmcnt(0)
	v_mfma_f32_16x16x32_bf16 v[124:127], v[144:147], v[182:185], v[124:127]
	v_mfma_f32_16x16x32_bf16 v[120:123], v[158:161], v[182:185], v[120:123]
	v_mfma_f32_16x16x32_bf16 v[116:119], v[144:147], v[192:195], v[116:119]
	v_mfma_f32_16x16x32_bf16 v[108:111], v[158:161], v[192:195], v[108:111]
	v_mfma_f32_16x16x32_bf16 v[100:103], v[144:147], v[200:203], v[100:103]
	v_mfma_f32_16x16x32_bf16 v[92:95], v[158:161], v[200:203], v[92:95]
	v_mfma_f32_16x16x32_bf16 v[84:87], v[144:147], v[208:211], v[84:87]
	v_mfma_f32_16x16x32_bf16 v[76:79], v[158:161], v[208:211], v[76:79]
	v_mfma_f32_16x16x32_bf16 v[124:127], v[154:157], v[186:189], v[124:127]
	v_mfma_f32_16x16x32_bf16 v[120:123], v[162:165], v[186:189], v[120:123]
	v_mfma_f32_16x16x32_bf16 v[116:119], v[154:157], v[196:199], v[116:119]
	v_mfma_f32_16x16x32_bf16 v[108:111], v[162:165], v[196:199], v[108:111]
	v_mfma_f32_16x16x32_bf16 v[100:103], v[154:157], v[204:207], v[100:103]
	v_mfma_f32_16x16x32_bf16 v[92:95], v[162:165], v[204:207], v[92:95]
	v_mfma_f32_16x16x32_bf16 v[84:87], v[154:157], v[212:215], v[84:87]
	v_mfma_f32_16x16x32_bf16 v[76:79], v[162:165], v[212:215], v[76:79]
	s_setprio 0
	s_setprio 1
	v_mfma_f32_16x16x32_bf16 v[112:115], v[166:169], v[182:185], v[112:115]
	v_mfma_f32_16x16x32_bf16 v[104:107], v[174:177], v[182:185], v[104:107]
	v_mfma_f32_16x16x32_bf16 v[96:99], v[166:169], v[192:195], v[96:99]
	v_mfma_f32_16x16x32_bf16 v[88:91], v[174:177], v[192:195], v[88:91]
	v_mfma_f32_16x16x32_bf16 v[80:83], v[166:169], v[200:203], v[80:83]
	v_mfma_f32_16x16x32_bf16 v[72:75], v[174:177], v[200:203], v[72:75]
	v_mfma_f32_16x16x32_bf16 v[68:71], v[166:169], v[208:211], v[68:71]
	v_mfma_f32_16x16x32_bf16 v[64:67], v[174:177], v[208:211], v[64:67]
	v_mfma_f32_16x16x32_bf16 v[112:115], v[170:173], v[186:189], v[112:115]
	v_mfma_f32_16x16x32_bf16 v[104:107], v[178:181], v[186:189], v[104:107]
	v_mfma_f32_16x16x32_bf16 v[96:99], v[170:173], v[196:199], v[96:99]
	v_mfma_f32_16x16x32_bf16 v[88:91], v[178:181], v[196:199], v[88:91]
	v_mfma_f32_16x16x32_bf16 v[80:83], v[170:173], v[204:207], v[80:83]
	v_mfma_f32_16x16x32_bf16 v[72:75], v[178:181], v[204:207], v[72:75]
	v_mfma_f32_16x16x32_bf16 v[68:71], v[170:173], v[212:215], v[68:71]
	v_mfma_f32_16x16x32_bf16 v[64:67], v[178:181], v[212:215], v[64:67]
	s_setprio 0
	s_barrier
	s_add_i32 s16, s68, s28
	v_lshl_add_u64 v[216:217], v[216:217], 0, s[10:11]
	s_mov_b32 m0, s16
	ds_read_b128 v[182:185], v153 offset:49152
	ds_read_b128 v[186:189], v153 offset:50176
	ds_read_b128 v[192:195], v153 offset:51200
	ds_read_b128 v[196:199], v153 offset:52224
	ds_read_b128 v[200:203], v153 offset:53248
	ds_read_b128 v[204:207], v153 offset:54272
	ds_read_b128 v[208:211], v153 offset:55296
	ds_read_b128 v[212:215], v153 offset:56320
	global_load_lds_dwordx4 v[216:217], off
	s_add_i32 m0, s16, 0x2000
	s_add_u32 s16, s20, 0x18080
	v_lshl_add_u64 v[216:217], v[218:219], 0, s[10:11]
	s_addc_u32 s17, s21, 0
	s_add_i32 s20, s69, s28
	global_load_lds_dwordx4 v[216:217], off
	s_mov_b32 m0, s20
	s_nop 0
	global_load_lds_dwordx4 v132, s[16:17]
	s_add_i32 m0, s20, 0x2000
	s_nop 0
	global_load_lds_dwordx4 v128, s[16:17]
	v_lshl_add_u64 v[216:217], v[220:221], 0, s[10:11]
	s_mov_b32 m0, s43
	s_nop 0
	global_load_lds_dwordx4 v[216:217], off
	v_lshl_add_u64 v[216:217], v[222:223], 0, s[10:11]
	s_mov_b32 m0, s52
	s_nop 0
	global_load_lds_dwordx4 v[216:217], off
	s_waitcnt vmcnt(8)
	s_waitcnt lgkmcnt(0)
	s_barrier
	s_setprio 1
	s_waitcnt lgkmcnt(0)
	v_mfma_f32_16x16x32_bf16 v[60:63], v[144:147], v[182:185], v[60:63]
	v_mfma_f32_16x16x32_bf16 v[56:59], v[158:161], v[182:185], v[56:59]
	v_mfma_f32_16x16x32_bf16 v[52:55], v[144:147], v[192:195], v[52:55]
	v_mfma_f32_16x16x32_bf16 v[44:47], v[158:161], v[192:195], v[44:47]
	v_mfma_f32_16x16x32_bf16 v[36:39], v[144:147], v[200:203], v[36:39]
	v_mfma_f32_16x16x32_bf16 v[28:31], v[158:161], v[200:203], v[28:31]
	v_mfma_f32_16x16x32_bf16 v[20:23], v[144:147], v[208:211], v[20:23]
	v_mfma_f32_16x16x32_bf16 v[12:15], v[158:161], v[208:211], v[12:15]
	v_mfma_f32_16x16x32_bf16 v[60:63], v[154:157], v[186:189], v[60:63]
	v_mfma_f32_16x16x32_bf16 v[56:59], v[162:165], v[186:189], v[56:59]
	v_mfma_f32_16x16x32_bf16 v[52:55], v[154:157], v[196:199], v[52:55]
	v_mfma_f32_16x16x32_bf16 v[44:47], v[162:165], v[196:199], v[44:47]
	v_mfma_f32_16x16x32_bf16 v[36:39], v[154:157], v[204:207], v[36:39]
	v_mfma_f32_16x16x32_bf16 v[28:31], v[162:165], v[204:207], v[28:31]
	v_mfma_f32_16x16x32_bf16 v[20:23], v[154:157], v[212:215], v[20:23]
	v_mfma_f32_16x16x32_bf16 v[12:15], v[162:165], v[212:215], v[12:15]
	s_setprio 0
	s_setprio 1
	v_mfma_f32_16x16x32_bf16 v[48:51], v[166:169], v[182:185], v[48:51]
	v_mfma_f32_16x16x32_bf16 v[40:43], v[174:177], v[182:185], v[40:43]
	v_mfma_f32_16x16x32_bf16 v[32:35], v[166:169], v[192:195], v[32:35]
	v_mfma_f32_16x16x32_bf16 v[24:27], v[174:177], v[192:195], v[24:27]
	v_mfma_f32_16x16x32_bf16 v[16:19], v[166:169], v[200:203], v[16:19]
	v_mfma_f32_16x16x32_bf16 v[8:11], v[174:177], v[200:203], v[8:11]
	v_mfma_f32_16x16x32_bf16 v[4:7], v[166:169], v[208:211], v[4:7]
	v_mfma_f32_16x16x32_bf16 v[0:3], v[174:177], v[208:211], v[0:3]
	v_mfma_f32_16x16x32_bf16 v[48:51], v[170:173], v[186:189], v[48:51]
	v_mfma_f32_16x16x32_bf16 v[40:43], v[178:181], v[186:189], v[40:43]
	v_mfma_f32_16x16x32_bf16 v[32:35], v[170:173], v[196:199], v[32:35]
	v_mfma_f32_16x16x32_bf16 v[24:27], v[178:181], v[196:199], v[24:27]
	v_mfma_f32_16x16x32_bf16 v[16:19], v[170:173], v[204:207], v[16:19]
	v_mfma_f32_16x16x32_bf16 v[8:11], v[178:181], v[204:207], v[8:11]
	v_mfma_f32_16x16x32_bf16 v[4:7], v[170:173], v[212:215], v[4:7]
	v_mfma_f32_16x16x32_bf16 v[0:3], v[178:181], v[212:215], v[0:3]
	s_setprio 0
	s_barrier
	s_add_i32 s67, s67, 2
	s_add_u32 s65, s65, 0x100
	s_addc_u32 s66, s66, 0
	s_cmp_gt_u32 s67, 3
	s_mov_b64 s[16:17], s[18:19]
	s_cbranch_scc0 .LBB0_1266
	s_and_b64 vcc, exec, s[12:13]
	s_cbranch_vccz .LBB0_1269
	s_barrier

.LBB0_1424:
	s_lshl_b32 s1, s1, 5
	s_mov_b64 s[10:11], 0x80
	s_and_b32 s1, s1, 0x60
	s_add_i32 m0, s29, 0x18000
	v_lshl_add_u64 v[6:7], v[6:7], 0, s[10:11]
	s_lshl_b32 s16, s13, 13
	s_lshl_b32 s17, s1, 7
	s_waitcnt vmcnt(2)
	s_barrier
	global_load_lds_dwordx4 v[6:7], off
	v_lshl_add_u64 v[2:3], v[2:3], 0, s[10:11]
	s_add_i32 m0, s29, 0x1a000
	s_add_i32 s65, s29, 0x8000
	s_add_i32 s66, s29, 0xa000
	global_load_lds_dwordx4 v[2:3], off
	v_lshl_add_u64 v[0:1], v[0:1], 0, s[10:11]
	s_mov_b32 m0, s65
	s_add_u32 s14, s34, 0x40080
	global_load_lds_dwordx4 v[0:1], off
	v_lshl_add_u64 v[0:1], v[4:5], 0, s[10:11]
	s_mov_b32 m0, s66
	s_addc_u32 s15, s35, 0
	global_load_lds_dwordx4 v[0:1], off
	s_add_i32 m0, s29, 0x1c000
	s_nop 0
	global_load_lds_dwordx4 v130, s[14:15]
	s_add_i32 m0, s29, 0x1e000
	s_cmpk_lt_u32 s12, 0x100
	global_load_lds_dwordx4 v134, s[14:15]
	v_lshrrev_b32_e32 v1, 1, v8
	v_and_b32_e32 v1, 24, v1
	v_and_b32_e32 v0, 15, v8
	v_lshlrev_b32_e32 v2, 1, v1
	v_lshl_or_b32 v146, s13, 6, v0
	v_lshl_or_b32 v0, v0, 6, v2
	v_lshlrev_b32_e32 v2, 2, v8
	v_and_b32_e32 v2, 32, v2
	v_bitop3_b32 v3, v0, s16, v2 bitop3:0xde
	v_bitop3_b32 v147, v0, s17, v2 bitop3:0xde
	v_lshlrev_b32_e32 v0, 14, v9
	v_and_b32_e32 v0, 0xffff8000, v0
	v_or_b32_e32 v148, s1, v1
	v_lshl_add_u32 v0, v10, 11, v0
	v_and_b32_e32 v1, 1, v9
	v_lshl_or_b32 v0, v1, 6, v0
	v_lshl_add_u32 v136, v11, 1, v0
	v_lshlrev_b32_e32 v0, 14, v12
	v_and_b32_e32 v0, 0xffff8000, v0
	s_waitcnt vmcnt(6)
	v_lshl_add_u32 v0, v13, 11, v0
	v_and_b32_e32 v1, 1, v12
	s_cselect_b64 s[12:13], -1, 0
	v_lshl_or_b32 v0, v1, 6, v0
	s_add_i32 s68, 0, 0x10000
	s_add_i32 s69, 0, 0x14000
	s_sext_i32_i8 s54, s0
	s_ashr_i32 s67, s3, 31
	v_mov_b32_e32 v137, v131
	v_lshl_add_u32 v138, v14, 1, v0
	v_mov_b32_e32 v139, v131
	v_mov_b64_e32 v[140:141], 0x200
	v_mov_b64_e32 v[142:143], 0x1ff
	v_add_u32_e32 v149, s68, v147
	v_add_u32_e32 v150, s69, v147
	v_add_u32_e32 v151, 0, v3
	s_mov_b32 s70, 0x40000
	s_mov_b64 s[14:15], 0x48000
	s_mov_b32 s71, 0x48000
	s_mov_b64 s[16:17], 0x50000
	s_mov_b32 s72, 0x50000
	s_mov_b64 s[18:19], 0x58000
	s_mov_b32 s73, 0x58000
	s_barrier
	s_branch .LBB0_1427

.LBB0_1434:
	ds_read_b128 v[152:155], v149
	ds_read_b128 v[156:159], v149 offset:1024
	ds_read_b128 v[160:163], v149 offset:2048
	ds_read_b128 v[164:167], v149 offset:3072
	ds_read_b128 v[168:171], v150
	ds_read_b128 v[172:175], v150 offset:1024
	ds_read_b128 v[176:179], v150 offset:2048
	ds_read_b128 v[180:183], v150 offset:3072
	s_add_u32 s34, s30, 0xfffc0080
	s_addc_u32 s35, s31, -1
	s_cmp_eq_u32 s77, 12
	s_cselect_b32 s43, s23, s35
	s_cselect_b32 s42, s55, s34
	s_cselect_b32 s35, s21, s76
	s_cselect_b32 s34, s74, s75
	s_add_i32 m0, s29, 0xc000
	ds_read_b128 v[184:187], v151
	ds_read_b128 v[192:195], v151 offset:1024
	ds_read_b128 v[196:199], v151 offset:2048
	ds_read_b128 v[200:203], v151 offset:3072
	ds_read_b128 v[204:207], v151 offset:4096
	ds_read_b128 v[208:211], v151 offset:5120
	ds_read_b128 v[212:215], v151 offset:6144
	ds_read_b128 v[216:219], v151 offset:7168
	global_load_lds_dwordx4 v136, s[30:31]
	s_add_i32 m0, s29, 0xe000
	s_nop 0
	global_load_lds_dwordx4 v138, s[30:31]
	s_waitcnt vmcnt(8)
	s_waitcnt lgkmcnt(0)
	s_barrier
	s_setprio 1
	s_waitcnt lgkmcnt(0)
	v_mfma_f32_16x16x32_bf16 v[124:127], v[152:155], v[184:187], v[124:127]
	v_mfma_f32_16x16x32_bf16 v[120:123], v[160:163], v[184:187], v[120:123]
	v_mfma_f32_16x16x32_bf16 v[116:119], v[152:155], v[196:199], v[116:119]
	v_mfma_f32_16x16x32_bf16 v[108:111], v[160:163], v[196:199], v[108:111]
	v_mfma_f32_16x16x32_bf16 v[100:103], v[152:155], v[204:207], v[100:103]
	v_mfma_f32_16x16x32_bf16 v[92:95], v[160:163], v[204:207], v[92:95]
	v_mfma_f32_16x16x32_bf16 v[84:87], v[152:155], v[212:215], v[84:87]
	v_mfma_f32_16x16x32_bf16 v[76:79], v[160:163], v[212:215], v[76:79]
	v_mfma_f32_16x16x32_bf16 v[124:127], v[156:159], v[192:195], v[124:127]
	v_mfma_f32_16x16x32_bf16 v[120:123], v[164:167], v[192:195], v[120:123]
	v_mfma_f32_16x16x32_bf16 v[116:119], v[156:159], v[200:203], v[116:119]
	v_mfma_f32_16x16x32_bf16 v[108:111], v[164:167], v[200:203], v[108:111]
	v_mfma_f32_16x16x32_bf16 v[100:103], v[156:159], v[208:211], v[100:103]
	v_mfma_f32_16x16x32_bf16 v[92:95], v[164:167], v[208:211], v[92:95]
	v_mfma_f32_16x16x32_bf16 v[84:87], v[156:159], v[216:219], v[84:87]
	v_mfma_f32_16x16x32_bf16 v[76:79], v[164:167], v[216:219], v[76:79]
	s_setprio 0
	s_setprio 1
	v_mfma_f32_16x16x32_bf16 v[112:115], v[168:171], v[184:187], v[112:115]
	v_mfma_f32_16x16x32_bf16 v[104:107], v[176:179], v[184:187], v[104:107]
	v_mfma_f32_16x16x32_bf16 v[96:99], v[168:171], v[196:199], v[96:99]
	v_mfma_f32_16x16x32_bf16 v[88:91], v[176:179], v[196:199], v[88:91]
	v_mfma_f32_16x16x32_bf16 v[80:83], v[168:171], v[204:207], v[80:83]
	v_mfma_f32_16x16x32_bf16 v[72:75], v[176:179], v[204:207], v[72:75]
	v_mfma_f32_16x16x32_bf16 v[68:71], v[168:171], v[212:215], v[68:71]
	v_mfma_f32_16x16x32_bf16 v[64:67], v[176:179], v[212:215], v[64:67]
	v_mfma_f32_16x16x32_bf16 v[112:115], v[172:175], v[192:195], v[112:115]
	v_mfma_f32_16x16x32_bf16 v[104:107], v[180:183], v[192:195], v[104:107]
	v_mfma_f32_16x16x32_bf16 v[96:99], v[172:175], v[200:203], v[96:99]
	v_mfma_f32_16x16x32_bf16 v[88:91], v[180:183], v[200:203], v[88:91]
	v_mfma_f32_16x16x32_bf16 v[80:83], v[172:175], v[208:211], v[80:83]
	v_mfma_f32_16x16x32_bf16 v[72:75], v[180:183], v[208:211], v[72:75]
	v_mfma_f32_16x16x32_bf16 v[68:71], v[172:175], v[216:219], v[68:71]
	v_mfma_f32_16x16x32_bf16 v[64:67], v[180:183], v[216:219], v[64:67]
	s_setprio 0
	s_barrier
	s_add_i32 s79, s68, s61
	v_lshl_add_u64 v[144:145], s[34:35], 0, v[130:131]
	s_mov_b32 m0, s79
	ds_read_b128 v[184:187], v151 offset:16384
	ds_read_b128 v[192:195], v151 offset:17408
	ds_read_b128 v[196:199], v151 offset:18432
	ds_read_b128 v[200:203], v151 offset:19456
	ds_read_b128 v[204:207], v151 offset:20480
	ds_read_b128 v[208:211], v151 offset:21504
	ds_read_b128 v[212:215], v151 offset:22528
	ds_read_b128 v[216:219], v151 offset:23552
	global_load_lds_dwordx4 v[144:145], off
	s_add_i32 m0, s79, 0x2000
	s_add_u32 s80, s34, 0x40000
	v_lshl_add_u64 v[188:189], s[34:35], 0, v[134:135]
	s_addc_u32 s81, s35, 0
	s_add_i32 s79, s69, s61
	global_load_lds_dwordx4 v[188:189], off
	s_mov_b32 m0, s79
	v_lshl_add_u64 v[222:223], s[42:43], 0, v[132:133]
	global_load_lds_dwordx4 v130, s[80:81]
	s_add_i32 m0, s79, 0x2000
	s_nop 0
	global_load_lds_dwordx4 v134, s[80:81]
	v_lshl_add_u64 v[220:221], s[42:43], 0, v[128:129]
	s_mov_b32 m0, s29
	s_nop 0
	global_load_lds_dwordx4 v[220:221], off
	s_mov_b32 m0, s33
	s_nop 0
	global_load_lds_dwordx4 v[222:223], off
	s_waitcnt vmcnt(8)
	s_waitcnt lgkmcnt(0)
	s_barrier
	s_setprio 1
	s_waitcnt lgkmcnt(0)
	v_mfma_f32_16x16x32_bf16 v[60:63], v[152:155], v[184:187], v[60:63]
	v_mfma_f32_16x16x32_bf16 v[56:59], v[160:163], v[184:187], v[56:59]
	v_mfma_f32_16x16x32_bf16 v[52:55], v[152:155], v[196:199], v[52:55]
	v_mfma_f32_16x16x32_bf16 v[44:47], v[160:163], v[196:199], v[44:47]
	v_mfma_f32_16x16x32_bf16 v[36:39], v[152:155], v[204:207], v[36:39]
	v_mfma_f32_16x16x32_bf16 v[28:31], v[160:163], v[204:207], v[28:31]
	v_mfma_f32_16x16x32_bf16 v[20:23], v[152:155], v[212:215], v[20:23]
	v_mfma_f32_16x16x32_bf16 v[12:15], v[160:163], v[212:215], v[12:15]
	v_mfma_f32_16x16x32_bf16 v[60:63], v[156:159], v[192:195], v[60:63]
	v_mfma_f32_16x16x32_bf16 v[56:59], v[164:167], v[192:195], v[56:59]
	v_mfma_f32_16x16x32_bf16 v[52:55], v[156:159], v[200:203], v[52:55]
	v_mfma_f32_16x16x32_bf16 v[44:47], v[164:167], v[200:203], v[44:47]
	v_mfma_f32_16x16x32_bf16 v[36:39], v[156:159], v[208:211], v[36:39]
	v_mfma_f32_16x16x32_bf16 v[28:31], v[164:167], v[208:211], v[28:31]
	v_mfma_f32_16x16x32_bf16 v[20:23], v[156:159], v[216:219], v[20:23]
	v_mfma_f32_16x16x32_bf16 v[12:15], v[164:167], v[216:219], v[12:15]
	s_setprio 0
	s_setprio 1
	v_mfma_f32_16x16x32_bf16 v[48:51], v[168:171], v[184:187], v[48:51]
	v_mfma_f32_16x16x32_bf16 v[40:43], v[176:179], v[184:187], v[40:43]
	v_mfma_f32_16x16x32_bf16 v[32:35], v[168:171], v[196:199], v[32:35]
	v_mfma_f32_16x16x32_bf16 v[24:27], v[176:179], v[196:199], v[24:27]
	v_mfma_f32_16x16x32_bf16 v[16:19], v[168:171], v[204:207], v[16:19]
	v_mfma_f32_16x16x32_bf16 v[8:11], v[176:179], v[204:207], v[8:11]
	v_mfma_f32_16x16x32_bf16 v[4:7], v[168:171], v[212:215], v[4:7]
	v_mfma_f32_16x16x32_bf16 v[0:3], v[176:179], v[212:215], v[0:3]
	v_mfma_f32_16x16x32_bf16 v[48:51], v[172:175], v[192:195], v[48:51]
	v_mfma_f32_16x16x32_bf16 v[40:43], v[180:183], v[192:195], v[40:43]
	v_mfma_f32_16x16x32_bf16 v[32:35], v[172:175], v[200:203], v[32:35]
	v_mfma_f32_16x16x32_bf16 v[24:27], v[180:183], v[200:203], v[24:27]
	v_mfma_f32_16x16x32_bf16 v[16:19], v[172:175], v[208:211], v[16:19]
	v_mfma_f32_16x16x32_bf16 v[8:11], v[180:183], v[208:211], v[8:11]
	v_mfma_f32_16x16x32_bf16 v[4:7], v[172:175], v[216:219], v[4:7]
	v_mfma_f32_16x16x32_bf16 v[0:3], v[180:183], v[216:219], v[0:3]
	s_setprio 0
	s_barrier
	s_add_i32 s79, 0, 0x18000
	s_add_i32 s80, 0, 0x1c000
	v_add_u32_e32 v164, s79, v147
	v_add_u32_e32 v180, s80, v147
	ds_read_b128 v[152:155], v164
	ds_read_b128 v[156:159], v164 offset:1024
	ds_read_b128 v[160:163], v164 offset:2048
	ds_read_b128 v[164:167], v164 offset:3072
	ds_read_b128 v[168:171], v180
	ds_read_b128 v[172:175], v180 offset:1024
	ds_read_b128 v[176:179], v180 offset:2048
	ds_read_b128 v[180:183], v180 offset:3072
	s_add_u32 s42, s42, 0x40000
	s_addc_u32 s43, s43, 0
	s_mov_b32 m0, s62
	ds_read_b128 v[184:187], v151 offset:32768
	ds_read_b128 v[192:195], v151 offset:33792
	ds_read_b128 v[196:199], v151 offset:34816
	ds_read_b128 v[200:203], v151 offset:35840
	ds_read_b128 v[204:207], v151 offset:36864
	ds_read_b128 v[208:211], v151 offset:37888
	ds_read_b128 v[212:215], v151 offset:38912
	ds_read_b128 v[216:219], v151 offset:39936
	global_load_lds_dwordx4 v128, s[42:43]
	s_mov_b32 m0, s63
	s_nop 0
	global_load_lds_dwordx4 v132, s[42:43]
	s_waitcnt vmcnt(8)
	s_waitcnt lgkmcnt(0)
	s_barrier
	s_setprio 1
	s_waitcnt lgkmcnt(0)
	v_mfma_f32_16x16x32_bf16 v[124:127], v[152:155], v[184:187], v[124:127]
	v_mfma_f32_16x16x32_bf16 v[120:123], v[160:163], v[184:187], v[120:123]
	v_mfma_f32_16x16x32_bf16 v[116:119], v[152:155], v[196:199], v[116:119]
	v_mfma_f32_16x16x32_bf16 v[108:111], v[160:163], v[196:199], v[108:111]
	v_mfma_f32_16x16x32_bf16 v[100:103], v[152:155], v[204:207], v[100:103]
	v_mfma_f32_16x16x32_bf16 v[92:95], v[160:163], v[204:207], v[92:95]
	v_mfma_f32_16x16x32_bf16 v[84:87], v[152:155], v[212:215], v[84:87]
	v_mfma_f32_16x16x32_bf16 v[76:79], v[160:163], v[212:215], v[76:79]
	v_mfma_f32_16x16x32_bf16 v[124:127], v[156:159], v[192:195], v[124:127]
	v_mfma_f32_16x16x32_bf16 v[120:123], v[164:167], v[192:195], v[120:123]
	v_mfma_f32_16x16x32_bf16 v[116:119], v[156:159], v[200:203], v[116:119]
	v_mfma_f32_16x16x32_bf16 v[108:111], v[164:167], v[200:203], v[108:111]
	v_mfma_f32_16x16x32_bf16 v[100:103], v[156:159], v[208:211], v[100:103]
	v_mfma_f32_16x16x32_bf16 v[92:95], v[164:167], v[208:211], v[92:95]
	v_mfma_f32_16x16x32_bf16 v[84:87], v[156:159], v[216:219], v[84:87]
	v_mfma_f32_16x16x32_bf16 v[76:79], v[164:167], v[216:219], v[76:79]
	s_setprio 0
	s_setprio 1
	v_mfma_f32_16x16x32_bf16 v[112:115], v[168:171], v[184:187], v[112:115]
	v_mfma_f32_16x16x32_bf16 v[104:107], v[176:179], v[184:187], v[104:107]
	v_mfma_f32_16x16x32_bf16 v[96:99], v[168:171], v[196:199], v[96:99]
	v_mfma_f32_16x16x32_bf16 v[88:91], v[176:179], v[196:199], v[88:91]
	v_mfma_f32_16x16x32_bf16 v[80:83], v[168:171], v[204:207], v[80:83]
	v_mfma_f32_16x16x32_bf16 v[72:75], v[176:179], v[204:207], v[72:75]
	v_mfma_f32_16x16x32_bf16 v[68:71], v[168:171], v[212:215], v[68:71]
	v_mfma_f32_16x16x32_bf16 v[64:67], v[176:179], v[212:215], v[64:67]
	v_mfma_f32_16x16x32_bf16 v[112:115], v[172:175], v[192:195], v[112:115]
	v_mfma_f32_16x16x32_bf16 v[104:107], v[180:183], v[192:195], v[104:107]
	v_mfma_f32_16x16x32_bf16 v[96:99], v[172:175], v[200:203], v[96:99]
	v_mfma_f32_16x16x32_bf16 v[88:91], v[180:183], v[200:203], v[88:91]
	v_mfma_f32_16x16x32_bf16 v[80:83], v[172:175], v[208:211], v[80:83]
	v_mfma_f32_16x16x32_bf16 v[72:75], v[180:183], v[208:211], v[72:75]
	v_mfma_f32_16x16x32_bf16 v[68:71], v[172:175], v[216:219], v[68:71]
	v_mfma_f32_16x16x32_bf16 v[64:67], v[180:183], v[216:219], v[64:67]
	s_setprio 0
	s_barrier
	s_add_i32 s42, s79, s61
	v_lshl_add_u64 v[144:145], v[144:145], 0, s[10:11]
	s_mov_b32 m0, s42
	ds_read_b128 v[184:187], v151 offset:49152
	ds_read_b128 v[192:195], v151 offset:50176
	ds_read_b128 v[196:199], v151 offset:51200
	ds_read_b128 v[200:203], v151 offset:52224
	ds_read_b128 v[204:207], v151 offset:53248
	ds_read_b128 v[208:211], v151 offset:54272
	ds_read_b128 v[212:215], v151 offset:55296
	ds_read_b128 v[216:219], v151 offset:56320
	global_load_lds_dwordx4 v[144:145], off
	s_add_i32 m0, s42, 0x2000
	s_add_u32 s34, s34, 0x40080
	v_lshl_add_u64 v[144:145], v[188:189], 0, s[10:11]
	s_addc_u32 s35, s35, 0
	s_add_i32 s42, s80, s61
	global_load_lds_dwordx4 v[144:145], off
	s_mov_b32 m0, s42
	s_nop 0
	global_load_lds_dwordx4 v130, s[34:35]
	s_add_i32 m0, s42, 0x2000
	s_nop 0
	global_load_lds_dwordx4 v134, s[34:35]
	v_lshl_add_u64 v[144:145], v[220:221], 0, s[10:11]
	s_mov_b32 m0, s65
	s_nop 0
	global_load_lds_dwordx4 v[144:145], off
	v_lshl_add_u64 v[144:145], v[222:223], 0, s[10:11]
	s_mov_b32 m0, s66
	s_nop 0
	global_load_lds_dwordx4 v[144:145], off
	s_waitcnt vmcnt(8)
	s_waitcnt lgkmcnt(0)
	s_barrier
	s_setprio 1
	s_waitcnt lgkmcnt(0)
	v_mfma_f32_16x16x32_bf16 v[60:63], v[152:155], v[184:187], v[60:63]
	v_mfma_f32_16x16x32_bf16 v[56:59], v[160:163], v[184:187], v[56:59]
	v_mfma_f32_16x16x32_bf16 v[52:55], v[152:155], v[196:199], v[52:55]
	v_mfma_f32_16x16x32_bf16 v[44:47], v[160:163], v[196:199], v[44:47]
	v_mfma_f32_16x16x32_bf16 v[36:39], v[152:155], v[204:207], v[36:39]
	v_mfma_f32_16x16x32_bf16 v[28:31], v[160:163], v[204:207], v[28:31]
	v_mfma_f32_16x16x32_bf16 v[20:23], v[152:155], v[212:215], v[20:23]
	v_mfma_f32_16x16x32_bf16 v[12:15], v[160:163], v[212:215], v[12:15]
	v_mfma_f32_16x16x32_bf16 v[60:63], v[156:159], v[192:195], v[60:63]
	v_mfma_f32_16x16x32_bf16 v[56:59], v[164:167], v[192:195], v[56:59]
	v_mfma_f32_16x16x32_bf16 v[52:55], v[156:159], v[200:203], v[52:55]
	v_mfma_f32_16x16x32_bf16 v[44:47], v[164:167], v[200:203], v[44:47]
	v_mfma_f32_16x16x32_bf16 v[36:39], v[156:159], v[208:211], v[36:39]
	v_mfma_f32_16x16x32_bf16 v[28:31], v[164:167], v[208:211], v[28:31]
	v_mfma_f32_16x16x32_bf16 v[20:23], v[156:159], v[216:219], v[20:23]
	v_mfma_f32_16x16x32_bf16 v[12:15], v[164:167], v[216:219], v[12:15]
	s_setprio 0
	s_setprio 1
	v_mfma_f32_16x16x32_bf16 v[48:51], v[168:171], v[184:187], v[48:51]
	v_mfma_f32_16x16x32_bf16 v[40:43], v[176:179], v[184:187], v[40:43]
	v_mfma_f32_16x16x32_bf16 v[32:35], v[168:171], v[196:199], v[32:35]
	v_mfma_f32_16x16x32_bf16 v[24:27], v[176:179], v[196:199], v[24:27]
	v_mfma_f32_16x16x32_bf16 v[16:19], v[168:171], v[204:207], v[16:19]
	v_mfma_f32_16x16x32_bf16 v[8:11], v[176:179], v[204:207], v[8:11]
	v_mfma_f32_16x16x32_bf16 v[4:7], v[168:171], v[212:215], v[4:7]
	v_mfma_f32_16x16x32_bf16 v[0:3], v[176:179], v[212:215], v[0:3]
	v_mfma_f32_16x16x32_bf16 v[48:51], v[172:175], v[192:195], v[48:51]
	v_mfma_f32_16x16x32_bf16 v[40:43], v[180:183], v[192:195], v[40:43]
	v_mfma_f32_16x16x32_bf16 v[32:35], v[172:175], v[200:203], v[32:35]
	v_mfma_f32_16x16x32_bf16 v[24:27], v[180:183], v[200:203], v[24:27]
	v_mfma_f32_16x16x32_bf16 v[16:19], v[172:175], v[208:211], v[16:19]
	v_mfma_f32_16x16x32_bf16 v[8:11], v[180:183], v[208:211], v[8:11]
	v_mfma_f32_16x16x32_bf16 v[4:7], v[172:175], v[216:219], v[4:7]
	v_mfma_f32_16x16x32_bf16 v[0:3], v[180:183], v[216:219], v[0:3]
	s_setprio 0
	s_barrier
	s_add_i32 s77, s77, 2
	s_add_u32 s30, s30, 0x100
	s_addc_u32 s31, s31, 0
	s_add_u32 s75, s75, 0x100
	s_addc_u32 s76, s76, 0
	s_cmp_gt_u32 s77, 13
	s_cbranch_scc0 .LBB0_1434
	s_and_b64 vcc, exec, s[12:13]
	s_cbranch_vccz .LBB0_1437
	s_barrier

.LBB0_1561:
	s_lshl_b32 s8, s8, 5
	s_and_b32 s14, s8, 0x60
	s_mov_b64 s[8:9], 0x80
	s_add_i32 m0, s29, 0x18000
	v_lshl_add_u64 v[6:7], v[6:7], 0, s[8:9]
	s_lshl_b32 s11, s1, 13
	s_lshl_b32 s15, s14, 7
	s_waitcnt vmcnt(2)
	s_barrier
	global_load_lds_dwordx4 v[6:7], off
	v_lshl_add_u64 v[4:5], v[4:5], 0, s[8:9]
	s_add_i32 m0, s29, 0x1a000
	s_add_i32 s52, s29, 0x8000
	s_add_i32 s53, s29, 0xa000
	global_load_lds_dwordx4 v[4:5], off
	v_lshl_add_u64 v[0:1], v[0:1], 0, s[8:9]
	s_mov_b32 m0, s52
	s_add_u32 s12, s34, 0x40080
	global_load_lds_dwordx4 v[0:1], off
	v_lshl_add_u64 v[0:1], v[2:3], 0, s[8:9]
	s_mov_b32 m0, s53
	s_addc_u32 s13, s35, 0
	global_load_lds_dwordx4 v[0:1], off
	s_add_i32 m0, s29, 0x1c000
	s_nop 0
	global_load_lds_dwordx4 v130, s[12:13]
	s_add_i32 m0, s29, 0x1e000
	s_cmpk_lt_u32 s10, 0x100
	global_load_lds_dwordx4 v134, s[12:13]
	v_lshrrev_b32_e32 v1, 1, v8
	v_and_b32_e32 v1, 24, v1
	v_and_b32_e32 v0, 15, v8
	v_lshlrev_b32_e32 v2, 1, v1
	v_lshl_or_b32 v146, s1, 6, v0
	v_lshl_or_b32 v0, v0, 6, v2
	v_lshlrev_b32_e32 v2, 2, v8
	v_and_b32_e32 v2, 32, v2
	v_bitop3_b32 v3, v0, s11, v2 bitop3:0xde
	v_bitop3_b32 v147, v0, s15, v2 bitop3:0xde
	v_lshlrev_b32_e32 v0, 14, v9
	v_and_b32_e32 v0, 0xffff8000, v0
	v_or_b32_e32 v148, s14, v1
	v_lshl_add_u32 v0, v10, 11, v0
	v_and_b32_e32 v1, 1, v9
	v_lshl_or_b32 v0, v1, 6, v0
	v_lshl_add_u32 v136, v11, 1, v0
	v_lshlrev_b32_e32 v0, 14, v12
	v_and_b32_e32 v0, 0xffff8000, v0
	s_waitcnt vmcnt(6)
	v_lshl_add_u32 v0, v13, 11, v0
	v_and_b32_e32 v1, 1, v12
	s_cselect_b64 s[10:11], -1, 0
	v_lshl_or_b32 v0, v1, 6, v0
	s_add_i32 s69, 0, 0x10000
	s_add_i32 s70, 0, 0x14000
	s_sext_i32_i8 s33, s0
	s_ashr_i32 s68, s3, 31
	v_mov_b32_e32 v137, v131
	v_lshl_add_u32 v138, v14, 1, v0
	v_mov_b32_e32 v139, v131
	v_mov_b64_e32 v[140:141], 0x800
	v_mov_b64_e32 v[142:143], 0x7ff
	v_add_u32_e32 v149, s69, v147
	v_add_u32_e32 v150, s70, v147
	v_add_u32_e32 v151, 0, v3
	s_mov_b64 s[12:13], 0x100000
	s_mov_b32 s71, 0x100000
	s_mov_b64 s[14:15], 0x120000
	s_mov_b32 s72, 0x120000
	s_mov_b64 s[16:17], 0x140000
	s_mov_b32 s73, 0x140000
	s_mov_b64 s[18:19], 0x160000
	s_mov_b32 s74, 0x160000
	s_barrier
	s_branch .LBB0_1564

.LBB0_1571:
	ds_read_b128 v[152:155], v149
	ds_read_b128 v[156:159], v149 offset:1024
	ds_read_b128 v[160:163], v149 offset:2048
	ds_read_b128 v[164:167], v149 offset:3072
	ds_read_b128 v[168:171], v150
	ds_read_b128 v[172:175], v150 offset:1024
	ds_read_b128 v[176:179], v150 offset:2048
	ds_read_b128 v[180:183], v150 offset:3072
	s_add_u32 s34, s30, 0xfffc0080
	s_addc_u32 s35, s31, -1
	s_cmp_eq_u32 s77, 12
	s_cselect_b32 s43, s23, s35
	s_cselect_b32 s42, s54, s34
	s_cselect_b32 s35, s21, s76
	s_cselect_b32 s34, s55, s75
	s_add_i32 m0, s29, 0xc000
	ds_read_b128 v[184:187], v151
	ds_read_b128 v[192:195], v151 offset:1024
	ds_read_b128 v[196:199], v151 offset:2048
	ds_read_b128 v[200:203], v151 offset:3072
	ds_read_b128 v[204:207], v151 offset:4096
	ds_read_b128 v[208:211], v151 offset:5120
	ds_read_b128 v[212:215], v151 offset:6144
	ds_read_b128 v[216:219], v151 offset:7168
	global_load_lds_dwordx4 v136, s[30:31]
	s_add_i32 m0, s29, 0xe000
	s_nop 0
	global_load_lds_dwordx4 v138, s[30:31]
	s_waitcnt vmcnt(8)
	s_waitcnt lgkmcnt(0)
	s_barrier
	s_setprio 1
	s_waitcnt lgkmcnt(0)
	v_mfma_f32_16x16x32_bf16 v[124:127], v[152:155], v[184:187], v[124:127]
	v_mfma_f32_16x16x32_bf16 v[120:123], v[160:163], v[184:187], v[120:123]
	v_mfma_f32_16x16x32_bf16 v[108:111], v[152:155], v[196:199], v[108:111]
	v_mfma_f32_16x16x32_bf16 v[104:107], v[160:163], v[196:199], v[104:107]
	v_mfma_f32_16x16x32_bf16 v[92:95], v[152:155], v[204:207], v[92:95]
	v_mfma_f32_16x16x32_bf16 v[88:91], v[160:163], v[204:207], v[88:91]
	v_mfma_f32_16x16x32_bf16 v[76:79], v[152:155], v[212:215], v[76:79]
	v_mfma_f32_16x16x32_bf16 v[72:75], v[160:163], v[212:215], v[72:75]
	v_mfma_f32_16x16x32_bf16 v[124:127], v[156:159], v[192:195], v[124:127]
	v_mfma_f32_16x16x32_bf16 v[120:123], v[164:167], v[192:195], v[120:123]
	v_mfma_f32_16x16x32_bf16 v[108:111], v[156:159], v[200:203], v[108:111]
	v_mfma_f32_16x16x32_bf16 v[104:107], v[164:167], v[200:203], v[104:107]
	v_mfma_f32_16x16x32_bf16 v[92:95], v[156:159], v[208:211], v[92:95]
	v_mfma_f32_16x16x32_bf16 v[88:91], v[164:167], v[208:211], v[88:91]
	v_mfma_f32_16x16x32_bf16 v[76:79], v[156:159], v[216:219], v[76:79]
	v_mfma_f32_16x16x32_bf16 v[72:75], v[164:167], v[216:219], v[72:75]
	s_setprio 0
	s_setprio 1
	v_mfma_f32_16x16x32_bf16 v[116:119], v[168:171], v[184:187], v[116:119]
	v_mfma_f32_16x16x32_bf16 v[112:115], v[176:179], v[184:187], v[112:115]
	v_mfma_f32_16x16x32_bf16 v[100:103], v[168:171], v[196:199], v[100:103]
	v_mfma_f32_16x16x32_bf16 v[96:99], v[176:179], v[196:199], v[96:99]
	v_mfma_f32_16x16x32_bf16 v[84:87], v[168:171], v[204:207], v[84:87]
	v_mfma_f32_16x16x32_bf16 v[80:83], v[176:179], v[204:207], v[80:83]
	v_mfma_f32_16x16x32_bf16 v[68:71], v[168:171], v[212:215], v[68:71]
	v_mfma_f32_16x16x32_bf16 v[64:67], v[176:179], v[212:215], v[64:67]
	v_mfma_f32_16x16x32_bf16 v[116:119], v[172:175], v[192:195], v[116:119]
	v_mfma_f32_16x16x32_bf16 v[112:115], v[180:183], v[192:195], v[112:115]
	v_mfma_f32_16x16x32_bf16 v[100:103], v[172:175], v[200:203], v[100:103]
	v_mfma_f32_16x16x32_bf16 v[96:99], v[180:183], v[200:203], v[96:99]
	v_mfma_f32_16x16x32_bf16 v[84:87], v[172:175], v[208:211], v[84:87]
	v_mfma_f32_16x16x32_bf16 v[80:83], v[180:183], v[208:211], v[80:83]
	v_mfma_f32_16x16x32_bf16 v[68:71], v[172:175], v[216:219], v[68:71]
	v_mfma_f32_16x16x32_bf16 v[64:67], v[180:183], v[216:219], v[64:67]
	s_setprio 0
	s_barrier
	s_add_i32 s79, s69, s63
	v_lshl_add_u64 v[144:145], s[34:35], 0, v[130:131]
	s_mov_b32 m0, s79
	ds_read_b128 v[184:187], v151 offset:16384
	ds_read_b128 v[192:195], v151 offset:17408
	ds_read_b128 v[196:199], v151 offset:18432
	ds_read_b128 v[200:203], v151 offset:19456
	ds_read_b128 v[204:207], v151 offset:20480
	ds_read_b128 v[208:211], v151 offset:21504
	ds_read_b128 v[212:215], v151 offset:22528
	ds_read_b128 v[216:219], v151 offset:23552
	global_load_lds_dwordx4 v[144:145], off
	s_add_i32 m0, s79, 0x2000
	s_add_u32 s80, s34, 0x40000
	v_lshl_add_u64 v[188:189], s[34:35], 0, v[134:135]
	s_addc_u32 s81, s35, 0
	s_add_i32 s79, s70, s63
	global_load_lds_dwordx4 v[188:189], off
	s_mov_b32 m0, s79
	v_lshl_add_u64 v[222:223], s[42:43], 0, v[132:133]
	global_load_lds_dwordx4 v130, s[80:81]
	s_add_i32 m0, s79, 0x2000
	s_nop 0
	global_load_lds_dwordx4 v134, s[80:81]
	v_lshl_add_u64 v[220:221], s[42:43], 0, v[128:129]
	s_mov_b32 m0, s29
	s_nop 0
	global_load_lds_dwordx4 v[220:221], off
	s_mov_b32 m0, s64
	s_nop 0
	global_load_lds_dwordx4 v[222:223], off
	s_waitcnt vmcnt(8)
	s_waitcnt lgkmcnt(0)
	s_barrier
	s_setprio 1
	s_waitcnt lgkmcnt(0)
	v_mfma_f32_16x16x32_bf16 v[60:63], v[152:155], v[184:187], v[60:63]
	v_mfma_f32_16x16x32_bf16 v[56:59], v[160:163], v[184:187], v[56:59]
	v_mfma_f32_16x16x32_bf16 v[44:47], v[152:155], v[196:199], v[44:47]
	v_mfma_f32_16x16x32_bf16 v[40:43], v[160:163], v[196:199], v[40:43]
	v_mfma_f32_16x16x32_bf16 v[28:31], v[152:155], v[204:207], v[28:31]
	v_mfma_f32_16x16x32_bf16 v[24:27], v[160:163], v[204:207], v[24:27]
	v_mfma_f32_16x16x32_bf16 v[12:15], v[152:155], v[212:215], v[12:15]
	v_mfma_f32_16x16x32_bf16 v[8:11], v[160:163], v[212:215], v[8:11]
	v_mfma_f32_16x16x32_bf16 v[60:63], v[156:159], v[192:195], v[60:63]
	v_mfma_f32_16x16x32_bf16 v[56:59], v[164:167], v[192:195], v[56:59]
	v_mfma_f32_16x16x32_bf16 v[44:47], v[156:159], v[200:203], v[44:47]
	v_mfma_f32_16x16x32_bf16 v[40:43], v[164:167], v[200:203], v[40:43]
	v_mfma_f32_16x16x32_bf16 v[28:31], v[156:159], v[208:211], v[28:31]
	v_mfma_f32_16x16x32_bf16 v[24:27], v[164:167], v[208:211], v[24:27]
	v_mfma_f32_16x16x32_bf16 v[12:15], v[156:159], v[216:219], v[12:15]
	v_mfma_f32_16x16x32_bf16 v[8:11], v[164:167], v[216:219], v[8:11]
	s_setprio 0
	s_setprio 1
	v_mfma_f32_16x16x32_bf16 v[52:55], v[168:171], v[184:187], v[52:55]
	v_mfma_f32_16x16x32_bf16 v[48:51], v[176:179], v[184:187], v[48:51]
	v_mfma_f32_16x16x32_bf16 v[36:39], v[168:171], v[196:199], v[36:39]
	v_mfma_f32_16x16x32_bf16 v[32:35], v[176:179], v[196:199], v[32:35]
	v_mfma_f32_16x16x32_bf16 v[20:23], v[168:171], v[204:207], v[20:23]
	v_mfma_f32_16x16x32_bf16 v[16:19], v[176:179], v[204:207], v[16:19]
	v_mfma_f32_16x16x32_bf16 v[4:7], v[168:171], v[212:215], v[4:7]
	v_mfma_f32_16x16x32_bf16 v[0:3], v[176:179], v[212:215], v[0:3]
	v_mfma_f32_16x16x32_bf16 v[52:55], v[172:175], v[192:195], v[52:55]
	v_mfma_f32_16x16x32_bf16 v[48:51], v[180:183], v[192:195], v[48:51]
	v_mfma_f32_16x16x32_bf16 v[36:39], v[172:175], v[200:203], v[36:39]
	v_mfma_f32_16x16x32_bf16 v[32:35], v[180:183], v[200:203], v[32:35]
	v_mfma_f32_16x16x32_bf16 v[20:23], v[172:175], v[208:211], v[20:23]
	v_mfma_f32_16x16x32_bf16 v[16:19], v[180:183], v[208:211], v[16:19]
	v_mfma_f32_16x16x32_bf16 v[4:7], v[172:175], v[216:219], v[4:7]
	v_mfma_f32_16x16x32_bf16 v[0:3], v[180:183], v[216:219], v[0:3]
	s_setprio 0
	s_barrier
	s_add_i32 s79, 0, 0x18000
	s_add_i32 s80, 0, 0x1c000
	v_add_u32_e32 v164, s79, v147
	v_add_u32_e32 v180, s80, v147
	ds_read_b128 v[152:155], v164
	ds_read_b128 v[156:159], v164 offset:1024
	ds_read_b128 v[160:163], v164 offset:2048
	ds_read_b128 v[164:167], v164 offset:3072
	ds_read_b128 v[168:171], v180
	ds_read_b128 v[172:175], v180 offset:1024
	ds_read_b128 v[176:179], v180 offset:2048
	ds_read_b128 v[180:183], v180 offset:3072
	s_add_u32 s42, s42, 0x40000
	s_addc_u32 s43, s43, 0
	s_mov_b32 m0, s65
	ds_read_b128 v[184:187], v151 offset:32768
	ds_read_b128 v[192:195], v151 offset:33792
	ds_read_b128 v[196:199], v151 offset:34816
	ds_read_b128 v[200:203], v151 offset:35840
	ds_read_b128 v[204:207], v151 offset:36864
	ds_read_b128 v[208:211], v151 offset:37888
	ds_read_b128 v[212:215], v151 offset:38912
	ds_read_b128 v[216:219], v151 offset:39936
	global_load_lds_dwordx4 v128, s[42:43]
	s_mov_b32 m0, s66
	s_nop 0
	global_load_lds_dwordx4 v132, s[42:43]
	s_waitcnt vmcnt(8)
	s_waitcnt lgkmcnt(0)
	s_barrier
	s_setprio 1
	s_waitcnt lgkmcnt(0)
	v_mfma_f32_16x16x32_bf16 v[124:127], v[152:155], v[184:187], v[124:127]
	v_mfma_f32_16x16x32_bf16 v[120:123], v[160:163], v[184:187], v[120:123]
	v_mfma_f32_16x16x32_bf16 v[108:111], v[152:155], v[196:199], v[108:111]
	v_mfma_f32_16x16x32_bf16 v[104:107], v[160:163], v[196:199], v[104:107]
	v_mfma_f32_16x16x32_bf16 v[92:95], v[152:155], v[204:207], v[92:95]
	v_mfma_f32_16x16x32_bf16 v[88:91], v[160:163], v[204:207], v[88:91]
	v_mfma_f32_16x16x32_bf16 v[76:79], v[152:155], v[212:215], v[76:79]
	v_mfma_f32_16x16x32_bf16 v[72:75], v[160:163], v[212:215], v[72:75]
	v_mfma_f32_16x16x32_bf16 v[124:127], v[156:159], v[192:195], v[124:127]
	v_mfma_f32_16x16x32_bf16 v[120:123], v[164:167], v[192:195], v[120:123]
	v_mfma_f32_16x16x32_bf16 v[108:111], v[156:159], v[200:203], v[108:111]
	v_mfma_f32_16x16x32_bf16 v[104:107], v[164:167], v[200:203], v[104:107]
	v_mfma_f32_16x16x32_bf16 v[92:95], v[156:159], v[208:211], v[92:95]
	v_mfma_f32_16x16x32_bf16 v[88:91], v[164:167], v[208:211], v[88:91]
	v_mfma_f32_16x16x32_bf16 v[76:79], v[156:159], v[216:219], v[76:79]
	v_mfma_f32_16x16x32_bf16 v[72:75], v[164:167], v[216:219], v[72:75]
	s_setprio 0
	s_setprio 1
	v_mfma_f32_16x16x32_bf16 v[116:119], v[168:171], v[184:187], v[116:119]
	v_mfma_f32_16x16x32_bf16 v[112:115], v[176:179], v[184:187], v[112:115]
	v_mfma_f32_16x16x32_bf16 v[100:103], v[168:171], v[196:199], v[100:103]
	v_mfma_f32_16x16x32_bf16 v[96:99], v[176:179], v[196:199], v[96:99]
	v_mfma_f32_16x16x32_bf16 v[84:87], v[168:171], v[204:207], v[84:87]
	v_mfma_f32_16x16x32_bf16 v[80:83], v[176:179], v[204:207], v[80:83]
	v_mfma_f32_16x16x32_bf16 v[68:71], v[168:171], v[212:215], v[68:71]
	v_mfma_f32_16x16x32_bf16 v[64:67], v[176:179], v[212:215], v[64:67]
	v_mfma_f32_16x16x32_bf16 v[116:119], v[172:175], v[192:195], v[116:119]
	v_mfma_f32_16x16x32_bf16 v[112:115], v[180:183], v[192:195], v[112:115]
	v_mfma_f32_16x16x32_bf16 v[100:103], v[172:175], v[200:203], v[100:103]
	v_mfma_f32_16x16x32_bf16 v[96:99], v[180:183], v[200:203], v[96:99]
	v_mfma_f32_16x16x32_bf16 v[84:87], v[172:175], v[208:211], v[84:87]
	v_mfma_f32_16x16x32_bf16 v[80:83], v[180:183], v[208:211], v[80:83]
	v_mfma_f32_16x16x32_bf16 v[68:71], v[172:175], v[216:219], v[68:71]
	v_mfma_f32_16x16x32_bf16 v[64:67], v[180:183], v[216:219], v[64:67]
	s_setprio 0
	s_barrier
	s_add_i32 s42, s79, s63
	v_lshl_add_u64 v[144:145], v[144:145], 0, s[8:9]
	s_mov_b32 m0, s42
	ds_read_b128 v[184:187], v151 offset:49152
	ds_read_b128 v[192:195], v151 offset:50176
	ds_read_b128 v[196:199], v151 offset:51200
	ds_read_b128 v[200:203], v151 offset:52224
	ds_read_b128 v[204:207], v151 offset:53248
	ds_read_b128 v[208:211], v151 offset:54272
	ds_read_b128 v[212:215], v151 offset:55296
	ds_read_b128 v[216:219], v151 offset:56320
	global_load_lds_dwordx4 v[144:145], off
	s_add_i32 m0, s42, 0x2000
	s_add_u32 s34, s34, 0x40080
	v_lshl_add_u64 v[144:145], v[188:189], 0, s[8:9]
	s_addc_u32 s35, s35, 0
	s_add_i32 s42, s80, s63
	global_load_lds_dwordx4 v[144:145], off
	s_mov_b32 m0, s42
	s_nop 0
	global_load_lds_dwordx4 v130, s[34:35]
	s_add_i32 m0, s42, 0x2000
	s_nop 0
	global_load_lds_dwordx4 v134, s[34:35]
	v_lshl_add_u64 v[144:145], v[220:221], 0, s[8:9]
	s_mov_b32 m0, s52
	s_nop 0
	global_load_lds_dwordx4 v[144:145], off
	v_lshl_add_u64 v[144:145], v[222:223], 0, s[8:9]
	s_mov_b32 m0, s53
	s_nop 0
	global_load_lds_dwordx4 v[144:145], off
	s_waitcnt vmcnt(8)
	s_waitcnt lgkmcnt(0)
	s_barrier
	s_setprio 1
	s_waitcnt lgkmcnt(0)
	v_mfma_f32_16x16x32_bf16 v[60:63], v[152:155], v[184:187], v[60:63]
	v_mfma_f32_16x16x32_bf16 v[56:59], v[160:163], v[184:187], v[56:59]
	v_mfma_f32_16x16x32_bf16 v[44:47], v[152:155], v[196:199], v[44:47]
	v_mfma_f32_16x16x32_bf16 v[40:43], v[160:163], v[196:199], v[40:43]
	v_mfma_f32_16x16x32_bf16 v[28:31], v[152:155], v[204:207], v[28:31]
	v_mfma_f32_16x16x32_bf16 v[24:27], v[160:163], v[204:207], v[24:27]
	v_mfma_f32_16x16x32_bf16 v[12:15], v[152:155], v[212:215], v[12:15]
	v_mfma_f32_16x16x32_bf16 v[8:11], v[160:163], v[212:215], v[8:11]
	v_mfma_f32_16x16x32_bf16 v[60:63], v[156:159], v[192:195], v[60:63]
	v_mfma_f32_16x16x32_bf16 v[56:59], v[164:167], v[192:195], v[56:59]
	v_mfma_f32_16x16x32_bf16 v[44:47], v[156:159], v[200:203], v[44:47]
	v_mfma_f32_16x16x32_bf16 v[40:43], v[164:167], v[200:203], v[40:43]
	v_mfma_f32_16x16x32_bf16 v[28:31], v[156:159], v[208:211], v[28:31]
	v_mfma_f32_16x16x32_bf16 v[24:27], v[164:167], v[208:211], v[24:27]
	v_mfma_f32_16x16x32_bf16 v[12:15], v[156:159], v[216:219], v[12:15]
	v_mfma_f32_16x16x32_bf16 v[8:11], v[164:167], v[216:219], v[8:11]
	s_setprio 0
	s_setprio 1
	v_mfma_f32_16x16x32_bf16 v[52:55], v[168:171], v[184:187], v[52:55]
	v_mfma_f32_16x16x32_bf16 v[48:51], v[176:179], v[184:187], v[48:51]
	v_mfma_f32_16x16x32_bf16 v[36:39], v[168:171], v[196:199], v[36:39]
	v_mfma_f32_16x16x32_bf16 v[32:35], v[176:179], v[196:199], v[32:35]
	v_mfma_f32_16x16x32_bf16 v[20:23], v[168:171], v[204:207], v[20:23]
	v_mfma_f32_16x16x32_bf16 v[16:19], v[176:179], v[204:207], v[16:19]
	v_mfma_f32_16x16x32_bf16 v[4:7], v[168:171], v[212:215], v[4:7]
	v_mfma_f32_16x16x32_bf16 v[0:3], v[176:179], v[212:215], v[0:3]
	v_mfma_f32_16x16x32_bf16 v[52:55], v[172:175], v[192:195], v[52:55]
	v_mfma_f32_16x16x32_bf16 v[48:51], v[180:183], v[192:195], v[48:51]
	v_mfma_f32_16x16x32_bf16 v[36:39], v[172:175], v[200:203], v[36:39]
	v_mfma_f32_16x16x32_bf16 v[32:35], v[180:183], v[200:203], v[32:35]
	v_mfma_f32_16x16x32_bf16 v[20:23], v[172:175], v[208:211], v[20:23]
	v_mfma_f32_16x16x32_bf16 v[16:19], v[180:183], v[208:211], v[16:19]
	v_mfma_f32_16x16x32_bf16 v[4:7], v[172:175], v[216:219], v[4:7]
	v_mfma_f32_16x16x32_bf16 v[0:3], v[180:183], v[216:219], v[0:3]
	s_setprio 0
	s_barrier
	s_add_i32 s77, s77, 2
	s_add_u32 s30, s30, 0x100
	s_addc_u32 s31, s31, 0
	s_add_u32 s75, s75, 0x100
	s_addc_u32 s76, s76, 0
	s_cmp_gt_u32 s77, 13
	s_cbranch_scc0 .LBB0_1571
	s_and_b64 vcc, exec, s[10:11]
	s_cbranch_vccz .LBB0_1574
	s_barrier

.LBB0_1640:
	s_lshl_b32 s1, s1, 5
	s_mov_b64 s[8:9], 0x80
	s_and_b32 s1, s1, 0x60
	s_add_i32 m0, s29, 0x18000
	v_lshl_add_u64 v[6:7], v[6:7], 0, s[8:9]
	s_lshl_b32 s14, s11, 13
	s_lshl_b32 s15, s1, 7
	s_waitcnt vmcnt(2)
	s_barrier
	global_load_lds_dwordx4 v[6:7], off
	v_lshl_add_u64 v[4:5], v[4:5], 0, s[8:9]
	s_add_i32 m0, s29, 0x1a000
	s_add_i32 s63, s29, 0x8000
	s_add_i32 s64, s29, 0xa000
	global_load_lds_dwordx4 v[4:5], off
	v_lshl_add_u64 v[0:1], v[0:1], 0, s[8:9]
	s_mov_b32 m0, s63
	s_add_u32 s12, s34, 0x100080
	global_load_lds_dwordx4 v[0:1], off
	v_lshl_add_u64 v[0:1], v[2:3], 0, s[8:9]
	s_mov_b32 m0, s64
	s_addc_u32 s13, s35, 0
	global_load_lds_dwordx4 v[0:1], off
	s_add_i32 m0, s29, 0x1c000
	s_nop 0
	global_load_lds_dwordx4 v130, s[12:13]
	s_add_i32 m0, s29, 0x1e000
	s_cmpk_lt_u32 s10, 0x100
	global_load_lds_dwordx4 v134, s[12:13]
	v_lshrrev_b32_e32 v1, 1, v8
	v_and_b32_e32 v1, 24, v1
	v_and_b32_e32 v0, 15, v8
	v_lshlrev_b32_e32 v2, 1, v1
	v_lshl_or_b32 v146, s11, 6, v0
	v_lshl_or_b32 v0, v0, 6, v2
	v_lshlrev_b32_e32 v2, 2, v8
	v_and_b32_e32 v2, 32, v2
	v_bitop3_b32 v3, v0, s14, v2 bitop3:0xde
	v_bitop3_b32 v147, v0, s15, v2 bitop3:0xde
	v_lshlrev_b32_e32 v0, 16, v9
	v_and_b32_e32 v0, 0xfffe0000, v0
	v_or_b32_e32 v148, s1, v1
	v_lshl_add_u32 v0, v10, 13, v0
	v_and_b32_e32 v1, 1, v9
	v_lshl_or_b32 v0, v1, 6, v0
	v_lshl_add_u32 v136, v11, 1, v0
	v_lshlrev_b32_e32 v0, 16, v12
	v_and_b32_e32 v0, 0xfffe0000, v0
	s_waitcnt vmcnt(6)
	v_lshl_add_u32 v0, v13, 13, v0
	v_and_b32_e32 v1, 1, v12
	s_cselect_b64 s[10:11], -1, 0
	v_lshl_or_b32 v0, v1, 6, v0
	s_add_i32 s66, 0, 0x10000
	s_add_i32 s67, 0, 0x14000
	s_sext_i32_i8 s54, s0
	s_ashr_i32 s65, s3, 31
	v_mov_b32_e32 v137, v131
	v_lshl_add_u32 v138, v14, 1, v0
	v_mov_b32_e32 v139, v131
	v_mov_b64_e32 v[140:141], 0x200
	v_mov_b64_e32 v[142:143], 0x1ff
	v_add_u32_e32 v149, s66, v147
	v_add_u32_e32 v150, s67, v147
	v_add_u32_e32 v151, 0, v3
	s_mov_b64 s[12:13], 0x40000
	s_mov_b32 s68, 0x40000
	s_mov_b64 s[14:15], 0x48000
	s_mov_b32 s69, 0x48000
	s_mov_b64 s[16:17], 0x50000
	s_mov_b32 s70, 0x50000
	s_mov_b64 s[18:19], 0x58000
	s_mov_b32 s71, 0x58000
	s_barrier
	s_branch .LBB0_1643

.LBB0_1650:
	ds_read_b128 v[152:155], v149
	ds_read_b128 v[156:159], v149 offset:1024
	ds_read_b128 v[160:163], v149 offset:2048
	ds_read_b128 v[164:167], v149 offset:3072
	ds_read_b128 v[168:171], v150
	ds_read_b128 v[172:175], v150 offset:1024
	ds_read_b128 v[176:179], v150 offset:2048
	ds_read_b128 v[180:183], v150 offset:3072
	s_add_u32 s34, s30, 0xfff00080
	s_addc_u32 s35, s31, -1
	s_cmp_eq_u32 s75, 60
	s_cselect_b32 s43, s23, s35
	s_cselect_b32 s42, s55, s34
	s_cselect_b32 s35, s21, s74
	s_cselect_b32 s34, s72, s73
	s_add_i32 m0, s29, 0xc000
	ds_read_b128 v[184:187], v151
	ds_read_b128 v[192:195], v151 offset:1024
	ds_read_b128 v[196:199], v151 offset:2048
	ds_read_b128 v[200:203], v151 offset:3072
	ds_read_b128 v[204:207], v151 offset:4096
	ds_read_b128 v[208:211], v151 offset:5120
	ds_read_b128 v[212:215], v151 offset:6144
	ds_read_b128 v[216:219], v151 offset:7168
	global_load_lds_dwordx4 v136, s[30:31]
	s_add_i32 m0, s29, 0xe000
	s_nop 0
	global_load_lds_dwordx4 v138, s[30:31]
	s_waitcnt vmcnt(8)
	s_waitcnt lgkmcnt(0)
	s_barrier
	s_setprio 1
	s_waitcnt lgkmcnt(0)
	v_mfma_f32_16x16x32_bf16 v[124:127], v[152:155], v[184:187], v[124:127]
	v_mfma_f32_16x16x32_bf16 v[120:123], v[160:163], v[184:187], v[120:123]
	v_mfma_f32_16x16x32_bf16 v[116:119], v[152:155], v[196:199], v[116:119]
	v_mfma_f32_16x16x32_bf16 v[108:111], v[160:163], v[196:199], v[108:111]
	v_mfma_f32_16x16x32_bf16 v[100:103], v[152:155], v[204:207], v[100:103]
	v_mfma_f32_16x16x32_bf16 v[92:95], v[160:163], v[204:207], v[92:95]
	v_mfma_f32_16x16x32_bf16 v[84:87], v[152:155], v[212:215], v[84:87]
	v_mfma_f32_16x16x32_bf16 v[76:79], v[160:163], v[212:215], v[76:79]
	v_mfma_f32_16x16x32_bf16 v[124:127], v[156:159], v[192:195], v[124:127]
	v_mfma_f32_16x16x32_bf16 v[120:123], v[164:167], v[192:195], v[120:123]
	v_mfma_f32_16x16x32_bf16 v[116:119], v[156:159], v[200:203], v[116:119]
	v_mfma_f32_16x16x32_bf16 v[108:111], v[164:167], v[200:203], v[108:111]
	v_mfma_f32_16x16x32_bf16 v[100:103], v[156:159], v[208:211], v[100:103]
	v_mfma_f32_16x16x32_bf16 v[92:95], v[164:167], v[208:211], v[92:95]
	v_mfma_f32_16x16x32_bf16 v[84:87], v[156:159], v[216:219], v[84:87]
	v_mfma_f32_16x16x32_bf16 v[76:79], v[164:167], v[216:219], v[76:79]
	s_setprio 0
	s_setprio 1
	v_mfma_f32_16x16x32_bf16 v[112:115], v[168:171], v[184:187], v[112:115]
	v_mfma_f32_16x16x32_bf16 v[104:107], v[176:179], v[184:187], v[104:107]
	v_mfma_f32_16x16x32_bf16 v[96:99], v[168:171], v[196:199], v[96:99]
	v_mfma_f32_16x16x32_bf16 v[88:91], v[176:179], v[196:199], v[88:91]
	v_mfma_f32_16x16x32_bf16 v[80:83], v[168:171], v[204:207], v[80:83]
	v_mfma_f32_16x16x32_bf16 v[72:75], v[176:179], v[204:207], v[72:75]
	v_mfma_f32_16x16x32_bf16 v[68:71], v[168:171], v[212:215], v[68:71]
	v_mfma_f32_16x16x32_bf16 v[64:67], v[176:179], v[212:215], v[64:67]
	v_mfma_f32_16x16x32_bf16 v[112:115], v[172:175], v[192:195], v[112:115]
	v_mfma_f32_16x16x32_bf16 v[104:107], v[180:183], v[192:195], v[104:107]
	v_mfma_f32_16x16x32_bf16 v[96:99], v[172:175], v[200:203], v[96:99]
	v_mfma_f32_16x16x32_bf16 v[88:91], v[180:183], v[200:203], v[88:91]
	v_mfma_f32_16x16x32_bf16 v[80:83], v[172:175], v[208:211], v[80:83]
	v_mfma_f32_16x16x32_bf16 v[72:75], v[180:183], v[208:211], v[72:75]
	v_mfma_f32_16x16x32_bf16 v[68:71], v[172:175], v[216:219], v[68:71]
	v_mfma_f32_16x16x32_bf16 v[64:67], v[180:183], v[216:219], v[64:67]
	s_setprio 0
	s_barrier
	s_add_i32 s76, s66, s59
	v_lshl_add_u64 v[144:145], s[34:35], 0, v[130:131]
	s_mov_b32 m0, s76
	ds_read_b128 v[184:187], v151 offset:16384
	ds_read_b128 v[192:195], v151 offset:17408
	ds_read_b128 v[196:199], v151 offset:18432
	ds_read_b128 v[200:203], v151 offset:19456
	ds_read_b128 v[204:207], v151 offset:20480
	ds_read_b128 v[208:211], v151 offset:21504
	ds_read_b128 v[212:215], v151 offset:22528
	ds_read_b128 v[216:219], v151 offset:23552
	global_load_lds_dwordx4 v[144:145], off
	s_add_i32 m0, s76, 0x2000
	s_add_u32 s76, s34, 0x100000
	v_lshl_add_u64 v[188:189], s[34:35], 0, v[134:135]
	s_addc_u32 s77, s35, 0
	s_add_i32 s79, s67, s59
	global_load_lds_dwordx4 v[188:189], off
	s_mov_b32 m0, s79
	v_lshl_add_u64 v[222:223], s[42:43], 0, v[132:133]
	global_load_lds_dwordx4 v130, s[76:77]
	s_add_i32 m0, s79, 0x2000
	s_nop 0
	global_load_lds_dwordx4 v134, s[76:77]
	v_lshl_add_u64 v[220:221], s[42:43], 0, v[128:129]
	s_mov_b32 m0, s29
	s_nop 0
	global_load_lds_dwordx4 v[220:221], off
	s_mov_b32 m0, s33
	s_nop 0
	global_load_lds_dwordx4 v[222:223], off
	s_waitcnt vmcnt(8)
	s_waitcnt lgkmcnt(0)
	s_barrier
	s_setprio 1
	s_waitcnt lgkmcnt(0)
	v_mfma_f32_16x16x32_bf16 v[60:63], v[152:155], v[184:187], v[60:63]
	v_mfma_f32_16x16x32_bf16 v[56:59], v[160:163], v[184:187], v[56:59]
	v_mfma_f32_16x16x32_bf16 v[52:55], v[152:155], v[196:199], v[52:55]
	v_mfma_f32_16x16x32_bf16 v[44:47], v[160:163], v[196:199], v[44:47]
	v_mfma_f32_16x16x32_bf16 v[36:39], v[152:155], v[204:207], v[36:39]
	v_mfma_f32_16x16x32_bf16 v[28:31], v[160:163], v[204:207], v[28:31]
	v_mfma_f32_16x16x32_bf16 v[20:23], v[152:155], v[212:215], v[20:23]
	v_mfma_f32_16x16x32_bf16 v[12:15], v[160:163], v[212:215], v[12:15]
	v_mfma_f32_16x16x32_bf16 v[60:63], v[156:159], v[192:195], v[60:63]
	v_mfma_f32_16x16x32_bf16 v[56:59], v[164:167], v[192:195], v[56:59]
	v_mfma_f32_16x16x32_bf16 v[52:55], v[156:159], v[200:203], v[52:55]
	v_mfma_f32_16x16x32_bf16 v[44:47], v[164:167], v[200:203], v[44:47]
	v_mfma_f32_16x16x32_bf16 v[36:39], v[156:159], v[208:211], v[36:39]
	v_mfma_f32_16x16x32_bf16 v[28:31], v[164:167], v[208:211], v[28:31]
	v_mfma_f32_16x16x32_bf16 v[20:23], v[156:159], v[216:219], v[20:23]
	v_mfma_f32_16x16x32_bf16 v[12:15], v[164:167], v[216:219], v[12:15]
	s_setprio 0
	s_setprio 1
	v_mfma_f32_16x16x32_bf16 v[48:51], v[168:171], v[184:187], v[48:51]
	v_mfma_f32_16x16x32_bf16 v[40:43], v[176:179], v[184:187], v[40:43]
	v_mfma_f32_16x16x32_bf16 v[32:35], v[168:171], v[196:199], v[32:35]
	v_mfma_f32_16x16x32_bf16 v[24:27], v[176:179], v[196:199], v[24:27]
	v_mfma_f32_16x16x32_bf16 v[16:19], v[168:171], v[204:207], v[16:19]
	v_mfma_f32_16x16x32_bf16 v[8:11], v[176:179], v[204:207], v[8:11]
	v_mfma_f32_16x16x32_bf16 v[4:7], v[168:171], v[212:215], v[4:7]
	v_mfma_f32_16x16x32_bf16 v[0:3], v[176:179], v[212:215], v[0:3]
	v_mfma_f32_16x16x32_bf16 v[48:51], v[172:175], v[192:195], v[48:51]
	v_mfma_f32_16x16x32_bf16 v[40:43], v[180:183], v[192:195], v[40:43]
	v_mfma_f32_16x16x32_bf16 v[32:35], v[172:175], v[200:203], v[32:35]
	v_mfma_f32_16x16x32_bf16 v[24:27], v[180:183], v[200:203], v[24:27]
	v_mfma_f32_16x16x32_bf16 v[16:19], v[172:175], v[208:211], v[16:19]
	v_mfma_f32_16x16x32_bf16 v[8:11], v[180:183], v[208:211], v[8:11]
	v_mfma_f32_16x16x32_bf16 v[4:7], v[172:175], v[216:219], v[4:7]
	v_mfma_f32_16x16x32_bf16 v[0:3], v[180:183], v[216:219], v[0:3]
	s_setprio 0
	s_barrier
	s_add_i32 s76, 0, 0x18000
	s_add_i32 s77, 0, 0x1c000
	v_add_u32_e32 v164, s76, v147
	v_add_u32_e32 v180, s77, v147
	ds_read_b128 v[152:155], v164
	ds_read_b128 v[156:159], v164 offset:1024
	ds_read_b128 v[160:163], v164 offset:2048
	ds_read_b128 v[164:167], v164 offset:3072
	ds_read_b128 v[168:171], v180
	ds_read_b128 v[172:175], v180 offset:1024
	ds_read_b128 v[176:179], v180 offset:2048
	ds_read_b128 v[180:183], v180 offset:3072
	s_add_u32 s42, s42, 0x100000
	s_addc_u32 s43, s43, 0
	s_mov_b32 m0, s60
	ds_read_b128 v[184:187], v151 offset:32768
	ds_read_b128 v[192:195], v151 offset:33792
	ds_read_b128 v[196:199], v151 offset:34816
	ds_read_b128 v[200:203], v151 offset:35840
	ds_read_b128 v[204:207], v151 offset:36864
	ds_read_b128 v[208:211], v151 offset:37888
	ds_read_b128 v[212:215], v151 offset:38912
	ds_read_b128 v[216:219], v151 offset:39936
	global_load_lds_dwordx4 v128, s[42:43]
	s_mov_b32 m0, s61
	s_nop 0
	global_load_lds_dwordx4 v132, s[42:43]
	s_waitcnt vmcnt(8)
	s_waitcnt lgkmcnt(0)
	s_barrier
	s_setprio 1
	s_waitcnt lgkmcnt(0)
	v_mfma_f32_16x16x32_bf16 v[124:127], v[152:155], v[184:187], v[124:127]
	v_mfma_f32_16x16x32_bf16 v[120:123], v[160:163], v[184:187], v[120:123]
	v_mfma_f32_16x16x32_bf16 v[116:119], v[152:155], v[196:199], v[116:119]
	v_mfma_f32_16x16x32_bf16 v[108:111], v[160:163], v[196:199], v[108:111]
	v_mfma_f32_16x16x32_bf16 v[100:103], v[152:155], v[204:207], v[100:103]
	v_mfma_f32_16x16x32_bf16 v[92:95], v[160:163], v[204:207], v[92:95]
	v_mfma_f32_16x16x32_bf16 v[84:87], v[152:155], v[212:215], v[84:87]
	v_mfma_f32_16x16x32_bf16 v[76:79], v[160:163], v[212:215], v[76:79]
	v_mfma_f32_16x16x32_bf16 v[124:127], v[156:159], v[192:195], v[124:127]
	v_mfma_f32_16x16x32_bf16 v[120:123], v[164:167], v[192:195], v[120:123]
	v_mfma_f32_16x16x32_bf16 v[116:119], v[156:159], v[200:203], v[116:119]
	v_mfma_f32_16x16x32_bf16 v[108:111], v[164:167], v[200:203], v[108:111]
	v_mfma_f32_16x16x32_bf16 v[100:103], v[156:159], v[208:211], v[100:103]
	v_mfma_f32_16x16x32_bf16 v[92:95], v[164:167], v[208:211], v[92:95]
	v_mfma_f32_16x16x32_bf16 v[84:87], v[156:159], v[216:219], v[84:87]
	v_mfma_f32_16x16x32_bf16 v[76:79], v[164:167], v[216:219], v[76:79]
	s_setprio 0
	s_setprio 1
	v_mfma_f32_16x16x32_bf16 v[112:115], v[168:171], v[184:187], v[112:115]
	v_mfma_f32_16x16x32_bf16 v[104:107], v[176:179], v[184:187], v[104:107]
	v_mfma_f32_16x16x32_bf16 v[96:99], v[168:171], v[196:199], v[96:99]
	v_mfma_f32_16x16x32_bf16 v[88:91], v[176:179], v[196:199], v[88:91]
	v_mfma_f32_16x16x32_bf16 v[80:83], v[168:171], v[204:207], v[80:83]
	v_mfma_f32_16x16x32_bf16 v[72:75], v[176:179], v[204:207], v[72:75]
	v_mfma_f32_16x16x32_bf16 v[68:71], v[168:171], v[212:215], v[68:71]
	v_mfma_f32_16x16x32_bf16 v[64:67], v[176:179], v[212:215], v[64:67]
	v_mfma_f32_16x16x32_bf16 v[112:115], v[172:175], v[192:195], v[112:115]
	v_mfma_f32_16x16x32_bf16 v[104:107], v[180:183], v[192:195], v[104:107]
	v_mfma_f32_16x16x32_bf16 v[96:99], v[172:175], v[200:203], v[96:99]
	v_mfma_f32_16x16x32_bf16 v[88:91], v[180:183], v[200:203], v[88:91]
	v_mfma_f32_16x16x32_bf16 v[80:83], v[172:175], v[208:211], v[80:83]
	v_mfma_f32_16x16x32_bf16 v[72:75], v[180:183], v[208:211], v[72:75]
	v_mfma_f32_16x16x32_bf16 v[68:71], v[172:175], v[216:219], v[68:71]
	v_mfma_f32_16x16x32_bf16 v[64:67], v[180:183], v[216:219], v[64:67]
	s_setprio 0
	s_barrier
	s_add_i32 s42, s76, s59
	v_lshl_add_u64 v[144:145], v[144:145], 0, s[8:9]
	s_mov_b32 m0, s42
	ds_read_b128 v[184:187], v151 offset:49152
	ds_read_b128 v[192:195], v151 offset:50176
	ds_read_b128 v[196:199], v151 offset:51200
	ds_read_b128 v[200:203], v151 offset:52224
	ds_read_b128 v[204:207], v151 offset:53248
	ds_read_b128 v[208:211], v151 offset:54272
	ds_read_b128 v[212:215], v151 offset:55296
	ds_read_b128 v[216:219], v151 offset:56320
	global_load_lds_dwordx4 v[144:145], off
	s_add_i32 m0, s42, 0x2000
	s_add_u32 s34, s34, 0x100080
	v_lshl_add_u64 v[144:145], v[188:189], 0, s[8:9]
	s_addc_u32 s35, s35, 0
	s_add_i32 s42, s77, s59
	global_load_lds_dwordx4 v[144:145], off
	s_mov_b32 m0, s42
	s_nop 0
	global_load_lds_dwordx4 v130, s[34:35]
	s_add_i32 m0, s42, 0x2000
	s_nop 0
	global_load_lds_dwordx4 v134, s[34:35]
	v_lshl_add_u64 v[144:145], v[220:221], 0, s[8:9]
	s_mov_b32 m0, s63
	s_nop 0
	global_load_lds_dwordx4 v[144:145], off
	v_lshl_add_u64 v[144:145], v[222:223], 0, s[8:9]
	s_mov_b32 m0, s64
	s_nop 0
	global_load_lds_dwordx4 v[144:145], off
	s_waitcnt vmcnt(8)
	s_waitcnt lgkmcnt(0)
	s_barrier
	s_setprio 1
	s_waitcnt lgkmcnt(0)
	v_mfma_f32_16x16x32_bf16 v[60:63], v[152:155], v[184:187], v[60:63]
	v_mfma_f32_16x16x32_bf16 v[56:59], v[160:163], v[184:187], v[56:59]
	v_mfma_f32_16x16x32_bf16 v[52:55], v[152:155], v[196:199], v[52:55]
	v_mfma_f32_16x16x32_bf16 v[44:47], v[160:163], v[196:199], v[44:47]
	v_mfma_f32_16x16x32_bf16 v[36:39], v[152:155], v[204:207], v[36:39]
	v_mfma_f32_16x16x32_bf16 v[28:31], v[160:163], v[204:207], v[28:31]
	v_mfma_f32_16x16x32_bf16 v[20:23], v[152:155], v[212:215], v[20:23]
	v_mfma_f32_16x16x32_bf16 v[12:15], v[160:163], v[212:215], v[12:15]
	v_mfma_f32_16x16x32_bf16 v[60:63], v[156:159], v[192:195], v[60:63]
	v_mfma_f32_16x16x32_bf16 v[56:59], v[164:167], v[192:195], v[56:59]
	v_mfma_f32_16x16x32_bf16 v[52:55], v[156:159], v[200:203], v[52:55]
	v_mfma_f32_16x16x32_bf16 v[44:47], v[164:167], v[200:203], v[44:47]
	v_mfma_f32_16x16x32_bf16 v[36:39], v[156:159], v[208:211], v[36:39]
	v_mfma_f32_16x16x32_bf16 v[28:31], v[164:167], v[208:211], v[28:31]
	v_mfma_f32_16x16x32_bf16 v[20:23], v[156:159], v[216:219], v[20:23]
	v_mfma_f32_16x16x32_bf16 v[12:15], v[164:167], v[216:219], v[12:15]
	s_setprio 0
	s_setprio 1
	v_mfma_f32_16x16x32_bf16 v[48:51], v[168:171], v[184:187], v[48:51]
	v_mfma_f32_16x16x32_bf16 v[40:43], v[176:179], v[184:187], v[40:43]
	v_mfma_f32_16x16x32_bf16 v[32:35], v[168:171], v[196:199], v[32:35]
	v_mfma_f32_16x16x32_bf16 v[24:27], v[176:179], v[196:199], v[24:27]
	v_mfma_f32_16x16x32_bf16 v[16:19], v[168:171], v[204:207], v[16:19]
	v_mfma_f32_16x16x32_bf16 v[8:11], v[176:179], v[204:207], v[8:11]
	v_mfma_f32_16x16x32_bf16 v[4:7], v[168:171], v[212:215], v[4:7]
	v_mfma_f32_16x16x32_bf16 v[0:3], v[176:179], v[212:215], v[0:3]
	v_mfma_f32_16x16x32_bf16 v[48:51], v[172:175], v[192:195], v[48:51]
	v_mfma_f32_16x16x32_bf16 v[40:43], v[180:183], v[192:195], v[40:43]
	v_mfma_f32_16x16x32_bf16 v[32:35], v[172:175], v[200:203], v[32:35]
	v_mfma_f32_16x16x32_bf16 v[24:27], v[180:183], v[200:203], v[24:27]
	v_mfma_f32_16x16x32_bf16 v[16:19], v[172:175], v[208:211], v[16:19]
	v_mfma_f32_16x16x32_bf16 v[8:11], v[180:183], v[208:211], v[8:11]
	v_mfma_f32_16x16x32_bf16 v[4:7], v[172:175], v[216:219], v[4:7]
	v_mfma_f32_16x16x32_bf16 v[0:3], v[180:183], v[216:219], v[0:3]
	s_setprio 0
	s_barrier
	s_add_i32 s75, s75, 2
	s_add_u32 s30, s30, 0x100
	s_addc_u32 s31, s31, 0
	s_add_u32 s73, s73, 0x100
	s_addc_u32 s74, s74, 0
	s_cmp_gt_u32 s75, 61
	s_cbranch_scc0 .LBB0_1650
	s_and_b64 vcc, exec, s[10:11]
	s_cbranch_vccz .LBB0_1653
	s_barrier
